# all 16-byte global stores write-through (sc0 sc1) so the grid barriers find no dirty L2 lines
# speedup vs baseline: 1.0055x; 1.0049x over previous
; #define LAS __attribute__((address_space(3)))
; __device__ __forceinline__ unsigned pk2(float lo, float hi) { return f2bf(lo) | (f2bf(hi) << 16); }
; #define LDS_WAIT() asm volatile("s_waitcnt lgkmcnt(0)" ::: "memory")
; __device__ __forceinline__ void wt_item(const float* __restrict__ W, int ldw, int K, int src_c0, bf16_t* __restrict__ WT, int dst_r0, int k0, LAS float* scr, int lane, int Ndst) {
; #pragma unroll 32
;     for (int i = 0; i < 32; ++i) { const int kk = 2 * i + (lane >> 5); scr[kk * 33 + (lane & 31)] = (src_c0 >= 0) ? W[(size_t)(k0 + kk) * ldw + src_c0 + (lane & 31)] : 0.f; }
;     LDS_WAIT(); asm volatile("" ::: "memory");
;     const int c = lane & 7;
; #pragma unroll
;     for (int j = 0; j < 4; ++j) { const int n = (lane >> 3) + 8 * j; const LAS float* s = scr + (8 * c) * 33 + n;
;         v4u o; o.x = pk2(s[0 * 33], s[1 * 33]); o.y = pk2(s[2 * 33], s[3 * 33]); o.z = pk2(s[4 * 33], s[5 * 33]); o.w = pk2(s[6 * 33], s[7 * 33]);
;         *(v4u*)(WT + ((size_t)(k0 >> 6) * Ndst + dst_r0 + n) * 64 + 8 * c) = o; }
;     LDS_WAIT(); asm volatile("" ::: "memory");
; }
; __device__ __forceinline__ void conv_plain(const float* W, int K, int N, bf16_t* WT, LAS float* scr, int gw, int NGW, int lane) {
;     const int nblk = N / 32, items = (K / 64) * nblk;
;     for (int it = gw; it < items; it += NGW) { const int kb = it / nblk, nb = it % nblk; wt_item(W, N, K, nb * 32, WT, nb * 32, kb * 64, scr, lane, N); }
.LBB0_12:
	v_add_u32_e32 v10, v56, v57
	v_add_u32_e32 v10, 0x400, v10
	s_waitcnt vmcnt(2)
	ds_write2_b32 v10, v5, v58 offset0:8 offset1:74
	s_waitcnt vmcnt(0)
	ds_write2_b32 v10, v59, v60 offset0:140 offset1:206
	s_waitcnt lgkmcnt(0)
	ds_read2_b32 v[10:11], v46 offset1:8
	ds_read2_b32 v[62:63], v46 offset0:33 offset1:41
	ds_read2_b32 v[64:65], v46 offset0:66 offset1:74
	ds_read2_b32 v[66:67], v46 offset0:99 offset1:107
	ds_read2_b32 v[68:69], v46 offset0:132 offset1:140
	s_waitcnt lgkmcnt(4)
	v_bfe_u32 v5, v10, 16, 1
	v_add3_u32 v5, v10, v5, s14
	s_waitcnt lgkmcnt(3)
	v_bfe_u32 v10, v62, 16, 1
	v_lshrrev_b32_e32 v5, 16, v5
	v_add3_u32 v10, v62, v10, s14
	ds_read2_b32 v[70:71], v46 offset0:165 offset1:173
	v_and_or_b32 v58, v10, s15, v5
	s_waitcnt lgkmcnt(3)
	v_bfe_u32 v5, v64, 16, 1
	v_add3_u32 v5, v64, v5, s14
	s_waitcnt lgkmcnt(2)
	v_bfe_u32 v10, v66, 16, 1
	ds_read2_b32 v[72:73], v46 offset0:198 offset1:206
	v_lshrrev_b32_e32 v5, 16, v5
	v_add3_u32 v10, v66, v10, s14
	ds_read2_b32 v[74:75], v46 offset0:231 offset1:239
	v_and_or_b32 v59, v10, s15, v5
	s_waitcnt lgkmcnt(3)
	v_bfe_u32 v5, v68, 16, 1
	v_add3_u32 v5, v68, v5, s14
	s_waitcnt lgkmcnt(2)
	v_bfe_u32 v10, v70, 16, 1
	s_ashr_i32 s7, s6, 31
	v_lshrrev_b32_e32 v5, 16, v5
	v_add3_u32 v10, v70, v10, s14
	s_lshl_b64 s[0:1], s[6:7], 13
	s_ashr_i32 s6, s4, 31
	v_and_or_b32 v60, v10, s15, v5
	s_waitcnt lgkmcnt(1)
	v_bfe_u32 v5, v72, 16, 1
	s_add_u32 s0, s0, s4
	v_add3_u32 v5, v72, v5, s14
	s_waitcnt lgkmcnt(0)
	v_bfe_u32 v10, v74, 16, 1
	s_addc_u32 s1, s1, s6
	v_lshrrev_b32_e32 v5, 16, v5
	v_add3_u32 v10, v74, v10, s14
	v_and_or_b32 v61, v10, s15, v5
	v_mov_b32_e32 v77, s1
	v_or_b32_e32 v76, s0, v45
	v_bfe_u32 v5, v11, 16, 1
	v_lshlrev_b64 v[76:77], 7, v[76:77]
	v_add3_u32 v5, v11, v5, s14
	v_bfe_u32 v10, v63, 16, 1
	v_lshl_add_u64 v[76:77], v[8:9], 0, v[76:77]
	v_lshrrev_b32_e32 v5, 16, v5
	v_add3_u32 v10, v63, v10, s14
	global_store_dwordx4 v[76:77], v[58:61], off sc0 sc1
	v_mov_b32_e32 v11, s1
	ds_read2_b32 v[62:63], v46 offset0:16 offset1:24
	v_and_or_b32 v58, v10, s15, v5
	v_bfe_u32 v5, v65, 16, 1
	v_add3_u32 v5, v65, v5, s14
	v_bfe_u32 v10, v67, 16, 1
	v_lshrrev_b32_e32 v5, 16, v5
	v_add3_u32 v10, v67, v10, s14
	v_and_or_b32 v59, v10, s15, v5
	v_bfe_u32 v5, v69, 16, 1
	v_add3_u32 v5, v69, v5, s14
	v_bfe_u32 v10, v71, 16, 1
	v_lshrrev_b32_e32 v5, 16, v5
	v_add3_u32 v10, v71, v10, s14
	v_and_or_b32 v60, v10, s15, v5
	v_bfe_u32 v5, v73, 16, 1
	v_add3_u32 v5, v73, v5, s14
	v_bfe_u32 v10, v75, 16, 1
	v_lshrrev_b32_e32 v5, 16, v5
	v_add3_u32 v10, v75, v10, s14
	v_and_or_b32 v61, v10, s15, v5
	v_or_b32_e32 v10, s0, v47
	v_lshlrev_b64 v[10:11], 7, v[10:11]
	v_lshl_add_u64 v[10:11], v[8:9], 0, v[10:11]
	global_store_dwordx4 v[10:11], v[58:61], off sc0 sc1
	ds_read2_b32 v[10:11], v46 offset0:49 offset1:57
	ds_read2_b32 v[64:65], v46 offset0:82 offset1:90
	ds_read2_b32 v[66:67], v46 offset0:115 offset1:123
	s_waitcnt lgkmcnt(3)
	v_bfe_u32 v5, v62, 16, 1
	v_add3_u32 v5, v62, v5, s14
	s_waitcnt lgkmcnt(2)
	v_bfe_u32 v58, v10, 16, 1
	ds_read2_b32 v[68:69], v46 offset0:148 offset1:156
	v_lshrrev_b32_e32 v5, 16, v5
	v_add3_u32 v10, v10, v58, s14
	ds_read2_b32 v[70:71], v46 offset0:181 offset1:189
	v_and_or_b32 v58, v10, s15, v5
	s_waitcnt lgkmcnt(3)
	v_bfe_u32 v5, v64, 16, 1
	v_add3_u32 v5, v64, v5, s14
	s_waitcnt lgkmcnt(2)
	v_bfe_u32 v10, v66, 16, 1
	ds_read2_b32 v[72:73], v46 offset0:214 offset1:222
	v_lshrrev_b32_e32 v5, 16, v5
	v_add3_u32 v10, v66, v10, s14
	ds_read2_b32 v[74:75], v46 offset0:247 offset1:255
	v_and_or_b32 v59, v10, s15, v5
	s_waitcnt lgkmcnt(3)
	v_bfe_u32 v5, v68, 16, 1
	v_add3_u32 v5, v68, v5, s14
	s_waitcnt lgkmcnt(2)
	v_bfe_u32 v10, v70, 16, 1
	v_lshrrev_b32_e32 v5, 16, v5
	v_add3_u32 v10, v70, v10, s14
	v_and_or_b32 v60, v10, s15, v5
	s_waitcnt lgkmcnt(1)
	v_bfe_u32 v5, v72, 16, 1
	v_add3_u32 v5, v72, v5, s14
	s_waitcnt lgkmcnt(0)
	v_bfe_u32 v10, v74, 16, 1
	v_lshrrev_b32_e32 v5, 16, v5
	v_add3_u32 v10, v74, v10, s14
	v_and_or_b32 v61, v10, s15, v5
	v_mov_b32_e32 v77, s1
	v_or_b32_e32 v76, s0, v48
	v_bfe_u32 v5, v63, 16, 1
	v_lshlrev_b64 v[76:77], 7, v[76:77]
	v_add3_u32 v5, v63, v5, s14
	v_bfe_u32 v10, v11, 16, 1
	v_lshl_add_u64 v[76:77], v[8:9], 0, v[76:77]
	v_lshrrev_b32_e32 v5, 16, v5
	v_add3_u32 v10, v11, v10, s14
	global_store_dwordx4 v[76:77], v[58:61], off sc0 sc1
	v_mov_b32_e32 v11, s1
	s_add_i32 s16, s16, s52
	v_and_or_b32 v58, v10, s15, v5
	v_bfe_u32 v5, v65, 16, 1
	v_add3_u32 v5, v65, v5, s14
	v_bfe_u32 v10, v67, 16, 1
	v_lshrrev_b32_e32 v5, 16, v5
	v_add3_u32 v10, v67, v10, s14
	v_and_or_b32 v59, v10, s15, v5
	v_bfe_u32 v5, v69, 16, 1
	v_add3_u32 v5, v69, v5, s14
	v_bfe_u32 v10, v71, 16, 1
	v_lshrrev_b32_e32 v5, 16, v5
	v_add3_u32 v10, v71, v10, s14
	v_and_or_b32 v60, v10, s15, v5
	v_bfe_u32 v5, v73, 16, 1
	v_add3_u32 v5, v73, v5, s14
	v_bfe_u32 v10, v75, 16, 1
	v_lshrrev_b32_e32 v5, 16, v5
	v_add3_u32 v10, v75, v10, s14
	v_and_or_b32 v61, v10, s15, v5
	v_or_b32_e32 v10, s0, v49
	v_lshlrev_b64 v[10:11], 7, v[10:11]
	v_lshl_add_u64 v[10:11], v[8:9], 0, v[10:11]
	global_store_dwordx4 v[10:11], v[58:61], off sc0 sc1
	s_waitcnt lgkmcnt(0)
	s_add_i32 s12, s12, s13
	s_cmpk_lt_i32 s16, 0x2000
	s_cbranch_scc0 .LBB0_29

; #define LAS __attribute__((address_space(3)))
; __device__ __forceinline__ unsigned pk2(float lo, float hi) { return f2bf(lo) | (f2bf(hi) << 16); }
; #define LDS_WAIT() asm volatile("s_waitcnt lgkmcnt(0)" ::: "memory")
; __device__ __forceinline__ void wt_item(const float* __restrict__ W, int ldw, int K, int src_c0, bf16_t* __restrict__ WT, int dst_r0, int k0, LAS float* scr, int lane, int Ndst) {
; #pragma unroll 32
;     for (int i = 0; i < 32; ++i) { const int kk = 2 * i + (lane >> 5); scr[kk * 33 + (lane & 31)] = (src_c0 >= 0) ? W[(size_t)(k0 + kk) * ldw + src_c0 + (lane & 31)] : 0.f; }
;     LDS_WAIT(); asm volatile("" ::: "memory");
;     const int c = lane & 7;
; #pragma unroll
;     for (int j = 0; j < 4; ++j) { const int n = (lane >> 3) + 8 * j; const LAS float* s = scr + (8 * c) * 33 + n;
;         v4u o; o.x = pk2(s[0 * 33], s[1 * 33]); o.y = pk2(s[2 * 33], s[3 * 33]); o.z = pk2(s[4 * 33], s[5 * 33]); o.w = pk2(s[6 * 33], s[7 * 33]);
;         *(v4u*)(WT + ((size_t)(k0 >> 6) * Ndst + dst_r0 + n) * 64 + 8 * c) = o; }
;     LDS_WAIT(); asm volatile("" ::: "memory");
; }
; __device__ __forceinline__ void conv_plain(const float* W, int K, int N, bf16_t* WT, LAS float* scr, int gw, int NGW, int lane) {
;     const int nblk = N / 32, items = (K / 64) * nblk;
;     for (int it = gw; it < items; it += NGW) { const int kb = it / nblk, nb = it % nblk; wt_item(W, N, K, nb * 32, WT, nb * 32, kb * 64, scr, lane, N); }
.LBB0_31:
	v_add_u32_e32 v10, v56, v57
	v_add_u32_e32 v10, 0x400, v10
	s_waitcnt vmcnt(2)
	ds_write2_b32 v10, v5, v58 offset0:8 offset1:74
	s_waitcnt vmcnt(0)
	ds_write2_b32 v10, v59, v60 offset0:140 offset1:206
	s_waitcnt lgkmcnt(0)
	ds_read2_b32 v[10:11], v46 offset1:8
	ds_read2_b32 v[62:63], v46 offset0:33 offset1:41
	ds_read2_b32 v[64:65], v46 offset0:66 offset1:74
	ds_read2_b32 v[66:67], v46 offset0:99 offset1:107
	ds_read2_b32 v[68:69], v46 offset0:132 offset1:140
	s_waitcnt lgkmcnt(4)
	v_bfe_u32 v5, v10, 16, 1
	v_add3_u32 v5, v10, v5, s18
	s_waitcnt lgkmcnt(3)
	v_bfe_u32 v10, v62, 16, 1
	v_lshrrev_b32_e32 v5, 16, v5
	v_add3_u32 v10, v62, v10, s18
	ds_read2_b32 v[70:71], v46 offset0:165 offset1:173
	v_and_or_b32 v58, v10, s19, v5
	s_waitcnt lgkmcnt(3)
	v_bfe_u32 v5, v64, 16, 1
	v_add3_u32 v5, v64, v5, s18
	s_waitcnt lgkmcnt(2)
	v_bfe_u32 v10, v66, 16, 1
	ds_read2_b32 v[72:73], v46 offset0:198 offset1:206
	v_lshrrev_b32_e32 v5, 16, v5
	v_add3_u32 v10, v66, v10, s18
	ds_read2_b32 v[74:75], v46 offset0:231 offset1:239
	v_and_or_b32 v59, v10, s19, v5
	s_waitcnt lgkmcnt(3)
	v_bfe_u32 v5, v68, 16, 1
	v_add3_u32 v5, v68, v5, s18
	s_waitcnt lgkmcnt(2)
	v_bfe_u32 v10, v70, 16, 1
	s_ashr_i32 s13, s12, 31
	v_lshrrev_b32_e32 v5, 16, v5
	v_add3_u32 v10, v70, v10, s18
	s_lshl_b64 s[0:1], s[12:13], 11
	s_ashr_i32 s12, s4, 31
	v_and_or_b32 v60, v10, s19, v5
	s_waitcnt lgkmcnt(1)
	v_bfe_u32 v5, v72, 16, 1
	s_add_u32 s0, s0, s4
	v_add3_u32 v5, v72, v5, s18
	s_waitcnt lgkmcnt(0)
	v_bfe_u32 v10, v74, 16, 1
	s_addc_u32 s1, s1, s12
	v_lshrrev_b32_e32 v5, 16, v5
	v_add3_u32 v10, v74, v10, s18
	v_and_or_b32 v61, v10, s19, v5
	v_mov_b32_e32 v77, s1
	v_or_b32_e32 v76, s0, v45
	v_bfe_u32 v5, v11, 16, 1
	v_lshlrev_b64 v[76:77], 7, v[76:77]
	v_add3_u32 v5, v11, v5, s18
	v_bfe_u32 v10, v63, 16, 1
	v_lshl_add_u64 v[76:77], v[8:9], 0, v[76:77]
	v_lshrrev_b32_e32 v5, 16, v5
	v_add3_u32 v10, v63, v10, s18
	global_store_dwordx4 v[76:77], v[58:61], off sc0 sc1
	v_mov_b32_e32 v11, s1
	ds_read2_b32 v[62:63], v46 offset0:16 offset1:24
	v_and_or_b32 v58, v10, s19, v5
	v_bfe_u32 v5, v65, 16, 1
	v_add3_u32 v5, v65, v5, s18
	v_bfe_u32 v10, v67, 16, 1
	v_lshrrev_b32_e32 v5, 16, v5
	v_add3_u32 v10, v67, v10, s18
	v_and_or_b32 v59, v10, s19, v5
	v_bfe_u32 v5, v69, 16, 1
	v_add3_u32 v5, v69, v5, s18
	v_bfe_u32 v10, v71, 16, 1
	v_lshrrev_b32_e32 v5, 16, v5
	v_add3_u32 v10, v71, v10, s18
	v_and_or_b32 v60, v10, s19, v5
	v_bfe_u32 v5, v73, 16, 1
	v_add3_u32 v5, v73, v5, s18
	v_bfe_u32 v10, v75, 16, 1
	v_lshrrev_b32_e32 v5, 16, v5
	v_add3_u32 v10, v75, v10, s18
	v_and_or_b32 v61, v10, s19, v5
	v_or_b32_e32 v10, s0, v47
	v_lshlrev_b64 v[10:11], 7, v[10:11]
	v_lshl_add_u64 v[10:11], v[8:9], 0, v[10:11]
	global_store_dwordx4 v[10:11], v[58:61], off sc0 sc1
	ds_read2_b32 v[10:11], v46 offset0:49 offset1:57
	ds_read2_b32 v[64:65], v46 offset0:82 offset1:90
	ds_read2_b32 v[66:67], v46 offset0:115 offset1:123
	s_waitcnt lgkmcnt(3)
	v_bfe_u32 v5, v62, 16, 1
	v_add3_u32 v5, v62, v5, s18
	s_waitcnt lgkmcnt(2)
	v_bfe_u32 v58, v10, 16, 1
	ds_read2_b32 v[68:69], v46 offset0:148 offset1:156
	v_lshrrev_b32_e32 v5, 16, v5
	v_add3_u32 v10, v10, v58, s18
	ds_read2_b32 v[70:71], v46 offset0:181 offset1:189
	v_and_or_b32 v58, v10, s19, v5
	s_waitcnt lgkmcnt(3)
	v_bfe_u32 v5, v64, 16, 1
	v_add3_u32 v5, v64, v5, s18
	s_waitcnt lgkmcnt(2)
	v_bfe_u32 v10, v66, 16, 1
	ds_read2_b32 v[72:73], v46 offset0:214 offset1:222
	v_lshrrev_b32_e32 v5, 16, v5
	v_add3_u32 v10, v66, v10, s18
	ds_read2_b32 v[74:75], v46 offset0:247 offset1:255
	v_and_or_b32 v59, v10, s19, v5
	s_waitcnt lgkmcnt(3)
	v_bfe_u32 v5, v68, 16, 1
	v_add3_u32 v5, v68, v5, s18
	s_waitcnt lgkmcnt(2)
	v_bfe_u32 v10, v70, 16, 1
	v_lshrrev_b32_e32 v5, 16, v5
	v_add3_u32 v10, v70, v10, s18
	v_and_or_b32 v60, v10, s19, v5
	s_waitcnt lgkmcnt(1)
	v_bfe_u32 v5, v72, 16, 1
	v_add3_u32 v5, v72, v5, s18
	s_waitcnt lgkmcnt(0)
	v_bfe_u32 v10, v74, 16, 1
	v_lshrrev_b32_e32 v5, 16, v5
	v_add3_u32 v10, v74, v10, s18
	v_and_or_b32 v61, v10, s19, v5
	v_mov_b32_e32 v77, s1
	v_or_b32_e32 v76, s0, v48
	v_bfe_u32 v5, v63, 16, 1
	v_lshlrev_b64 v[76:77], 7, v[76:77]
	v_add3_u32 v5, v63, v5, s18
	v_bfe_u32 v10, v11, 16, 1
	v_lshl_add_u64 v[76:77], v[8:9], 0, v[76:77]
	v_lshrrev_b32_e32 v5, 16, v5
	v_add3_u32 v10, v11, v10, s18
	global_store_dwordx4 v[76:77], v[58:61], off sc0 sc1
	v_mov_b32_e32 v11, s1
	s_add_i32 s20, s20, s52
	v_and_or_b32 v58, v10, s19, v5
	v_bfe_u32 v5, v65, 16, 1
	v_add3_u32 v5, v65, v5, s18
	v_bfe_u32 v10, v67, 16, 1
	v_lshrrev_b32_e32 v5, 16, v5
	v_add3_u32 v10, v67, v10, s18
	v_and_or_b32 v59, v10, s19, v5
	v_bfe_u32 v5, v69, 16, 1
	v_add3_u32 v5, v69, v5, s18
	v_bfe_u32 v10, v71, 16, 1
	v_lshrrev_b32_e32 v5, 16, v5
	v_add3_u32 v10, v71, v10, s18
	v_and_or_b32 v60, v10, s19, v5
	v_bfe_u32 v5, v73, 16, 1
	v_add3_u32 v5, v73, v5, s18
	v_bfe_u32 v10, v75, 16, 1
	v_lshrrev_b32_e32 v5, 16, v5
	v_add3_u32 v10, v75, v10, s18
	v_and_or_b32 v61, v10, s19, v5
	v_or_b32_e32 v10, s0, v49
	v_lshlrev_b64 v[10:11], 7, v[10:11]
	v_lshl_add_u64 v[10:11], v[8:9], 0, v[10:11]
	global_store_dwordx4 v[10:11], v[58:61], off sc0 sc1
	s_waitcnt lgkmcnt(0)
	s_add_i32 s16, s16, s17
	s_cmpk_lt_i32 s20, 0x800
	s_cbranch_scc0 .LBB0_48

; #define LAS __attribute__((address_space(3)))
; __device__ __forceinline__ unsigned pk2(float lo, float hi) { return f2bf(lo) | (f2bf(hi) << 16); }
; #define LDS_WAIT() asm volatile("s_waitcnt lgkmcnt(0)" ::: "memory")
; __device__ __forceinline__ void wt_item(const float* __restrict__ W, int ldw, int K, int src_c0, bf16_t* __restrict__ WT, int dst_r0, int k0, LAS float* scr, int lane, int Ndst) {
; #pragma unroll 32
;     for (int i = 0; i < 32; ++i) { const int kk = 2 * i + (lane >> 5); scr[kk * 33 + (lane & 31)] = (src_c0 >= 0) ? W[(size_t)(k0 + kk) * ldw + src_c0 + (lane & 31)] : 0.f; }
;     LDS_WAIT(); asm volatile("" ::: "memory");
;     const int c = lane & 7;
; #pragma unroll
;     for (int j = 0; j < 4; ++j) { const int n = (lane >> 3) + 8 * j; const LAS float* s = scr + (8 * c) * 33 + n;
;         v4u o; o.x = pk2(s[0 * 33], s[1 * 33]); o.y = pk2(s[2 * 33], s[3 * 33]); o.z = pk2(s[4 * 33], s[5 * 33]); o.w = pk2(s[6 * 33], s[7 * 33]);
;         *(v4u*)(WT + ((size_t)(k0 >> 6) * Ndst + dst_r0 + n) * 64 + 8 * c) = o; }
;     LDS_WAIT(); asm volatile("" ::: "memory");
; }
; __device__ __forceinline__ void conv_mla_win(const float* W, bf16_t* WT, LAS float* scr, int gw, int NGW, int lane) {
;     constexpr int nblk = MLA_NP / 32, items = (DM / 64) * nblk;
;     for (int it = gw; it < items; it += NGW) { const int kb = it / nblk, nb = it % nblk;
;         const int src = nb < 32 ? nb * 32 : nb < 96 ? 1088 + (nb - 32) * 32 : nb < 98 ? 1024 + (nb - 96) * 32 : -1;
;         wt_item(W, 3136, DM, src, WT, nb * 32, kb * 64, scr, lane, MLA_NP); }
.LBB0_50:
	s_waitcnt vmcnt(2)
	ds_write2_b32 v5, v57, v58 offset0:8 offset1:74
	s_waitcnt vmcnt(0)
	ds_write2_b32 v5, v59, v60 offset0:140 offset1:206
	s_waitcnt lgkmcnt(0)
	ds_read2_b32 v[10:11], v46 offset1:8
	ds_read2_b32 v[62:63], v46 offset0:33 offset1:41
	ds_read2_b32 v[64:65], v46 offset0:66 offset1:74
	ds_read2_b32 v[66:67], v46 offset0:99 offset1:107
	ds_read2_b32 v[68:69], v46 offset0:132 offset1:140
	s_waitcnt lgkmcnt(4)
	v_bfe_u32 v57, v10, 16, 1
	v_add3_u32 v10, v10, v57, s15
	s_waitcnt lgkmcnt(3)
	v_bfe_u32 v57, v62, 16, 1
	v_lshrrev_b32_e32 v10, 16, v10
	v_add3_u32 v57, v62, v57, s15
	ds_read2_b32 v[70:71], v46 offset0:165 offset1:173
	v_and_or_b32 v58, v57, s16, v10
	s_waitcnt lgkmcnt(3)
	v_bfe_u32 v10, v64, 16, 1
	v_add3_u32 v10, v64, v10, s15
	s_waitcnt lgkmcnt(2)
	v_bfe_u32 v57, v66, 16, 1
	ds_read2_b32 v[72:73], v46 offset0:198 offset1:206
	v_lshrrev_b32_e32 v10, 16, v10
	v_add3_u32 v57, v66, v57, s15
	ds_read2_b32 v[74:75], v46 offset0:231 offset1:239
	v_and_or_b32 v59, v57, s16, v10
	s_waitcnt lgkmcnt(3)
	v_bfe_u32 v10, v68, 16, 1
	v_add3_u32 v10, v68, v10, s15
	s_waitcnt lgkmcnt(2)
	v_bfe_u32 v57, v70, 16, 1
	v_lshrrev_b32_e32 v10, 16, v10
	v_add3_u32 v57, v70, v57, s15
	s_mul_hi_i32 s0, s18, 0xd00
	s_mulk_i32 s18, 0xd00
	s_ashr_i32 s1, s19, 31
	v_and_or_b32 v60, v57, s16, v10
	s_waitcnt lgkmcnt(1)
	v_bfe_u32 v10, v72, 16, 1
	s_add_u32 s4, s18, s19
	v_add3_u32 v10, v72, v10, s15
	s_waitcnt lgkmcnt(0)
	v_bfe_u32 v57, v74, 16, 1
	s_addc_u32 s0, s0, s1
	v_lshrrev_b32_e32 v10, 16, v10
	v_add3_u32 v57, v74, v57, s15
	v_and_or_b32 v61, v57, s16, v10
	v_mov_b32_e32 v77, s0
	v_or_b32_e32 v76, s4, v45
	v_bfe_u32 v10, v11, 16, 1
	v_lshlrev_b64 v[76:77], 7, v[76:77]
	v_add3_u32 v10, v11, v10, s15
	v_bfe_u32 v11, v63, 16, 1
	v_lshl_add_u64 v[76:77], v[8:9], 0, v[76:77]
	v_lshrrev_b32_e32 v10, 16, v10
	v_add3_u32 v11, v63, v11, s15
	global_store_dwordx4 v[76:77], v[58:61], off sc0 sc1
	ds_read2_b32 v[62:63], v46 offset0:16 offset1:24
	v_mov_b32_e32 v77, s0
	v_and_or_b32 v58, v11, s16, v10
	v_bfe_u32 v10, v65, 16, 1
	v_add3_u32 v10, v65, v10, s15
	v_bfe_u32 v11, v67, 16, 1
	v_lshrrev_b32_e32 v10, 16, v10
	v_add3_u32 v11, v67, v11, s15
	v_and_or_b32 v59, v11, s16, v10
	v_bfe_u32 v10, v69, 16, 1
	v_add3_u32 v10, v69, v10, s15
	v_bfe_u32 v11, v71, 16, 1
	v_lshrrev_b32_e32 v10, 16, v10
	v_add3_u32 v11, v71, v11, s15
	v_and_or_b32 v60, v11, s16, v10
	v_bfe_u32 v10, v73, 16, 1
	v_add3_u32 v10, v73, v10, s15
	v_bfe_u32 v11, v75, 16, 1
	v_lshrrev_b32_e32 v10, 16, v10
	v_add3_u32 v11, v75, v11, s15
	v_and_or_b32 v61, v11, s16, v10
	v_mov_b32_e32 v11, s0
	v_or_b32_e32 v10, s4, v47
	v_lshlrev_b64 v[10:11], 7, v[10:11]
	v_lshl_add_u64 v[10:11], v[8:9], 0, v[10:11]
	global_store_dwordx4 v[10:11], v[58:61], off sc0 sc1
	ds_read2_b32 v[10:11], v46 offset0:49 offset1:57
	ds_read2_b32 v[64:65], v46 offset0:82 offset1:90
	ds_read2_b32 v[66:67], v46 offset0:115 offset1:123
	s_waitcnt lgkmcnt(3)
	v_bfe_u32 v57, v62, 16, 1
	v_add3_u32 v57, v62, v57, s15
	s_waitcnt lgkmcnt(2)
	v_bfe_u32 v58, v10, 16, 1
	ds_read2_b32 v[68:69], v46 offset0:148 offset1:156
	v_lshrrev_b32_e32 v57, 16, v57
	v_add3_u32 v10, v10, v58, s15
	ds_read2_b32 v[70:71], v46 offset0:181 offset1:189
	v_and_or_b32 v58, v10, s16, v57
	s_waitcnt lgkmcnt(3)
	v_bfe_u32 v10, v64, 16, 1
	v_add3_u32 v10, v64, v10, s15
	s_waitcnt lgkmcnt(2)
	v_bfe_u32 v57, v66, 16, 1
	ds_read2_b32 v[72:73], v46 offset0:214 offset1:222
	v_lshrrev_b32_e32 v10, 16, v10
	v_add3_u32 v57, v66, v57, s15
	ds_read2_b32 v[74:75], v46 offset0:247 offset1:255
	v_and_or_b32 v59, v57, s16, v10
	s_waitcnt lgkmcnt(3)
	v_bfe_u32 v10, v68, 16, 1
	v_add3_u32 v10, v68, v10, s15
	s_waitcnt lgkmcnt(2)
	v_bfe_u32 v57, v70, 16, 1
	v_lshrrev_b32_e32 v10, 16, v10
	v_add3_u32 v57, v70, v57, s15
	v_and_or_b32 v60, v57, s16, v10
	s_waitcnt lgkmcnt(1)
	v_bfe_u32 v10, v72, 16, 1
	v_add3_u32 v10, v72, v10, s15
	s_waitcnt lgkmcnt(0)
	v_bfe_u32 v57, v74, 16, 1
	v_lshrrev_b32_e32 v10, 16, v10
	v_add3_u32 v57, v74, v57, s15
	v_and_or_b32 v61, v57, s16, v10
	v_or_b32_e32 v76, s4, v48
	v_bfe_u32 v10, v63, 16, 1
	v_lshlrev_b64 v[76:77], 7, v[76:77]
	v_add3_u32 v10, v63, v10, s15
	v_bfe_u32 v57, v11, 16, 1
	v_lshl_add_u64 v[76:77], v[8:9], 0, v[76:77]
	v_lshrrev_b32_e32 v10, 16, v10
	v_add3_u32 v11, v11, v57, s15
	global_store_dwordx4 v[76:77], v[58:61], off sc0 sc1
	s_add_i32 s17, s17, s52
	s_add_i32 s12, s12, s13
	v_and_or_b32 v58, v11, s16, v10
	v_bfe_u32 v10, v65, 16, 1
	v_add3_u32 v10, v65, v10, s15
	v_bfe_u32 v11, v67, 16, 1
	v_lshrrev_b32_e32 v10, 16, v10
	v_add3_u32 v11, v67, v11, s15
	v_and_or_b32 v59, v11, s16, v10
	v_bfe_u32 v10, v69, 16, 1
	v_add3_u32 v10, v69, v10, s15
	v_bfe_u32 v11, v71, 16, 1
	v_lshrrev_b32_e32 v10, 16, v10
	v_add3_u32 v11, v71, v11, s15
	v_and_or_b32 v60, v11, s16, v10
	v_bfe_u32 v10, v73, 16, 1
	v_add3_u32 v10, v73, v10, s15
	v_bfe_u32 v11, v75, 16, 1
	v_lshrrev_b32_e32 v10, 16, v10
	v_add3_u32 v11, v75, v11, s15
	v_and_or_b32 v61, v11, s16, v10
	v_mov_b32_e32 v11, s0
	v_or_b32_e32 v10, s4, v49
	v_lshlrev_b64 v[10:11], 7, v[10:11]
	v_lshl_add_u64 v[10:11], v[8:9], 0, v[10:11]
	global_store_dwordx4 v[10:11], v[58:61], off sc0 sc1
	s_waitcnt lgkmcnt(0)
	s_cmpk_lt_i32 s17, 0xd00
	s_cbranch_scc0 .LBB0_75

; #define LAS __attribute__((address_space(3)))
; __device__ __forceinline__ unsigned pk2(float lo, float hi) { return f2bf(lo) | (f2bf(hi) << 16); }
; #define LDS_WAIT() asm volatile("s_waitcnt lgkmcnt(0)" ::: "memory")
; __device__ __forceinline__ void wt_item(const float* __restrict__ W, int ldw, int K, int src_c0, bf16_t* __restrict__ WT, int dst_r0, int k0, LAS float* scr, int lane, int Ndst) {
; #pragma unroll 32
;     for (int i = 0; i < 32; ++i) { const int kk = 2 * i + (lane >> 5); scr[kk * 33 + (lane & 31)] = (src_c0 >= 0) ? W[(size_t)(k0 + kk) * ldw + src_c0 + (lane & 31)] : 0.f; }
;     LDS_WAIT(); asm volatile("" ::: "memory");
;     const int c = lane & 7;
; #pragma unroll
;     for (int j = 0; j < 4; ++j) { const int n = (lane >> 3) + 8 * j; const LAS float* s = scr + (8 * c) * 33 + n;
;         v4u o; o.x = pk2(s[0 * 33], s[1 * 33]); o.y = pk2(s[2 * 33], s[3 * 33]); o.z = pk2(s[4 * 33], s[5 * 33]); o.w = pk2(s[6 * 33], s[7 * 33]);
;         *(v4u*)(WT + ((size_t)(k0 >> 6) * Ndst + dst_r0 + n) * 64 + 8 * c) = o; }
;     LDS_WAIT(); asm volatile("" ::: "memory");
; }
; __device__ __forceinline__ void conv_plain(const float* W, int K, int N, bf16_t* WT, LAS float* scr, int gw, int NGW, int lane) {
;     const int nblk = N / 32, items = (K / 64) * nblk;
;     for (int it = gw; it < items; it += NGW) { const int kb = it / nblk, nb = it % nblk; wt_item(W, N, K, nb * 32, WT, nb * 32, kb * 64, scr, lane, N); }
.LBB0_77:
	s_waitcnt vmcnt(2)
	ds_write2_b32 v5, v57, v58 offset0:8 offset1:74
	s_waitcnt vmcnt(0)
	ds_write2_b32 v5, v59, v60 offset0:140 offset1:206
	s_waitcnt lgkmcnt(0)
	ds_read2_b32 v[10:11], v46 offset1:8
	ds_read2_b32 v[62:63], v46 offset0:33 offset1:41
	ds_read2_b32 v[64:65], v46 offset0:66 offset1:74
	ds_read2_b32 v[66:67], v46 offset0:99 offset1:107
	ds_read2_b32 v[68:69], v46 offset0:132 offset1:140
	s_waitcnt lgkmcnt(4)
	v_bfe_u32 v57, v10, 16, 1
	v_add3_u32 v10, v10, v57, s15
	s_waitcnt lgkmcnt(3)
	v_bfe_u32 v57, v62, 16, 1
	v_lshrrev_b32_e32 v10, 16, v10
	v_add3_u32 v57, v62, v57, s15
	ds_read2_b32 v[70:71], v46 offset0:165 offset1:173
	v_and_or_b32 v58, v57, s16, v10
	s_waitcnt lgkmcnt(3)
	v_bfe_u32 v10, v64, 16, 1
	v_add3_u32 v10, v64, v10, s15
	s_waitcnt lgkmcnt(2)
	v_bfe_u32 v57, v66, 16, 1
	ds_read2_b32 v[72:73], v46 offset0:198 offset1:206
	v_lshrrev_b32_e32 v10, 16, v10
	v_add3_u32 v57, v66, v57, s15
	ds_read2_b32 v[74:75], v46 offset0:231 offset1:239
	v_and_or_b32 v59, v57, s16, v10
	s_waitcnt lgkmcnt(3)
	v_bfe_u32 v10, v68, 16, 1
	v_add3_u32 v10, v68, v10, s15
	s_waitcnt lgkmcnt(2)
	v_bfe_u32 v57, v70, 16, 1
	v_lshrrev_b32_e32 v10, 16, v10
	v_add3_u32 v57, v70, v57, s15
	s_mul_hi_i32 s0, s18, 0xc00
	s_mulk_i32 s18, 0xc00
	s_ashr_i32 s1, s4, 31
	v_and_or_b32 v60, v57, s16, v10
	s_waitcnt lgkmcnt(1)
	v_bfe_u32 v10, v72, 16, 1
	s_add_u32 s4, s18, s4
	v_add3_u32 v10, v72, v10, s15
	s_waitcnt lgkmcnt(0)
	v_bfe_u32 v57, v74, 16, 1
	s_addc_u32 s0, s0, s1
	v_lshrrev_b32_e32 v10, 16, v10
	v_add3_u32 v57, v74, v57, s15
	v_and_or_b32 v61, v57, s16, v10
	v_mov_b32_e32 v77, s0
	v_or_b32_e32 v76, s4, v45
	v_bfe_u32 v10, v11, 16, 1
	v_lshlrev_b64 v[76:77], 7, v[76:77]
	v_add3_u32 v10, v11, v10, s15
	v_bfe_u32 v11, v63, 16, 1
	v_lshl_add_u64 v[76:77], v[8:9], 0, v[76:77]
	v_lshrrev_b32_e32 v10, 16, v10
	v_add3_u32 v11, v63, v11, s15
	global_store_dwordx4 v[76:77], v[58:61], off sc0 sc1
	ds_read2_b32 v[62:63], v46 offset0:16 offset1:24
	v_mov_b32_e32 v77, s0
	v_and_or_b32 v58, v11, s16, v10
	v_bfe_u32 v10, v65, 16, 1
	v_add3_u32 v10, v65, v10, s15
	v_bfe_u32 v11, v67, 16, 1
	v_lshrrev_b32_e32 v10, 16, v10
	v_add3_u32 v11, v67, v11, s15
	v_and_or_b32 v59, v11, s16, v10
	v_bfe_u32 v10, v69, 16, 1
	v_add3_u32 v10, v69, v10, s15
	v_bfe_u32 v11, v71, 16, 1
	v_lshrrev_b32_e32 v10, 16, v10
	v_add3_u32 v11, v71, v11, s15
	v_and_or_b32 v60, v11, s16, v10
	v_bfe_u32 v10, v73, 16, 1
	v_add3_u32 v10, v73, v10, s15
	v_bfe_u32 v11, v75, 16, 1
	v_lshrrev_b32_e32 v10, 16, v10
	v_add3_u32 v11, v75, v11, s15
	v_and_or_b32 v61, v11, s16, v10
	v_mov_b32_e32 v11, s0
	v_or_b32_e32 v10, s4, v47
	v_lshlrev_b64 v[10:11], 7, v[10:11]
	v_lshl_add_u64 v[10:11], v[8:9], 0, v[10:11]
	global_store_dwordx4 v[10:11], v[58:61], off sc0 sc1
	ds_read2_b32 v[10:11], v46 offset0:49 offset1:57
	ds_read2_b32 v[64:65], v46 offset0:82 offset1:90
	ds_read2_b32 v[66:67], v46 offset0:115 offset1:123
	s_waitcnt lgkmcnt(3)
	v_bfe_u32 v57, v62, 16, 1
	v_add3_u32 v57, v62, v57, s15
	s_waitcnt lgkmcnt(2)
	v_bfe_u32 v58, v10, 16, 1
	ds_read2_b32 v[68:69], v46 offset0:148 offset1:156
	v_lshrrev_b32_e32 v57, 16, v57
	v_add3_u32 v10, v10, v58, s15
	ds_read2_b32 v[70:71], v46 offset0:181 offset1:189
	v_and_or_b32 v58, v10, s16, v57
	s_waitcnt lgkmcnt(3)
	v_bfe_u32 v10, v64, 16, 1
	v_add3_u32 v10, v64, v10, s15
	s_waitcnt lgkmcnt(2)
	v_bfe_u32 v57, v66, 16, 1
	ds_read2_b32 v[72:73], v46 offset0:214 offset1:222
	v_lshrrev_b32_e32 v10, 16, v10
	v_add3_u32 v57, v66, v57, s15
	ds_read2_b32 v[74:75], v46 offset0:247 offset1:255
	v_and_or_b32 v59, v57, s16, v10
	s_waitcnt lgkmcnt(3)
	v_bfe_u32 v10, v68, 16, 1
	v_add3_u32 v10, v68, v10, s15
	s_waitcnt lgkmcnt(2)
	v_bfe_u32 v57, v70, 16, 1
	v_lshrrev_b32_e32 v10, 16, v10
	v_add3_u32 v57, v70, v57, s15
	v_and_or_b32 v60, v57, s16, v10
	s_waitcnt lgkmcnt(1)
	v_bfe_u32 v10, v72, 16, 1
	v_add3_u32 v10, v72, v10, s15
	s_waitcnt lgkmcnt(0)
	v_bfe_u32 v57, v74, 16, 1
	v_lshrrev_b32_e32 v10, 16, v10
	v_add3_u32 v57, v74, v57, s15
	v_and_or_b32 v61, v57, s16, v10
	v_or_b32_e32 v76, s4, v48
	v_bfe_u32 v10, v63, 16, 1
	v_lshlrev_b64 v[76:77], 7, v[76:77]
	v_add3_u32 v10, v63, v10, s15
	v_bfe_u32 v57, v11, 16, 1
	v_lshl_add_u64 v[76:77], v[8:9], 0, v[76:77]
	v_lshrrev_b32_e32 v10, 16, v10
	v_add3_u32 v11, v11, v57, s15
	global_store_dwordx4 v[76:77], v[58:61], off sc0 sc1
	s_add_i32 s17, s17, s52
	s_add_i32 s12, s12, s13
	v_and_or_b32 v58, v11, s16, v10
	v_bfe_u32 v10, v65, 16, 1
	v_add3_u32 v10, v65, v10, s15
	v_bfe_u32 v11, v67, 16, 1
	v_lshrrev_b32_e32 v10, 16, v10
	v_add3_u32 v11, v67, v11, s15
	v_and_or_b32 v59, v11, s16, v10
	v_bfe_u32 v10, v69, 16, 1
	v_add3_u32 v10, v69, v10, s15
	v_bfe_u32 v11, v71, 16, 1
	v_lshrrev_b32_e32 v10, 16, v10
	v_add3_u32 v11, v71, v11, s15
	v_and_or_b32 v60, v11, s16, v10
	v_bfe_u32 v10, v73, 16, 1
	v_add3_u32 v10, v73, v10, s15
	v_bfe_u32 v11, v75, 16, 1
	v_lshrrev_b32_e32 v10, 16, v10
	v_add3_u32 v11, v75, v11, s15
	v_and_or_b32 v61, v11, s16, v10
	v_mov_b32_e32 v11, s0
	v_or_b32_e32 v10, s4, v49
	v_lshlrev_b64 v[10:11], 7, v[10:11]
	v_lshl_add_u64 v[10:11], v[8:9], 0, v[10:11]
	global_store_dwordx4 v[10:11], v[58:61], off sc0 sc1
	s_waitcnt lgkmcnt(0)
	s_cmpk_lt_i32 s17, 0x300
	s_cbranch_scc0 .LBB0_94

; #define LAS __attribute__((address_space(3)))
; __device__ __forceinline__ unsigned pk2(float lo, float hi) { return f2bf(lo) | (f2bf(hi) << 16); }
; #define LDS_WAIT() asm volatile("s_waitcnt lgkmcnt(0)" ::: "memory")
; __device__ __forceinline__ void wt_item(const float* __restrict__ W, int ldw, int K, int src_c0, bf16_t* __restrict__ WT, int dst_r0, int k0, LAS float* scr, int lane, int Ndst) {
; #pragma unroll 32
;     for (int i = 0; i < 32; ++i) { const int kk = 2 * i + (lane >> 5); scr[kk * 33 + (lane & 31)] = (src_c0 >= 0) ? W[(size_t)(k0 + kk) * ldw + src_c0 + (lane & 31)] : 0.f; }
;     LDS_WAIT(); asm volatile("" ::: "memory");
;     const int c = lane & 7;
; #pragma unroll
;     for (int j = 0; j < 4; ++j) { const int n = (lane >> 3) + 8 * j; const LAS float* s = scr + (8 * c) * 33 + n;
;         v4u o; o.x = pk2(s[0 * 33], s[1 * 33]); o.y = pk2(s[2 * 33], s[3 * 33]); o.z = pk2(s[4 * 33], s[5 * 33]); o.w = pk2(s[6 * 33], s[7 * 33]);
;         *(v4u*)(WT + ((size_t)(k0 >> 6) * Ndst + dst_r0 + n) * 64 + 8 * c) = o; }
;     LDS_WAIT(); asm volatile("" ::: "memory");
; }
; __device__ __forceinline__ void conv_plain(const float* W, int K, int N, bf16_t* WT, LAS float* scr, int gw, int NGW, int lane) {
;     const int nblk = N / 32, items = (K / 64) * nblk;
;     for (int it = gw; it < items; it += NGW) { const int kb = it / nblk, nb = it % nblk; wt_item(W, N, K, nb * 32, WT, nb * 32, kb * 64, scr, lane, N); }
.LBB0_96:
	v_add_u32_e32 v10, 0x400, v56
	s_waitcnt vmcnt(2)
	ds_write2_b32 v10, v5, v57 offset0:8 offset1:74
	s_waitcnt vmcnt(0)
	ds_write2_b32 v10, v58, v59 offset0:140 offset1:206
	s_waitcnt lgkmcnt(0)
	ds_read2_b32 v[10:11], v46 offset1:8
	ds_read2_b32 v[62:63], v46 offset0:33 offset1:41
	ds_read2_b32 v[64:65], v46 offset0:66 offset1:74
	ds_read2_b32 v[66:67], v46 offset0:99 offset1:107
	ds_read2_b32 v[68:69], v46 offset0:132 offset1:140
	s_waitcnt lgkmcnt(4)
	v_bfe_u32 v5, v10, 16, 1
	v_add3_u32 v5, v10, v5, s18
	s_waitcnt lgkmcnt(3)
	v_bfe_u32 v10, v62, 16, 1
	v_lshrrev_b32_e32 v5, 16, v5
	v_add3_u32 v10, v62, v10, s18
	ds_read2_b32 v[70:71], v46 offset0:165 offset1:173
	v_and_or_b32 v58, v10, s19, v5
	s_waitcnt lgkmcnt(3)
	v_bfe_u32 v5, v64, 16, 1
	v_add3_u32 v5, v64, v5, s18
	s_waitcnt lgkmcnt(2)
	v_bfe_u32 v10, v66, 16, 1
	ds_read2_b32 v[72:73], v46 offset0:198 offset1:206
	v_lshrrev_b32_e32 v5, 16, v5
	v_add3_u32 v10, v66, v10, s18
	ds_read2_b32 v[74:75], v46 offset0:231 offset1:239
	v_and_or_b32 v59, v10, s19, v5
	s_waitcnt lgkmcnt(3)
	v_bfe_u32 v5, v68, 16, 1
	v_add3_u32 v5, v68, v5, s18
	s_waitcnt lgkmcnt(2)
	v_bfe_u32 v10, v70, 16, 1
	s_ashr_i32 s13, s12, 31
	v_lshrrev_b32_e32 v5, 16, v5
	v_add3_u32 v10, v70, v10, s18
	s_lshl_b64 s[0:1], s[12:13], 12
	s_ashr_i32 s12, s4, 31
	v_and_or_b32 v60, v10, s19, v5
	s_waitcnt lgkmcnt(1)
	v_bfe_u32 v5, v72, 16, 1
	s_add_u32 s0, s0, s4
	v_add3_u32 v5, v72, v5, s18
	s_waitcnt lgkmcnt(0)
	v_bfe_u32 v10, v74, 16, 1
	s_addc_u32 s1, s1, s12
	v_lshrrev_b32_e32 v5, 16, v5
	v_add3_u32 v10, v74, v10, s18
	v_and_or_b32 v61, v10, s19, v5
	v_mov_b32_e32 v77, s1
	v_or_b32_e32 v76, s0, v45
	v_bfe_u32 v5, v11, 16, 1
	v_lshlrev_b64 v[76:77], 7, v[76:77]
	v_add3_u32 v5, v11, v5, s18
	v_bfe_u32 v10, v63, 16, 1
	v_lshl_add_u64 v[76:77], v[8:9], 0, v[76:77]
	v_lshrrev_b32_e32 v5, 16, v5
	v_add3_u32 v10, v63, v10, s18
	global_store_dwordx4 v[76:77], v[58:61], off sc0 sc1
	v_mov_b32_e32 v11, s1
	ds_read2_b32 v[62:63], v46 offset0:16 offset1:24
	v_and_or_b32 v58, v10, s19, v5
	v_bfe_u32 v5, v65, 16, 1
	v_add3_u32 v5, v65, v5, s18
	v_bfe_u32 v10, v67, 16, 1
	v_lshrrev_b32_e32 v5, 16, v5
	v_add3_u32 v10, v67, v10, s18
	v_and_or_b32 v59, v10, s19, v5
	v_bfe_u32 v5, v69, 16, 1
	v_add3_u32 v5, v69, v5, s18
	v_bfe_u32 v10, v71, 16, 1
	v_lshrrev_b32_e32 v5, 16, v5
	v_add3_u32 v10, v71, v10, s18
	v_and_or_b32 v60, v10, s19, v5
	v_bfe_u32 v5, v73, 16, 1
	v_add3_u32 v5, v73, v5, s18
	v_bfe_u32 v10, v75, 16, 1
	v_lshrrev_b32_e32 v5, 16, v5
	v_add3_u32 v10, v75, v10, s18
	v_and_or_b32 v61, v10, s19, v5
	v_or_b32_e32 v10, s0, v47
	v_lshlrev_b64 v[10:11], 7, v[10:11]
	v_lshl_add_u64 v[10:11], v[8:9], 0, v[10:11]
	global_store_dwordx4 v[10:11], v[58:61], off sc0 sc1
	ds_read2_b32 v[10:11], v46 offset0:49 offset1:57
	ds_read2_b32 v[64:65], v46 offset0:82 offset1:90
	ds_read2_b32 v[66:67], v46 offset0:115 offset1:123
	s_waitcnt lgkmcnt(3)
	v_bfe_u32 v5, v62, 16, 1
	v_add3_u32 v5, v62, v5, s18
	s_waitcnt lgkmcnt(2)
	v_bfe_u32 v57, v10, 16, 1
	ds_read2_b32 v[68:69], v46 offset0:148 offset1:156
	v_lshrrev_b32_e32 v5, 16, v5
	v_add3_u32 v10, v10, v57, s18
	ds_read2_b32 v[70:71], v46 offset0:181 offset1:189
	v_and_or_b32 v58, v10, s19, v5
	s_waitcnt lgkmcnt(3)
	v_bfe_u32 v5, v64, 16, 1
	v_add3_u32 v5, v64, v5, s18
	s_waitcnt lgkmcnt(2)
	v_bfe_u32 v10, v66, 16, 1
	ds_read2_b32 v[72:73], v46 offset0:214 offset1:222
	v_lshrrev_b32_e32 v5, 16, v5
	v_add3_u32 v10, v66, v10, s18
	ds_read2_b32 v[74:75], v46 offset0:247 offset1:255
	v_and_or_b32 v59, v10, s19, v5
	s_waitcnt lgkmcnt(3)
	v_bfe_u32 v5, v68, 16, 1
	v_add3_u32 v5, v68, v5, s18
	s_waitcnt lgkmcnt(2)
	v_bfe_u32 v10, v70, 16, 1
	v_lshrrev_b32_e32 v5, 16, v5
	v_add3_u32 v10, v70, v10, s18
	v_and_or_b32 v60, v10, s19, v5
	s_waitcnt lgkmcnt(1)
	v_bfe_u32 v5, v72, 16, 1
	v_add3_u32 v5, v72, v5, s18
	s_waitcnt lgkmcnt(0)
	v_bfe_u32 v10, v74, 16, 1
	v_lshrrev_b32_e32 v5, 16, v5
	v_add3_u32 v10, v74, v10, s18
	v_and_or_b32 v61, v10, s19, v5
	v_mov_b32_e32 v77, s1
	v_or_b32_e32 v76, s0, v48
	v_bfe_u32 v5, v63, 16, 1
	v_lshlrev_b64 v[76:77], 7, v[76:77]
	v_add3_u32 v5, v63, v5, s18
	v_bfe_u32 v10, v11, 16, 1
	v_lshl_add_u64 v[76:77], v[8:9], 0, v[76:77]
	v_lshrrev_b32_e32 v5, 16, v5
	v_add3_u32 v10, v11, v10, s18
	global_store_dwordx4 v[76:77], v[58:61], off sc0 sc1
	v_mov_b32_e32 v11, s1
	s_add_i32 s20, s20, s52
	v_and_or_b32 v58, v10, s19, v5
	v_bfe_u32 v5, v65, 16, 1
	v_add3_u32 v5, v65, v5, s18
	v_bfe_u32 v10, v67, 16, 1
	v_lshrrev_b32_e32 v5, 16, v5
	v_add3_u32 v10, v67, v10, s18
	v_and_or_b32 v59, v10, s19, v5
	v_bfe_u32 v5, v69, 16, 1
	v_add3_u32 v5, v69, v5, s18
	v_bfe_u32 v10, v71, 16, 1
	v_lshrrev_b32_e32 v5, 16, v5
	v_add3_u32 v10, v71, v10, s18
	v_and_or_b32 v60, v10, s19, v5
	v_bfe_u32 v5, v73, 16, 1
	v_add3_u32 v5, v73, v5, s18
	v_bfe_u32 v10, v75, 16, 1
	v_lshrrev_b32_e32 v5, 16, v5
	v_add3_u32 v10, v75, v10, s18
	v_and_or_b32 v61, v10, s19, v5
	v_or_b32_e32 v10, s0, v49
	v_lshlrev_b64 v[10:11], 7, v[10:11]
	v_lshl_add_u64 v[10:11], v[8:9], 0, v[10:11]
	global_store_dwordx4 v[10:11], v[58:61], off sc0 sc1
	s_waitcnt lgkmcnt(0)
	s_add_i32 s16, s16, s17
	s_cmpk_lt_i32 s20, 0x400
	s_cbranch_scc0 .LBB0_113

; #define LAS __attribute__((address_space(3)))
; __device__ __forceinline__ unsigned pk2(float lo, float hi) { return f2bf(lo) | (f2bf(hi) << 16); }
; #define LDS_WAIT() asm volatile("s_waitcnt lgkmcnt(0)" ::: "memory")
; __device__ __forceinline__ void wt_item(const float* __restrict__ W, int ldw, int K, int src_c0, bf16_t* __restrict__ WT, int dst_r0, int k0, LAS float* scr, int lane, int Ndst) {
; #pragma unroll 32
;     for (int i = 0; i < 32; ++i) { const int kk = 2 * i + (lane >> 5); scr[kk * 33 + (lane & 31)] = (src_c0 >= 0) ? W[(size_t)(k0 + kk) * ldw + src_c0 + (lane & 31)] : 0.f; }
;     LDS_WAIT(); asm volatile("" ::: "memory");
;     const int c = lane & 7;
; #pragma unroll
;     for (int j = 0; j < 4; ++j) { const int n = (lane >> 3) + 8 * j; const LAS float* s = scr + (8 * c) * 33 + n;
;         v4u o; o.x = pk2(s[0 * 33], s[1 * 33]); o.y = pk2(s[2 * 33], s[3 * 33]); o.z = pk2(s[4 * 33], s[5 * 33]); o.w = pk2(s[6 * 33], s[7 * 33]);
;         *(v4u*)(WT + ((size_t)(k0 >> 6) * Ndst + dst_r0 + n) * 64 + 8 * c) = o; }
;     LDS_WAIT(); asm volatile("" ::: "memory");
; }
; __device__ __forceinline__ void conv_plain(const float* W, int K, int N, bf16_t* WT, LAS float* scr, int gw, int NGW, int lane) {
;     const int nblk = N / 32, items = (K / 64) * nblk;
;     for (int it = gw; it < items; it += NGW) { const int kb = it / nblk, nb = it % nblk; wt_item(W, N, K, nb * 32, WT, nb * 32, kb * 64, scr, lane, N); }
.LBB0_115:
	v_add_u32_e32 v8, 0x400, v56
	s_waitcnt vmcnt(2)
	ds_write2_b32 v8, v2, v10 offset0:8 offset1:74
	s_waitcnt vmcnt(0)
	ds_write2_b32 v8, v11, v58 offset0:140 offset1:206
	s_waitcnt lgkmcnt(0)
	ds_read2_b32 v[58:59], v46 offset1:8
	ds_read2_b32 v[60:61], v46 offset0:33 offset1:41
	ds_read2_b32 v[62:63], v46 offset0:66 offset1:74
	ds_read2_b32 v[64:65], v46 offset0:99 offset1:107
	ds_read2_b32 v[66:67], v46 offset0:132 offset1:140
	s_waitcnt lgkmcnt(4)
	v_bfe_u32 v2, v58, 16, 1
	v_add3_u32 v2, v58, v2, s14
	s_waitcnt lgkmcnt(3)
	v_bfe_u32 v8, v60, 16, 1
	v_lshrrev_b32_e32 v2, 16, v2
	v_add3_u32 v8, v60, v8, s14
	ds_read2_b32 v[68:69], v46 offset0:165 offset1:173
	v_and_or_b32 v8, v8, s15, v2
	s_waitcnt lgkmcnt(3)
	v_bfe_u32 v2, v62, 16, 1
	v_add3_u32 v2, v62, v2, s14
	s_waitcnt lgkmcnt(2)
	v_bfe_u32 v9, v64, 16, 1
	ds_read2_b32 v[70:71], v46 offset0:198 offset1:206
	v_lshrrev_b32_e32 v2, 16, v2
	v_add3_u32 v9, v64, v9, s14
	ds_read2_b32 v[72:73], v46 offset0:231 offset1:239
	s_ashr_i32 s7, s6, 31
	v_and_or_b32 v9, v9, s15, v2
	s_waitcnt lgkmcnt(3)
	v_bfe_u32 v2, v66, 16, 1
	s_lshl_b64 s[0:1], s[6:7], 11
	s_ashr_i32 s6, s4, 31
	v_add3_u32 v2, v66, v2, s14
	s_waitcnt lgkmcnt(2)
	v_bfe_u32 v10, v68, 16, 1
	s_add_u32 s0, s0, s4
	v_lshrrev_b32_e32 v2, 16, v2
	v_add3_u32 v10, v68, v10, s14
	s_addc_u32 s1, s1, s6
	v_and_or_b32 v10, v10, s15, v2
	s_waitcnt lgkmcnt(1)
	v_bfe_u32 v2, v70, 16, 1
	v_add3_u32 v2, v70, v2, s14
	s_waitcnt lgkmcnt(0)
	v_bfe_u32 v11, v72, 16, 1
	v_mov_b32_e32 v75, s1
	v_or_b32_e32 v74, s0, v45
	v_lshrrev_b32_e32 v2, 16, v2
	v_add3_u32 v11, v72, v11, s14
	v_lshlrev_b64 v[74:75], 7, v[74:75]
	v_and_or_b32 v11, v11, s15, v2
	v_lshl_add_u64 v[74:75], v[4:5], 0, v[74:75]
	v_bfe_u32 v2, v59, 16, 1
	global_store_dwordx4 v[74:75], v[8:11], off sc0 sc1
	v_add3_u32 v2, v59, v2, s14
	v_lshrrev_b32_e32 v2, 16, v2
	v_bfe_u32 v8, v61, 16, 1
	v_add3_u32 v8, v61, v8, s14
	v_and_or_b32 v8, v8, s15, v2
	v_bfe_u32 v2, v63, 16, 1
	v_add3_u32 v2, v63, v2, s14
	v_bfe_u32 v9, v65, 16, 1
	v_lshrrev_b32_e32 v2, 16, v2
	v_add3_u32 v9, v65, v9, s14
	v_and_or_b32 v9, v9, s15, v2
	v_bfe_u32 v2, v67, 16, 1
	v_add3_u32 v2, v67, v2, s14
	v_bfe_u32 v10, v69, 16, 1
	v_lshrrev_b32_e32 v2, 16, v2
	v_add3_u32 v10, v69, v10, s14
	v_and_or_b32 v10, v10, s15, v2
	v_bfe_u32 v2, v71, 16, 1
	v_add3_u32 v2, v71, v2, s14
	v_bfe_u32 v11, v73, 16, 1
	v_mov_b32_e32 v59, s1
	v_or_b32_e32 v58, s0, v47
	v_lshrrev_b32_e32 v2, 16, v2
	v_add3_u32 v11, v73, v11, s14
	v_lshlrev_b64 v[58:59], 7, v[58:59]
	v_and_or_b32 v11, v11, s15, v2
	ds_read2_b32 v[60:61], v46 offset0:16 offset1:24
	v_lshl_add_u64 v[58:59], v[4:5], 0, v[58:59]
	global_store_dwordx4 v[58:59], v[8:11], off sc0 sc1
	ds_read2_b32 v[58:59], v46 offset0:49 offset1:57
	ds_read2_b32 v[62:63], v46 offset0:82 offset1:90
	ds_read2_b32 v[64:65], v46 offset0:115 offset1:123
	s_waitcnt lgkmcnt(3)
	v_bfe_u32 v2, v60, 16, 1
	v_add3_u32 v2, v60, v2, s14
	s_waitcnt lgkmcnt(2)
	v_bfe_u32 v8, v58, 16, 1
	ds_read2_b32 v[66:67], v46 offset0:148 offset1:156
	v_lshrrev_b32_e32 v2, 16, v2
	v_add3_u32 v8, v58, v8, s14
	ds_read2_b32 v[68:69], v46 offset0:181 offset1:189
	v_and_or_b32 v8, v8, s15, v2
	s_waitcnt lgkmcnt(3)
	v_bfe_u32 v2, v62, 16, 1
	v_add3_u32 v2, v62, v2, s14
	s_waitcnt lgkmcnt(2)
	v_bfe_u32 v9, v64, 16, 1
	ds_read2_b32 v[70:71], v46 offset0:214 offset1:222
	v_lshrrev_b32_e32 v2, 16, v2
	v_add3_u32 v9, v64, v9, s14
	ds_read2_b32 v[72:73], v46 offset0:247 offset1:255
	v_and_or_b32 v9, v9, s15, v2
	s_waitcnt lgkmcnt(3)
	v_bfe_u32 v2, v66, 16, 1
	v_add3_u32 v2, v66, v2, s14
	s_waitcnt lgkmcnt(2)
	v_bfe_u32 v10, v68, 16, 1
	v_lshrrev_b32_e32 v2, 16, v2
	v_add3_u32 v10, v68, v10, s14
	v_and_or_b32 v10, v10, s15, v2
	s_waitcnt lgkmcnt(1)
	v_bfe_u32 v2, v70, 16, 1
	v_add3_u32 v2, v70, v2, s14
	s_waitcnt lgkmcnt(0)
	v_bfe_u32 v11, v72, 16, 1
	v_mov_b32_e32 v75, s1
	v_or_b32_e32 v74, s0, v48
	v_lshrrev_b32_e32 v2, 16, v2
	v_add3_u32 v11, v72, v11, s14
	v_lshlrev_b64 v[74:75], 7, v[74:75]
	v_and_or_b32 v11, v11, s15, v2
	v_lshl_add_u64 v[74:75], v[4:5], 0, v[74:75]
	v_bfe_u32 v2, v61, 16, 1
	global_store_dwordx4 v[74:75], v[8:11], off sc0 sc1
	v_add3_u32 v2, v61, v2, s14
	v_lshrrev_b32_e32 v2, 16, v2
	v_bfe_u32 v8, v59, 16, 1
	v_add3_u32 v8, v59, v8, s14
	v_and_or_b32 v8, v8, s15, v2
	v_bfe_u32 v2, v63, 16, 1
	v_add3_u32 v2, v63, v2, s14
	v_bfe_u32 v9, v65, 16, 1
	v_lshrrev_b32_e32 v2, 16, v2
	v_add3_u32 v9, v65, v9, s14
	v_and_or_b32 v9, v9, s15, v2
	v_bfe_u32 v2, v67, 16, 1
	v_add3_u32 v2, v67, v2, s14
	v_bfe_u32 v10, v69, 16, 1
	v_lshrrev_b32_e32 v2, 16, v2
	v_add3_u32 v10, v69, v10, s14
	v_and_or_b32 v10, v10, s15, v2
	v_bfe_u32 v2, v71, 16, 1
	v_add3_u32 v2, v71, v2, s14
	v_bfe_u32 v11, v73, 16, 1
	v_mov_b32_e32 v59, s1
	v_or_b32_e32 v58, s0, v49
	v_lshrrev_b32_e32 v2, 16, v2
	v_add3_u32 v11, v73, v11, s14
	v_lshlrev_b64 v[58:59], 7, v[58:59]
	v_and_or_b32 v11, v11, s15, v2
	v_lshl_add_u64 v[58:59], v[4:5], 0, v[58:59]
	global_store_dwordx4 v[58:59], v[8:11], off sc0 sc1
	s_waitcnt lgkmcnt(0)
	s_add_i32 s16, s16, s52
	s_add_i32 s12, s12, s13
	s_cmpk_lt_i32 s16, 0x800
	s_cbranch_scc0 .LBB0_132

; __device__ __forceinline__ float bf2f(unsigned h) { return __uint_as_float(h << 16); }
; __device__ __forceinline__ void mla_mid(const bf16_t* __restrict__ wino, const float* __restrict__ gq, const float* __restrict__ gkv, const float* __restrict__ cs_tab, const float* __restrict__ sn_tab, ...
;     const f32x4 gq0 = *(const f32x4*)(gq + lane * 8), gq1 = *(const f32x4*)(gq + lane * 8 + 4), gk0 = *(const f32x4*)(gkv + lane * 8), gk1 = *(const f32x4*)(gkv + lane * 8 + 4);
;     for (int m0 = 4 * gw; m0 < M_TOK; m0 += 4 * NGW) {
;         v4u v[4][2]; unsigned w[4]; float cc[4], ss[4];
; #pragma unroll
;         for (int rr = 0; rr < 4; ++rr) { const bf16_t* row = wino + (size_t)(m0 + rr) * 256; constexpr size_t TS = (size_t)M_TOK * 256;
;             v[rr][0] = *(const v4u*)(row + (size_t)(lane >> 5) * TS + (lane & 31) * 8); v[rr][1] = *(const v4u*)(row + (size_t)(2 + (lane >> 5)) * TS + (lane & 31) * 8);
;             w[rr] = *(const unsigned*)(row + 12 * TS + 2 * (lane & 31));
;             const int pos = (m0 + rr) & (SEQ - 1); cc[rr] = cs_tab[pos * 32 + (lane & 31)]; ss[rr] = sn_tab[pos * 32 + (lane & 31)]; }
; #pragma unroll
;         for (int rr = 0; rr < 4; ++rr) { const int m = m0 + rr;
; #pragma unroll
;             for (int part = 0; part < 2; ++part) {
;                 float f[8]; float s = 0.f;
; #pragma unroll
;                 for (int e = 0; e < 4; ++e) { f[2 * e] = bf2f(v[rr][part][e] & 0xffffu); f[2 * e + 1] = bf2f(v[rr][part][e] >> 16); s += f[2 * e] * f[2 * e] + f[2 * e + 1] * f[2 * e + 1]; }
;                 const float rstd = 1.0f / sqrtf(wave_sum(s) * (1.f / LORA) + RMS_EPS);
;                 const f32x4 g0 = part == 0 ? gq0 : gk0, g1 = part == 0 ? gq1 : gk1;
;                 v4u o; o.x = pk2(f[0] * rstd * g0[0], f[1] * rstd * g0[1]); o.y = pk2(f[2] * rstd * g0[2], f[3] * rstd * g0[3]);
;                 o.z = pk2(f[4] * rstd * g1[0], f[5] * rstd * g1[1]); o.w = pk2(f[6] * rstd * g1[2], f[7] * rstd * g1[3]);
;                 *(v4u*)((part == 0 ? cqn : ckvn) + ((size_t)(lane >> 3) * M_TOK + m) * 64 + (lane & 7) * 8) = o;
;             }
;             if (lane < 32) { const float x1 = bf2f(w[rr] & 0xffffu), x2 = bf2f(w[rr] >> 16);
;                 *(unsigned*)(kr + (size_t)m * 64 + 2 * lane) = pk2(x1 * cc[rr] - x2 * ss[rr], x1 * ss[rr] + x2 * cc[rr]); }
.LBB0_212:
	v_lshl_add_u64 v[16:17], v[4:5], 0, s[46:47]
	v_add_co_u32_e32 v18, vcc, 0x8800000, v16
	s_add_i32 s0, s8, 32
	s_nop 0
	v_addc_co_u32_e32 v19, vcc, 0, v17, vcc
	global_load_dwordx4 v[72:75], v[18:19], off
	v_add_co_u32_e32 v16, vcc, 0x9800000, v16
	s_and_b32 s0, s0, 0x3ffa0
	s_nop 0
	v_addc_co_u32_e32 v17, vcc, 0, v17, vcc
	global_load_dwordx4 v[40:43], v[16:17], off
	v_or_b32_e32 v20, s0, v1
	s_add_i32 s0, s8, 64
	v_lshlrev_b32_e32 v20, 2, v20
	s_and_b32 s0, s0, 0x3ffc0
	v_lshl_add_u64 v[70:71], v[52:53], 0, s[46:47]
	global_load_dwordx4 v[36:39], v[18:19], off offset:512
	global_load_dwordx4 v[32:35], v[16:17], off offset:512
	global_load_dword v61, v[70:71], off offset:-512
	global_load_dword v66, v20, s[34:35]
	global_load_dword v68, v20, s[86:87]
	global_load_dwordx4 v[28:31], v[18:19], off offset:1024
	global_load_dwordx4 v[24:27], v[16:17], off offset:1024
	global_load_dword v57, v[70:71], off
	v_or_b32_e32 v20, s0, v1
	v_lshlrev_b32_e32 v20, 2, v20
	s_add_i32 s0, s8, 0x60
	global_load_dword v60, v20, s[34:35]
	global_load_dword v62, v20, s[86:87]
	s_nop 0
	global_load_dwordx4 v[20:23], v[18:19], off offset:1536
	s_nop 0
	global_load_dwordx4 v[16:19], v[16:17], off offset:1536
	s_nop 0
	global_load_dword v55, v[70:71], off offset:512
	s_and_b32 s0, s0, 0x3ffe0
	s_waitcnt vmcnt(24)
	v_or_b32_e32 v54, s0, v1
	s_waitcnt vmcnt(23)
	v_lshlrev_b32_e32 v56, 2, v54
	global_load_dword v54, v56, s[34:35]
	s_nop 0
	global_load_dword v56, v56, s[86:87]
	s_waitcnt vmcnt(16)
	v_lshlrev_b32_e32 v59, 16, v73
	v_lshlrev_b32_e32 v58, 16, v72
	v_pk_mul_f32 v[64:65], v[58:59], v[58:59]
	v_and_b32_e32 v73, 0xffff0000, v73
	v_and_b32_e32 v72, 0xffff0000, v72
	v_lshlrev_b32_e32 v77, 16, v75
	v_lshlrev_b32_e32 v76, 16, v74
	v_pk_fma_f32 v[64:65], v[72:73], v[72:73], v[64:65]
	v_pk_mul_f32 v[78:79], v[76:77], v[76:77]
	v_and_b32_e32 v75, 0xffff0000, v75
	v_and_b32_e32 v74, 0xffff0000, v74
	v_pk_fma_f32 v[78:79], v[74:75], v[74:75], v[78:79]
	v_add_f32_e32 v63, v64, v65
	v_add_f32_e32 v63, v78, v63
	v_add_f32_e32 v63, v79, v63
	s_nop 1
	v_add_f32_dpp v63, v63, v63 quad_perm:[1,0,3,2] row_mask:0xf bank_mask:0xf bound_ctrl:1
	s_nop 1
	v_add_f32_dpp v63, v63, v63 quad_perm:[2,3,0,1] row_mask:0xf bank_mask:0xf bound_ctrl:1
	s_nop 1
	v_add_f32_dpp v63, v63, v63 row_half_mirror row_mask:0xf bank_mask:0xf bound_ctrl:1
	s_nop 1
	v_add_f32_dpp v63, v63, v63 row_mirror row_mask:0xf bank_mask:0xf bound_ctrl:1
	v_mov_b32_e32 v64, v63
	s_nop 1
	v_permlane16_swap_b32_e32 v63, v64
	v_add_f32_e32 v63, v63, v64
	v_mov_b32_e32 v64, v63
	s_nop 1
	v_permlane32_swap_b32_e32 v63, v64
	v_add_f32_e32 v63, v63, v64
	v_fmamk_f32 v63, v63, 0x3b000000, v218
	v_cmp_gt_f32_e32 vcc, s30, v63
	v_mul_f32_e32 v64, 0x4f800000, v63
	s_nop 0
	v_cndmask_b32_e32 v63, v63, v64, vcc
	v_sqrt_f32_e32 v64, v63
	s_nop 0
	v_add_u32_e32 v65, -1, v64
	v_fma_f32 v67, -v65, v64, v63
	v_cmp_ge_f32_e64 s[42:43], 0, v67
	v_add_u32_e32 v67, 1, v64
	s_nop 0
	v_cndmask_b32_e64 v65, v64, v65, s[42:43]
	v_fma_f32 v64, -v67, v64, v63
	v_cmp_lt_f32_e64 s[42:43], 0, v64
	s_nop 1
	v_cndmask_b32_e64 v64, v65, v67, s[42:43]
	v_mul_f32_e32 v65, 0x37800000, v64
	v_cndmask_b32_e32 v64, v64, v65, vcc
	v_cmp_class_f32_e32 vcc, v63, v215
	s_nop 1
	v_cndmask_b32_e32 v63, v64, v63, vcc
	v_div_scale_f32 v64, s[0:1], v63, v63, 1.0
	v_rcp_f32_e32 v65, v64
	s_mov_b32 s0, 0x1d000000
	v_fma_f32 v67, -v64, v65, 1.0
	v_fmac_f32_e32 v65, v67, v65
	v_div_scale_f32 v67, vcc, 1.0, v63, 1.0
	v_mul_f32_e32 v69, v67, v65
	v_fma_f32 v78, -v64, v69, v67
	v_fmac_f32_e32 v69, v78, v65
	v_fma_f32 v64, -v64, v69, v67
	v_div_fmas_f32 v64, v64, v65, v69
	v_div_fixup_f32 v64, v64, v63, 1.0
	v_pk_mul_f32 v[58:59], v[64:65], v[58:59] op_sel_hi:[0,1]
	v_pk_mul_f32 v[72:73], v[64:65], v[72:73] op_sel_hi:[0,1]
	v_pk_mul_f32 v[76:77], v[64:65], v[76:77] op_sel_hi:[0,1]
	v_pk_mul_f32 v[64:65], v[64:65], v[74:75] op_sel_hi:[0,1]
	v_pk_mul_f32 v[64:65], v[46:47], v[64:65]
	v_pk_mul_f32 v[58:59], v[14:15], v[58:59]
	v_pk_mul_f32 v[72:73], v[44:45], v[72:73]
	v_bfe_u32 v63, v65, 16, 1
	v_bfe_u32 v67, v64, 16, 1
	v_pk_mul_f32 v[76:77], v[10:11], v[76:77]
	v_bfe_u32 v69, v73, 16, 1
	v_add3_u32 v64, v64, v67, s63
	v_add3_u32 v63, v65, v63, s63
	v_bfe_u32 v65, v58, 16, 1
	v_bfe_u32 v67, v59, 16, 1
	v_bfe_u32 v74, v72, 16, 1
	v_add3_u32 v69, v73, v69, s63
	v_bfe_u32 v73, v76, 16, 1
	v_add3_u32 v59, v59, v67, s63
	v_add3_u32 v58, v58, v65, s63
	v_add3_u32 v72, v72, v74, s63
	v_bfe_u32 v74, v77, 16, 1
	v_add3_u32 v73, v76, v73, s63
	v_lshrrev_b32_e32 v58, 16, v58
	v_lshrrev_b32_e32 v59, 16, v59
	v_add3_u32 v74, v77, v74, s63
	v_lshrrev_b32_e32 v65, 16, v73
	v_and_or_b32 v73, v69, s60, v59
	v_and_or_b32 v72, v72, s60, v58
	v_lshl_add_u64 v[58:59], v[48:49], 0, s[46:47]
	v_lshrrev_b32_e32 v67, 16, v74
	v_and_or_b32 v74, v64, s60, v65
	v_add_co_u32_e32 v64, vcc, s0, v58
	v_and_or_b32 v75, v63, s60, v67
	s_nop 0
	v_addc_co_u32_e32 v65, vcc, 0, v59, vcc
	global_store_dwordx4 v[64:65], v[72:75], off sc0 sc1
	s_waitcnt vmcnt(16)
; __device__ __forceinline__ float bf2f(unsigned h) { return __uint_as_float(h << 16); }
; __device__ __forceinline__ unsigned pk2(float lo, float hi) { return f2bf(lo) | (f2bf(hi) << 16); }
; __device__ __forceinline__ void mla_mid(const bf16_t* __restrict__ wino, const float* __restrict__ gq, const float* __restrict__ gkv, const float* __restrict__ cs_tab, const float* __restrict__ sn_tab, ...
;     ...
;             for (int part = 0; part < 2; ++part) {
;                 float f[8]; float s = 0.f;
; #pragma unroll
;                 for (int e = 0; e < 4; ++e) { f[2 * e] = bf2f(v[rr][part][e] & 0xffffu); f[2 * e + 1] = bf2f(v[rr][part][e] >> 16); s += f[2 * e] * f[2 * e] + f[2 * e + 1] * f[2 * e + 1]; }
;                 const float rstd = 1.0f / sqrtf(wave_sum(s) * (1.f / LORA) + RMS_EPS);
;                 const f32x4 g0 = part == 0 ? gq0 : gk0, g1 = part == 0 ? gq1 : gk1;
;                 v4u o; o.x = pk2(f[0] * rstd * g0[0], f[1] * rstd * g0[1]); o.y = pk2(f[2] * rstd * g0[2], f[3] * rstd * g0[3]);
;                 o.z = pk2(f[4] * rstd * g1[0], f[5] * rstd * g1[1]); o.w = pk2(f[6] * rstd * g1[2], f[7] * rstd * g1[3]);
;                 *(v4u*)((part == 0 ? cqn : ckvn) + ((size_t)(lane >> 3) * M_TOK + m) * 64 + (lane & 7) * 8) = o;
;             }
;             if (lane < 32) { const float x1 = bf2f(w[rr] & 0xffffu), x2 = bf2f(w[rr] >> 16);
;                 *(unsigned*)(kr + (size_t)m * 64 + 2 * lane) = pk2(x1 * cc[rr] - x2 * ss[rr], x1 * ss[rr] + x2 * cc[rr]); }
	v_lshlrev_b32_e32 v77, 16, v43
	v_lshlrev_b32_e32 v76, 16, v42
	v_lshlrev_b32_e32 v73, 16, v41
	v_lshlrev_b32_e32 v72, 16, v40
	v_pk_mul_f32 v[74:75], v[72:73], v[72:73]
	v_and_b32_e32 v41, 0xffff0000, v41
	v_and_b32_e32 v40, 0xffff0000, v40
	v_pk_fma_f32 v[74:75], v[40:41], v[40:41], v[74:75]
	v_pk_mul_f32 v[78:79], v[76:77], v[76:77]
	v_and_b32_e32 v43, 0xffff0000, v43
	v_and_b32_e32 v42, 0xffff0000, v42
	v_pk_fma_f32 v[78:79], v[42:43], v[42:43], v[78:79]
	v_add_f32_e32 v63, v74, v75
	v_add_f32_e32 v63, v78, v63
	v_add_f32_e32 v63, v79, v63
	s_nop 1
	v_add_f32_dpp v63, v63, v63 quad_perm:[1,0,3,2] row_mask:0xf bank_mask:0xf bound_ctrl:1
	s_nop 1
	v_add_f32_dpp v63, v63, v63 quad_perm:[2,3,0,1] row_mask:0xf bank_mask:0xf bound_ctrl:1
	s_nop 1
	v_add_f32_dpp v63, v63, v63 row_half_mirror row_mask:0xf bank_mask:0xf bound_ctrl:1
	s_nop 1
	v_add_f32_dpp v63, v63, v63 row_mirror row_mask:0xf bank_mask:0xf bound_ctrl:1
	v_mov_b32_e32 v67, v63
	s_nop 1
	v_permlane16_swap_b32_e32 v63, v67
	v_add_f32_e32 v63, v63, v67
	v_mov_b32_e32 v67, v63
	s_nop 1
	v_permlane32_swap_b32_e32 v63, v67
	v_add_f32_e32 v63, v63, v67
	v_fmamk_f32 v63, v63, 0x3b000000, v218
	v_cmp_gt_f32_e32 vcc, s30, v63
	v_mul_f32_e32 v67, 0x4f800000, v63
	s_nop 0
	v_cndmask_b32_e32 v63, v63, v67, vcc
	v_sqrt_f32_e32 v67, v63
	s_nop 0
	v_add_u32_e32 v69, -1, v67
	v_fma_f32 v74, -v69, v67, v63
	v_cmp_ge_f32_e64 s[42:43], 0, v74
	v_add_u32_e32 v74, 1, v67
	s_nop 0
	v_cndmask_b32_e64 v69, v67, v69, s[42:43]
	v_fma_f32 v67, -v74, v67, v63
	v_cmp_lt_f32_e64 s[42:43], 0, v67
	s_nop 1
	v_cndmask_b32_e64 v67, v69, v74, s[42:43]
	v_mul_f32_e32 v69, 0x37800000, v67
	v_cndmask_b32_e32 v67, v67, v69, vcc
	v_cmp_class_f32_e32 vcc, v63, v215
	s_nop 1
	v_cndmask_b32_e32 v63, v67, v63, vcc
	v_div_scale_f32 v67, s[0:1], v63, v63, 1.0
	v_rcp_f32_e32 v69, v67
	s_nop 0
	v_fma_f32 v74, -v67, v69, 1.0
	v_fmac_f32_e32 v69, v74, v69
	v_div_scale_f32 v74, vcc, 1.0, v63, 1.0
	v_mul_f32_e32 v75, v74, v69
	v_fma_f32 v78, -v67, v75, v74
	v_fmac_f32_e32 v75, v78, v69
	v_fma_f32 v67, -v67, v75, v74
	v_div_fmas_f32 v67, v67, v69, v75
	v_div_fixup_f32 v74, v67, v63, 1.0
	v_pk_mul_f32 v[40:41], v[74:75], v[40:41] op_sel_hi:[0,1]
	v_pk_mul_f32 v[40:41], v[12:13], v[40:41]
	v_pk_mul_f32 v[76:77], v[74:75], v[76:77] op_sel_hi:[0,1]
	v_pk_mul_f32 v[42:43], v[74:75], v[42:43] op_sel_hi:[0,1]
	v_pk_mul_f32 v[72:73], v[74:75], v[72:73] op_sel_hi:[0,1]
	v_pk_mul_f32 v[76:77], v[2:3], v[76:77]
	v_pk_mul_f32 v[42:43], v[8:9], v[42:43]
	v_bfe_u32 v74, v40, 16, 1
	v_pk_mul_f32 v[72:73], v[6:7], v[72:73]
	v_bfe_u32 v63, v43, 16, 1
	v_bfe_u32 v67, v42, 16, 1
	v_bfe_u32 v69, v41, 16, 1
	v_add3_u32 v40, v40, v74, s63
	v_bfe_u32 v74, v77, 16, 1
	v_add3_u32 v41, v41, v69, s63
	v_add3_u32 v42, v42, v67, s63
	v_add3_u32 v43, v43, v63, s63
	v_bfe_u32 v63, v72, 16, 1
	v_bfe_u32 v67, v73, 16, 1
	v_bfe_u32 v69, v76, 16, 1
	v_add3_u32 v74, v77, v74, s63
	v_add3_u32 v69, v76, v69, s63
	v_add3_u32 v67, v73, v67, s63
	v_add3_u32 v63, v72, v63, s63
	v_lshrrev_b32_e32 v72, 16, v74
	v_lshrrev_b32_e32 v63, 16, v63
	v_lshrrev_b32_e32 v67, 16, v67
	v_lshrrev_b32_e32 v69, 16, v69
	v_and_or_b32 v43, v43, s60, v72
	v_add_co_u32_e32 v72, vcc, 0x1e000000, v58
	v_and_or_b32 v42, v42, s60, v69
	v_and_or_b32 v41, v41, s60, v67
	v_and_or_b32 v40, v40, s60, v63
	v_addc_co_u32_e32 v73, vcc, 0, v59, vcc
	global_store_dwordx4 v[72:73], v[40:43], off sc0 sc1
	s_nop 1
	v_lshl_add_u64 v[40:41], v[50:51], 0, s[46:47]
	s_and_saveexec_b64 s[6:7], s[40:41]
	s_cbranch_execz .LBB0_214
	s_and_b32 s0, s8, 0x3ff80
	global_load_dword v43, v[70:71], off offset:-1024
	v_or_b32_e32 v42, s0, v1
	v_lshlrev_b32_e32 v63, 2, v42
	global_load_dword v42, v63, s[86:87]
	global_load_dword v70, v63, s[34:35]
	s_waitcnt vmcnt(2)
	v_lshlrev_b32_e32 v73, 16, v43
	v_and_b32_e32 v72, 0xffff0000, v43
	s_waitcnt vmcnt(1)
	v_pk_mul_f32 v[42:43], v[42:43], v[72:73] op_sel:[0,1] op_sel_hi:[0,0]
	s_waitcnt vmcnt(0)
	v_pk_fma_f32 v[74:75], v[70:71], v[72:73], v[42:43]
	v_pk_fma_f32 v[42:43], v[70:71], v[72:73], v[42:43] op_sel_hi:[0,1,1] neg_lo:[0,0,1] neg_hi:[0,0,1]
	v_and_b32_sdwa v42, v43, v217 dst_sel:DWORD dst_unused:UNUSED_PAD src0_sel:WORD_1 src1_sel:DWORD
	v_and_b32_sdwa v63, v74, v217 dst_sel:DWORD dst_unused:UNUSED_PAD src0_sel:WORD_1 src1_sel:DWORD
	v_add3_u32 v42, v43, v42, s63
	v_add3_u32 v63, v74, v63, s63
	v_lshrrev_b32_e32 v42, 16, v42
	v_and_or_b32 v42, v63, s60, v42
	global_store_dword v[40:41], v42, off offset:-256
; __device__ __forceinline__ float bf2f(unsigned h) { return __uint_as_float(h << 16); }
; __device__ __forceinline__ unsigned pk2(float lo, float hi) { return f2bf(lo) | (f2bf(hi) << 16); }
; __device__ __forceinline__ void mla_mid(const bf16_t* __restrict__ wino, const float* __restrict__ gq, const float* __restrict__ gkv, const float* __restrict__ cs_tab, const float* __restrict__ sn_tab, ...
;     ...
;             for (int part = 0; part < 2; ++part) {
;                 float f[8]; float s = 0.f;
; #pragma unroll
;                 for (int e = 0; e < 4; ++e) { f[2 * e] = bf2f(v[rr][part][e] & 0xffffu); f[2 * e + 1] = bf2f(v[rr][part][e] >> 16); s += f[2 * e] * f[2 * e] + f[2 * e + 1] * f[2 * e + 1]; }
;                 const float rstd = 1.0f / sqrtf(wave_sum(s) * (1.f / LORA) + RMS_EPS);
;                 const f32x4 g0 = part == 0 ? gq0 : gk0, g1 = part == 0 ? gq1 : gk1;
;                 v4u o; o.x = pk2(f[0] * rstd * g0[0], f[1] * rstd * g0[1]); o.y = pk2(f[2] * rstd * g0[2], f[3] * rstd * g0[3]);
;                 o.z = pk2(f[4] * rstd * g1[0], f[5] * rstd * g1[1]); o.w = pk2(f[6] * rstd * g1[2], f[7] * rstd * g1[3]);
;                 *(v4u*)((part == 0 ? cqn : ckvn) + ((size_t)(lane >> 3) * M_TOK + m) * 64 + (lane & 7) * 8) = o;
;             }
.LBB0_214:
	s_or_b64 exec, exec, s[6:7]
	s_waitcnt vmcnt(16)
	v_lshlrev_b32_e32 v43, 16, v37
	v_lshlrev_b32_e32 v42, 16, v36
	v_pk_mul_f32 v[70:71], v[42:43], v[42:43]
	v_and_b32_e32 v37, 0xffff0000, v37
	v_and_b32_e32 v36, 0xffff0000, v36
	v_lshlrev_b32_e32 v73, 16, v39
	v_lshlrev_b32_e32 v72, 16, v38
	v_pk_fma_f32 v[70:71], v[36:37], v[36:37], v[70:71]
	v_pk_mul_f32 v[74:75], v[72:73], v[72:73]
	v_and_b32_e32 v39, 0xffff0000, v39
	v_and_b32_e32 v38, 0xffff0000, v38
	v_pk_fma_f32 v[74:75], v[38:39], v[38:39], v[74:75]
	v_add_f32_e32 v63, v70, v71
	v_add_f32_e32 v63, v74, v63
	v_add_f32_e32 v63, v75, v63
	s_nop 1
	v_add_f32_dpp v63, v63, v63 quad_perm:[1,0,3,2] row_mask:0xf bank_mask:0xf bound_ctrl:1
	s_nop 1
	v_add_f32_dpp v63, v63, v63 quad_perm:[2,3,0,1] row_mask:0xf bank_mask:0xf bound_ctrl:1
	s_nop 1
	v_add_f32_dpp v63, v63, v63 row_half_mirror row_mask:0xf bank_mask:0xf bound_ctrl:1
	s_nop 1
	v_add_f32_dpp v63, v63, v63 row_mirror row_mask:0xf bank_mask:0xf bound_ctrl:1
	v_mov_b32_e32 v67, v63
	s_nop 1
	v_permlane16_swap_b32_e32 v63, v67
	v_add_f32_e32 v63, v63, v67
	v_mov_b32_e32 v67, v63
	s_nop 1
	v_permlane32_swap_b32_e32 v63, v67
	v_add_f32_e32 v63, v63, v67
	v_fmamk_f32 v63, v63, 0x3b000000, v218
	v_cmp_gt_f32_e32 vcc, s30, v63
	v_mul_f32_e32 v67, 0x4f800000, v63
	s_nop 0
	v_cndmask_b32_e32 v63, v63, v67, vcc
	v_sqrt_f32_e32 v67, v63
	s_nop 0
	v_add_u32_e32 v69, -1, v67
	v_fma_f32 v70, -v69, v67, v63
	v_cmp_ge_f32_e64 s[42:43], 0, v70
	v_add_u32_e32 v70, 1, v67
	s_nop 0
	v_cndmask_b32_e64 v69, v67, v69, s[42:43]
	v_fma_f32 v67, -v70, v67, v63
	v_cmp_lt_f32_e64 s[42:43], 0, v67
	s_nop 1
	v_cndmask_b32_e64 v67, v69, v70, s[42:43]
	v_mul_f32_e32 v69, 0x37800000, v67
	v_cndmask_b32_e32 v67, v67, v69, vcc
	v_cmp_class_f32_e32 vcc, v63, v215
	s_nop 1
	v_cndmask_b32_e32 v63, v67, v63, vcc
	v_div_scale_f32 v67, s[0:1], v63, v63, 1.0
	v_rcp_f32_e32 v69, v67
	s_nop 0
	v_fma_f32 v70, -v67, v69, 1.0
	v_fmac_f32_e32 v69, v70, v69
	v_div_scale_f32 v70, vcc, 1.0, v63, 1.0
	v_mul_f32_e32 v71, v70, v69
	v_fma_f32 v74, -v67, v71, v70
	v_fmac_f32_e32 v71, v74, v69
	v_fma_f32 v67, -v67, v71, v70
	v_div_fmas_f32 v67, v67, v69, v71
	v_div_fixup_f32 v70, v67, v63, 1.0
	v_pk_mul_f32 v[36:37], v[70:71], v[36:37] op_sel_hi:[0,1]
	v_pk_mul_f32 v[38:39], v[70:71], v[38:39] op_sel_hi:[0,1]
	v_pk_mul_f32 v[42:43], v[70:71], v[42:43] op_sel_hi:[0,1]
	v_pk_mul_f32 v[36:37], v[44:45], v[36:37]
	v_pk_mul_f32 v[72:73], v[70:71], v[72:73] op_sel_hi:[0,1]
	v_pk_mul_f32 v[38:39], v[46:47], v[38:39]
	v_pk_mul_f32 v[42:43], v[14:15], v[42:43]
	v_pk_mul_f32 v[72:73], v[10:11], v[72:73]
	v_bfe_u32 v63, v39, 16, 1
	v_bfe_u32 v67, v38, 16, 1
	v_bfe_u32 v69, v37, 16, 1
	v_bfe_u32 v70, v36, 16, 1
	v_add3_u32 v36, v36, v70, s63
	v_add3_u32 v37, v37, v69, s63
	v_add3_u32 v38, v38, v67, s63
	v_add3_u32 v39, v39, v63, s63
	v_bfe_u32 v63, v42, 16, 1
	v_bfe_u32 v67, v43, 16, 1
	v_bfe_u32 v69, v72, 16, 1
	v_bfe_u32 v70, v73, 16, 1
	v_add3_u32 v70, v73, v70, s63
	v_add3_u32 v69, v72, v69, s63
	v_add3_u32 v43, v43, v67, s63
	v_add3_u32 v42, v42, v63, s63
	v_lshrrev_b32_e32 v42, 16, v42
	v_lshrrev_b32_e32 v43, 16, v43
	v_lshrrev_b32_e32 v63, 16, v69
	v_lshrrev_b32_e32 v67, 16, v70
	v_and_or_b32 v39, v39, s60, v67
	v_and_or_b32 v38, v38, s60, v63
	v_and_or_b32 v37, v37, s60, v43
	v_and_or_b32 v36, v36, s60, v42
	global_store_dwordx4 v[64:65], v[36:39], off offset:128 sc0 sc1
	s_waitcnt vmcnt(16)
	v_lshlrev_b32_e32 v43, 16, v35
	v_lshlrev_b32_e32 v42, 16, v34
	v_lshlrev_b32_e32 v37, 16, v33
	v_lshlrev_b32_e32 v36, 16, v32
	v_pk_mul_f32 v[38:39], v[36:37], v[36:37]
	v_and_b32_e32 v33, 0xffff0000, v33
	v_and_b32_e32 v32, 0xffff0000, v32
	v_pk_fma_f32 v[38:39], v[32:33], v[32:33], v[38:39]
	v_pk_mul_f32 v[70:71], v[42:43], v[42:43]
	v_and_b32_e32 v35, 0xffff0000, v35
	v_and_b32_e32 v34, 0xffff0000, v34
	v_pk_fma_f32 v[70:71], v[34:35], v[34:35], v[70:71]
	v_add_f32_e32 v38, v38, v39
	v_add_f32_e32 v38, v70, v38
	v_add_f32_e32 v38, v71, v38
	s_nop 1
	v_add_f32_dpp v38, v38, v38 quad_perm:[1,0,3,2] row_mask:0xf bank_mask:0xf bound_ctrl:1
	s_nop 1
	v_add_f32_dpp v38, v38, v38 quad_perm:[2,3,0,1] row_mask:0xf bank_mask:0xf bound_ctrl:1
	s_nop 1
	v_add_f32_dpp v38, v38, v38 row_half_mirror row_mask:0xf bank_mask:0xf bound_ctrl:1
	s_nop 1
	v_add_f32_dpp v38, v38, v38 row_mirror row_mask:0xf bank_mask:0xf bound_ctrl:1
	v_mov_b32_e32 v39, v38
	s_nop 1
	v_permlane16_swap_b32_e32 v38, v39
	v_add_f32_e32 v38, v38, v39
	v_mov_b32_e32 v39, v38
	s_nop 1
	v_permlane32_swap_b32_e32 v38, v39
	v_add_f32_e32 v38, v38, v39
	v_fmamk_f32 v38, v38, 0x3b000000, v218
	v_cmp_gt_f32_e32 vcc, s30, v38
	v_mul_f32_e32 v39, 0x4f800000, v38
	s_nop 0
	v_cndmask_b32_e32 v38, v38, v39, vcc
	v_sqrt_f32_e32 v39, v38
	s_nop 0
	v_add_u32_e32 v63, -1, v39
	v_fma_f32 v67, -v63, v39, v38
	v_cmp_ge_f32_e64 s[42:43], 0, v67
	v_add_u32_e32 v67, 1, v39
	s_nop 0
	v_cndmask_b32_e64 v63, v39, v63, s[42:43]
	v_fma_f32 v39, -v67, v39, v38
	v_cmp_lt_f32_e64 s[42:43], 0, v39
	s_nop 1
	v_cndmask_b32_e64 v39, v63, v67, s[42:43]
	v_mul_f32_e32 v63, 0x37800000, v39
	v_cndmask_b32_e32 v39, v39, v63, vcc
	v_cmp_class_f32_e32 vcc, v38, v215
	s_nop 1
	v_cndmask_b32_e32 v38, v39, v38, vcc
	v_div_scale_f32 v39, s[0:1], v38, v38, 1.0
	v_rcp_f32_e32 v63, v39
	s_nop 0
	v_fma_f32 v67, -v39, v63, 1.0
	v_fmac_f32_e32 v63, v67, v63
	v_div_scale_f32 v67, vcc, 1.0, v38, 1.0
	v_mul_f32_e32 v69, v67, v63
	v_fma_f32 v70, -v39, v69, v67
	v_fmac_f32_e32 v69, v70, v63
	v_fma_f32 v39, -v39, v69, v67
	v_div_fmas_f32 v39, v39, v63, v69
	v_div_fixup_f32 v38, v39, v38, 1.0
	v_pk_mul_f32 v[34:35], v[38:39], v[34:35] op_sel_hi:[0,1]
	v_pk_mul_f32 v[36:37], v[38:39], v[36:37] op_sel_hi:[0,1]
	v_pk_mul_f32 v[32:33], v[38:39], v[32:33] op_sel_hi:[0,1]
	v_pk_mul_f32 v[34:35], v[8:9], v[34:35]
	v_pk_mul_f32 v[36:37], v[6:7], v[36:37]
	v_pk_mul_f32 v[32:33], v[12:13], v[32:33]
	v_pk_mul_f32 v[42:43], v[38:39], v[42:43] op_sel_hi:[0,1]
	v_bfe_u32 v38, v35, 16, 1
	v_pk_mul_f32 v[42:43], v[2:3], v[42:43]
	v_bfe_u32 v39, v34, 16, 1
	v_bfe_u32 v63, v33, 16, 1
	v_bfe_u32 v67, v32, 16, 1
	v_add3_u32 v35, v35, v38, s63
	v_bfe_u32 v38, v36, 16, 1
	v_add3_u32 v32, v32, v67, s63
	v_add3_u32 v33, v33, v63, s63
	v_add3_u32 v34, v34, v39, s63
	v_bfe_u32 v39, v37, 16, 1
	v_bfe_u32 v63, v42, 16, 1
	v_bfe_u32 v67, v43, 16, 1
	v_add3_u32 v36, v36, v38, s63
	v_add3_u32 v43, v43, v67, s63
	v_add3_u32 v42, v42, v63, s63
	v_add3_u32 v37, v37, v39, s63
	v_lshrrev_b32_e32 v36, 16, v36
	v_lshrrev_b32_e32 v37, 16, v37
	v_lshrrev_b32_e32 v38, 16, v42
	v_lshrrev_b32_e32 v39, 16, v43
	v_and_or_b32 v32, v32, s60, v36
	v_add_co_u32_e32 v36, vcc, 0x1e000000, v58
	v_and_or_b32 v35, v35, s60, v39
	v_and_or_b32 v34, v34, s60, v38
	v_and_or_b32 v33, v33, s60, v37
	v_addc_co_u32_e32 v37, vcc, 0, v59, vcc
	global_store_dwordx4 v[36:37], v[32:35], off offset:128 sc0 sc1
	s_and_saveexec_b64 s[6:7], s[40:41]
	s_cbranch_execz .LBB0_216
; __device__ __forceinline__ float bf2f(unsigned h) { return __uint_as_float(h << 16); }
; __device__ __forceinline__ unsigned pk2(float lo, float hi) { return f2bf(lo) | (f2bf(hi) << 16); }
; __device__ __forceinline__ void mla_mid(const bf16_t* __restrict__ wino, const float* __restrict__ gq, const float* __restrict__ gkv, const float* __restrict__ cs_tab, const float* __restrict__ sn_tab, ...
;     ...
;             for (int part = 0; part < 2; ++part) {
;                 float f[8]; float s = 0.f;
; #pragma unroll
;                 for (int e = 0; e < 4; ++e) { f[2 * e] = bf2f(v[rr][part][e] & 0xffffu); f[2 * e + 1] = bf2f(v[rr][part][e] >> 16); s += f[2 * e] * f[2 * e] + f[2 * e + 1] * f[2 * e + 1]; }
;                 const float rstd = 1.0f / sqrtf(wave_sum(s) * (1.f / LORA) + RMS_EPS);
;                 const f32x4 g0 = part == 0 ? gq0 : gk0, g1 = part == 0 ? gq1 : gk1;
;                 v4u o; o.x = pk2(f[0] * rstd * g0[0], f[1] * rstd * g0[1]); o.y = pk2(f[2] * rstd * g0[2], f[3] * rstd * g0[3]);
;                 o.z = pk2(f[4] * rstd * g1[0], f[5] * rstd * g1[1]); o.w = pk2(f[6] * rstd * g1[2], f[7] * rstd * g1[3]);
;                 *(v4u*)((part == 0 ? cqn : ckvn) + ((size_t)(lane >> 3) * M_TOK + m) * 64 + (lane & 7) * 8) = o;
;             }
;             if (lane < 32) { const float x1 = bf2f(w[rr] & 0xffffu), x2 = bf2f(w[rr] >> 16);
;                 *(unsigned*)(kr + (size_t)m * 64 + 2 * lane) = pk2(x1 * cc[rr] - x2 * ss[rr], x1 * ss[rr] + x2 * cc[rr]); }
	s_waitcnt vmcnt(16)
	v_lshlrev_b32_e32 v33, 16, v61
	v_and_b32_e32 v32, 0xffff0000, v61
	s_waitcnt vmcnt(14)
	v_pk_mul_f32 v[34:35], v[68:69], v[32:33] op_sel:[0,1] op_sel_hi:[0,0]
	v_pk_fma_f32 v[36:37], v[66:67], v[32:33], v[34:35]
	v_pk_fma_f32 v[32:33], v[66:67], v[32:33], v[34:35] op_sel_hi:[0,1,1] neg_lo:[0,0,1] neg_hi:[0,0,1]
	v_and_b32_sdwa v32, v33, v217 dst_sel:DWORD dst_unused:UNUSED_PAD src0_sel:WORD_1 src1_sel:DWORD
	v_and_b32_sdwa v34, v36, v217 dst_sel:DWORD dst_unused:UNUSED_PAD src0_sel:WORD_1 src1_sel:DWORD
	v_add3_u32 v32, v33, v32, s63
	v_add3_u32 v34, v36, v34, s63
	v_lshrrev_b32_e32 v32, 16, v32
	v_and_or_b32 v32, v34, s60, v32
	global_store_dword v[40:41], v32, off offset:-128
.LBB0_216:
	s_or_b64 exec, exec, s[6:7]
	s_waitcnt vmcnt(13)
	v_lshlrev_b32_e32 v33, 16, v29
	v_lshlrev_b32_e32 v32, 16, v28
	v_pk_mul_f32 v[34:35], v[32:33], v[32:33]
	v_and_b32_e32 v29, 0xffff0000, v29
	v_and_b32_e32 v28, 0xffff0000, v28
	v_lshlrev_b32_e32 v37, 16, v31
	v_lshlrev_b32_e32 v36, 16, v30
	v_pk_fma_f32 v[34:35], v[28:29], v[28:29], v[34:35]
	v_pk_mul_f32 v[38:39], v[36:37], v[36:37]
	v_and_b32_e32 v31, 0xffff0000, v31
	v_and_b32_e32 v30, 0xffff0000, v30
	v_pk_fma_f32 v[38:39], v[30:31], v[30:31], v[38:39]
	v_add_f32_e32 v34, v34, v35
	v_add_f32_e32 v34, v38, v34
	v_add_f32_e32 v34, v39, v34
	s_nop 1
	v_add_f32_dpp v34, v34, v34 quad_perm:[1,0,3,2] row_mask:0xf bank_mask:0xf bound_ctrl:1
	s_nop 1
	v_add_f32_dpp v34, v34, v34 quad_perm:[2,3,0,1] row_mask:0xf bank_mask:0xf bound_ctrl:1
	s_nop 1
	v_add_f32_dpp v34, v34, v34 row_half_mirror row_mask:0xf bank_mask:0xf bound_ctrl:1
	s_nop 1
	v_add_f32_dpp v34, v34, v34 row_mirror row_mask:0xf bank_mask:0xf bound_ctrl:1
	v_mov_b32_e32 v35, v34
	s_nop 1
	v_permlane16_swap_b32_e32 v34, v35
	v_add_f32_e32 v34, v34, v35
	v_mov_b32_e32 v35, v34
	s_nop 1
	v_permlane32_swap_b32_e32 v34, v35
	v_add_f32_e32 v34, v34, v35
	v_fmamk_f32 v34, v34, 0x3b000000, v218
	v_cmp_gt_f32_e32 vcc, s30, v34
	v_mul_f32_e32 v35, 0x4f800000, v34
	s_nop 0
	v_cndmask_b32_e32 v34, v34, v35, vcc
	v_sqrt_f32_e32 v35, v34
	s_nop 0
	v_add_u32_e32 v38, -1, v35
	v_fma_f32 v39, -v38, v35, v34
	v_cmp_ge_f32_e64 s[42:43], 0, v39
	v_add_u32_e32 v39, 1, v35
	s_nop 0
	v_cndmask_b32_e64 v38, v35, v38, s[42:43]
	v_fma_f32 v35, -v39, v35, v34
	v_cmp_lt_f32_e64 s[42:43], 0, v35
	s_nop 1
	v_cndmask_b32_e64 v35, v38, v39, s[42:43]
	v_mul_f32_e32 v38, 0x37800000, v35
	v_cndmask_b32_e32 v35, v35, v38, vcc
	v_cmp_class_f32_e32 vcc, v34, v215
	s_nop 1
	v_cndmask_b32_e32 v34, v35, v34, vcc
	v_div_scale_f32 v35, s[0:1], v34, v34, 1.0
	v_rcp_f32_e32 v38, v35
	s_nop 0
	v_fma_f32 v39, -v35, v38, 1.0
	v_fmac_f32_e32 v38, v39, v38
	v_div_scale_f32 v39, vcc, 1.0, v34, 1.0
	v_mul_f32_e32 v42, v39, v38
	v_fma_f32 v43, -v35, v42, v39
	v_fmac_f32_e32 v42, v43, v38
	v_fma_f32 v35, -v35, v42, v39
	v_div_fmas_f32 v35, v35, v38, v42
	v_div_fixup_f32 v34, v35, v34, 1.0
	v_pk_mul_f32 v[28:29], v[34:35], v[28:29] op_sel_hi:[0,1]
	v_pk_mul_f32 v[30:31], v[34:35], v[30:31] op_sel_hi:[0,1]
	v_pk_mul_f32 v[32:33], v[34:35], v[32:33] op_sel_hi:[0,1]
	v_pk_mul_f32 v[28:29], v[44:45], v[28:29]
	v_pk_mul_f32 v[36:37], v[34:35], v[36:37] op_sel_hi:[0,1]
	v_pk_mul_f32 v[30:31], v[46:47], v[30:31]
	v_pk_mul_f32 v[32:33], v[14:15], v[32:33]
	v_pk_mul_f32 v[36:37], v[10:11], v[36:37]
	v_bfe_u32 v34, v31, 16, 1
	v_bfe_u32 v35, v30, 16, 1
	v_bfe_u32 v38, v29, 16, 1
	v_bfe_u32 v39, v28, 16, 1
	v_add3_u32 v28, v28, v39, s63
	v_add3_u32 v29, v29, v38, s63
	v_add3_u32 v30, v30, v35, s63
	v_add3_u32 v31, v31, v34, s63
	v_bfe_u32 v34, v32, 16, 1
	v_bfe_u32 v35, v33, 16, 1
	v_bfe_u32 v38, v36, 16, 1
	v_bfe_u32 v39, v37, 16, 1
	v_add3_u32 v37, v37, v39, s63
	v_add3_u32 v36, v36, v38, s63
	v_add3_u32 v33, v33, v35, s63
	v_add3_u32 v32, v32, v34, s63
	v_lshrrev_b32_e32 v32, 16, v32
	v_lshrrev_b32_e32 v33, 16, v33
	v_lshrrev_b32_e32 v34, 16, v36
	v_lshrrev_b32_e32 v35, 16, v37
	v_and_or_b32 v31, v31, s60, v35
	v_and_or_b32 v30, v30, s60, v34
	v_and_or_b32 v29, v29, s60, v33
	v_and_or_b32 v28, v28, s60, v32
	global_store_dwordx4 v[64:65], v[28:31], off offset:256 sc0 sc1
	s_waitcnt vmcnt(13)
	v_lshlrev_b32_e32 v33, 16, v27
	v_lshlrev_b32_e32 v32, 16, v26
	v_lshlrev_b32_e32 v29, 16, v25
	v_lshlrev_b32_e32 v28, 16, v24
	v_pk_mul_f32 v[30:31], v[28:29], v[28:29]
	v_and_b32_e32 v25, 0xffff0000, v25
	v_and_b32_e32 v24, 0xffff0000, v24
	v_pk_fma_f32 v[30:31], v[24:25], v[24:25], v[30:31]
	v_pk_mul_f32 v[34:35], v[32:33], v[32:33]
	v_and_b32_e32 v27, 0xffff0000, v27
	v_and_b32_e32 v26, 0xffff0000, v26
	v_pk_fma_f32 v[34:35], v[26:27], v[26:27], v[34:35]
	v_add_f32_e32 v30, v30, v31
	v_add_f32_e32 v30, v34, v30
	v_add_f32_e32 v30, v35, v30
	s_nop 1
	v_add_f32_dpp v30, v30, v30 quad_perm:[1,0,3,2] row_mask:0xf bank_mask:0xf bound_ctrl:1
	s_nop 1
	v_add_f32_dpp v30, v30, v30 quad_perm:[2,3,0,1] row_mask:0xf bank_mask:0xf bound_ctrl:1
	s_nop 1
	v_add_f32_dpp v30, v30, v30 row_half_mirror row_mask:0xf bank_mask:0xf bound_ctrl:1
	s_nop 1
	v_add_f32_dpp v30, v30, v30 row_mirror row_mask:0xf bank_mask:0xf bound_ctrl:1
	v_mov_b32_e32 v31, v30
	s_nop 1
	v_permlane16_swap_b32_e32 v30, v31
	v_add_f32_e32 v30, v30, v31
	v_mov_b32_e32 v31, v30
	s_nop 1
	v_permlane32_swap_b32_e32 v30, v31
	v_add_f32_e32 v30, v30, v31
	v_fmamk_f32 v30, v30, 0x3b000000, v218
	v_cmp_gt_f32_e32 vcc, s30, v30
	v_mul_f32_e32 v31, 0x4f800000, v30
	s_nop 0
	v_cndmask_b32_e32 v30, v30, v31, vcc
	v_sqrt_f32_e32 v31, v30
	s_nop 0
	v_add_u32_e32 v34, -1, v31
	v_fma_f32 v35, -v34, v31, v30
	v_cmp_ge_f32_e64 s[42:43], 0, v35
	v_add_u32_e32 v35, 1, v31
	s_nop 0
	v_cndmask_b32_e64 v34, v31, v34, s[42:43]
	v_fma_f32 v31, -v35, v31, v30
; __device__ __forceinline__ float bf2f(unsigned h) { return __uint_as_float(h << 16); }
; __device__ __forceinline__ unsigned pk2(float lo, float hi) { return f2bf(lo) | (f2bf(hi) << 16); }
; __device__ __forceinline__ void mla_mid(const bf16_t* __restrict__ wino, const float* __restrict__ gq, const float* __restrict__ gkv, const float* __restrict__ cs_tab, const float* __restrict__ sn_tab, ...
;     ...
;             for (int part = 0; part < 2; ++part) {
;                 float f[8]; float s = 0.f;
; #pragma unroll
;                 for (int e = 0; e < 4; ++e) { f[2 * e] = bf2f(v[rr][part][e] & 0xffffu); f[2 * e + 1] = bf2f(v[rr][part][e] >> 16); s += f[2 * e] * f[2 * e] + f[2 * e + 1] * f[2 * e + 1]; }
;                 const float rstd = 1.0f / sqrtf(wave_sum(s) * (1.f / LORA) + RMS_EPS);
;                 const f32x4 g0 = part == 0 ? gq0 : gk0, g1 = part == 0 ? gq1 : gk1;
;                 v4u o; o.x = pk2(f[0] * rstd * g0[0], f[1] * rstd * g0[1]); o.y = pk2(f[2] * rstd * g0[2], f[3] * rstd * g0[3]);
;                 o.z = pk2(f[4] * rstd * g1[0], f[5] * rstd * g1[1]); o.w = pk2(f[6] * rstd * g1[2], f[7] * rstd * g1[3]);
;                 *(v4u*)((part == 0 ? cqn : ckvn) + ((size_t)(lane >> 3) * M_TOK + m) * 64 + (lane & 7) * 8) = o;
;             }
;             if (lane < 32) { const float x1 = bf2f(w[rr] & 0xffffu), x2 = bf2f(w[rr] >> 16);
;                 *(unsigned*)(kr + (size_t)m * 64 + 2 * lane) = pk2(x1 * cc[rr] - x2 * ss[rr], x1 * ss[rr] + x2 * cc[rr]); }
	v_cmp_lt_f32_e64 s[42:43], 0, v31
	s_nop 1
	v_cndmask_b32_e64 v31, v34, v35, s[42:43]
	v_mul_f32_e32 v34, 0x37800000, v31
	v_cndmask_b32_e32 v31, v31, v34, vcc
	v_cmp_class_f32_e32 vcc, v30, v215
	s_nop 1
	v_cndmask_b32_e32 v30, v31, v30, vcc
	v_div_scale_f32 v31, s[0:1], v30, v30, 1.0
	v_rcp_f32_e32 v34, v31
	s_nop 0
	v_fma_f32 v35, -v31, v34, 1.0
	v_fmac_f32_e32 v34, v35, v34
	v_div_scale_f32 v35, vcc, 1.0, v30, 1.0
	v_mul_f32_e32 v36, v35, v34
	v_fma_f32 v37, -v31, v36, v35
	v_fmac_f32_e32 v36, v37, v34
	v_fma_f32 v31, -v31, v36, v35
	v_div_fmas_f32 v31, v31, v34, v36
	v_div_fixup_f32 v30, v31, v30, 1.0
	v_pk_mul_f32 v[26:27], v[30:31], v[26:27] op_sel_hi:[0,1]
	v_pk_mul_f32 v[28:29], v[30:31], v[28:29] op_sel_hi:[0,1]
	v_pk_mul_f32 v[24:25], v[30:31], v[24:25] op_sel_hi:[0,1]
	v_pk_mul_f32 v[26:27], v[8:9], v[26:27]
	v_pk_mul_f32 v[28:29], v[6:7], v[28:29]
	v_pk_mul_f32 v[24:25], v[12:13], v[24:25]
	v_pk_mul_f32 v[32:33], v[30:31], v[32:33] op_sel_hi:[0,1]
	v_bfe_u32 v30, v27, 16, 1
	v_pk_mul_f32 v[32:33], v[2:3], v[32:33]
	v_bfe_u32 v31, v26, 16, 1
	v_bfe_u32 v34, v25, 16, 1
	v_bfe_u32 v35, v24, 16, 1
	v_add3_u32 v27, v27, v30, s63
	v_bfe_u32 v30, v28, 16, 1
	v_add3_u32 v24, v24, v35, s63
	v_add3_u32 v25, v25, v34, s63
	v_add3_u32 v26, v26, v31, s63
	v_bfe_u32 v31, v29, 16, 1
	v_bfe_u32 v34, v32, 16, 1
	v_bfe_u32 v35, v33, 16, 1
	v_add3_u32 v28, v28, v30, s63
	v_add3_u32 v33, v33, v35, s63
	v_add3_u32 v32, v32, v34, s63
	v_add3_u32 v29, v29, v31, s63
	v_lshrrev_b32_e32 v28, 16, v28
	v_lshrrev_b32_e32 v29, 16, v29
	v_lshrrev_b32_e32 v30, 16, v32
	v_lshrrev_b32_e32 v31, 16, v33
	v_and_or_b32 v24, v24, s60, v28
	v_add_co_u32_e32 v28, vcc, 0x1e000000, v58
	v_and_or_b32 v27, v27, s60, v31
	v_and_or_b32 v26, v26, s60, v30
	v_and_or_b32 v25, v25, s60, v29
	v_addc_co_u32_e32 v29, vcc, 0, v59, vcc
	global_store_dwordx4 v[28:29], v[24:27], off offset:256 sc0 sc1
	s_and_saveexec_b64 s[6:7], s[40:41]
	s_cbranch_execz .LBB0_218
	s_waitcnt vmcnt(13)
	v_lshlrev_b32_e32 v25, 16, v57
	v_and_b32_e32 v24, 0xffff0000, v57
	s_waitcnt vmcnt(11)
	v_pk_mul_f32 v[26:27], v[62:63], v[24:25] op_sel:[0,1] op_sel_hi:[0,0]
	v_pk_fma_f32 v[28:29], v[60:61], v[24:25], v[26:27]
	v_pk_fma_f32 v[24:25], v[60:61], v[24:25], v[26:27] op_sel_hi:[0,1,1] neg_lo:[0,0,1] neg_hi:[0,0,1]
	v_and_b32_sdwa v24, v25, v217 dst_sel:DWORD dst_unused:UNUSED_PAD src0_sel:WORD_1 src1_sel:DWORD
	v_and_b32_sdwa v26, v28, v217 dst_sel:DWORD dst_unused:UNUSED_PAD src0_sel:WORD_1 src1_sel:DWORD
	v_add3_u32 v24, v25, v24, s63
	v_add3_u32 v26, v28, v26, s63
	v_lshrrev_b32_e32 v24, 16, v24
	v_and_or_b32 v24, v26, s60, v24
	global_store_dword v[40:41], v24, off
.LBB0_218:
	s_or_b64 exec, exec, s[6:7]
	s_waitcnt vmcnt(10)
	v_lshlrev_b32_e32 v25, 16, v21
	v_lshlrev_b32_e32 v24, 16, v20
	v_pk_mul_f32 v[26:27], v[24:25], v[24:25]
	v_and_b32_e32 v21, 0xffff0000, v21
	v_and_b32_e32 v20, 0xffff0000, v20
	v_lshlrev_b32_e32 v29, 16, v23
	v_lshlrev_b32_e32 v28, 16, v22
	v_pk_fma_f32 v[26:27], v[20:21], v[20:21], v[26:27]
	v_pk_mul_f32 v[30:31], v[28:29], v[28:29]
	v_and_b32_e32 v23, 0xffff0000, v23
	v_and_b32_e32 v22, 0xffff0000, v22
	v_pk_fma_f32 v[30:31], v[22:23], v[22:23], v[30:31]
	v_add_f32_e32 v26, v26, v27
	v_add_f32_e32 v26, v30, v26
	v_add_f32_e32 v26, v31, v26
	s_nop 1
	v_add_f32_dpp v26, v26, v26 quad_perm:[1,0,3,2] row_mask:0xf bank_mask:0xf bound_ctrl:1
	s_nop 1
	v_add_f32_dpp v26, v26, v26 quad_perm:[2,3,0,1] row_mask:0xf bank_mask:0xf bound_ctrl:1
	s_nop 1
	v_add_f32_dpp v26, v26, v26 row_half_mirror row_mask:0xf bank_mask:0xf bound_ctrl:1
	s_nop 1
	v_add_f32_dpp v26, v26, v26 row_mirror row_mask:0xf bank_mask:0xf bound_ctrl:1
	v_mov_b32_e32 v27, v26
	s_nop 1
	v_permlane16_swap_b32_e32 v26, v27
	v_add_f32_e32 v26, v26, v27
	v_mov_b32_e32 v27, v26
	s_nop 1
	v_permlane32_swap_b32_e32 v26, v27
	v_add_f32_e32 v26, v26, v27
	v_fmamk_f32 v26, v26, 0x3b000000, v218
	v_cmp_gt_f32_e32 vcc, s30, v26
	v_mul_f32_e32 v27, 0x4f800000, v26
	s_nop 0
	v_cndmask_b32_e32 v26, v26, v27, vcc
	v_sqrt_f32_e32 v27, v26
	s_nop 0
	v_add_u32_e32 v30, -1, v27
	v_fma_f32 v31, -v30, v27, v26
	v_cmp_ge_f32_e64 s[42:43], 0, v31
	v_add_u32_e32 v31, 1, v27
	s_nop 0
	v_cndmask_b32_e64 v30, v27, v30, s[42:43]
	v_fma_f32 v27, -v31, v27, v26
	v_cmp_lt_f32_e64 s[42:43], 0, v27
	s_nop 1
	v_cndmask_b32_e64 v27, v30, v31, s[42:43]
	v_mul_f32_e32 v30, 0x37800000, v27
	v_cndmask_b32_e32 v27, v27, v30, vcc
	v_cmp_class_f32_e32 vcc, v26, v215
	s_nop 1
	v_cndmask_b32_e32 v26, v27, v26, vcc
	v_div_scale_f32 v27, s[0:1], v26, v26, 1.0
	v_rcp_f32_e32 v30, v27
	s_nop 0
	v_fma_f32 v31, -v27, v30, 1.0
	v_fmac_f32_e32 v30, v31, v30
	v_div_scale_f32 v31, vcc, 1.0, v26, 1.0
	v_mul_f32_e32 v32, v31, v30
	v_fma_f32 v33, -v27, v32, v31
	v_fmac_f32_e32 v32, v33, v30
	v_fma_f32 v27, -v27, v32, v31
	v_div_fmas_f32 v27, v27, v30, v32
	v_div_fixup_f32 v26, v27, v26, 1.0
	v_pk_mul_f32 v[20:21], v[26:27], v[20:21] op_sel_hi:[0,1]
	v_pk_mul_f32 v[22:23], v[26:27], v[22:23] op_sel_hi:[0,1]
	v_pk_mul_f32 v[24:25], v[26:27], v[24:25] op_sel_hi:[0,1]
	v_pk_mul_f32 v[20:21], v[44:45], v[20:21]
	v_pk_mul_f32 v[28:29], v[26:27], v[28:29] op_sel_hi:[0,1]
	v_pk_mul_f32 v[22:23], v[46:47], v[22:23]
	v_pk_mul_f32 v[24:25], v[14:15], v[24:25]
	v_pk_mul_f32 v[28:29], v[10:11], v[28:29]
	v_bfe_u32 v26, v23, 16, 1
	v_bfe_u32 v27, v22, 16, 1
	v_bfe_u32 v30, v21, 16, 1
	v_bfe_u32 v31, v20, 16, 1
	v_add3_u32 v20, v20, v31, s63
	v_add3_u32 v21, v21, v30, s63
	v_add3_u32 v22, v22, v27, s63
	v_add3_u32 v23, v23, v26, s63
	v_bfe_u32 v26, v24, 16, 1
	v_bfe_u32 v27, v25, 16, 1
	v_bfe_u32 v30, v28, 16, 1
	v_bfe_u32 v31, v29, 16, 1
	v_add3_u32 v29, v29, v31, s63
	v_add3_u32 v28, v28, v30, s63
	v_add3_u32 v25, v25, v27, s63
	v_add3_u32 v24, v24, v26, s63
	v_lshrrev_b32_e32 v24, 16, v24
	v_lshrrev_b32_e32 v25, 16, v25
	v_lshrrev_b32_e32 v26, 16, v28
	v_lshrrev_b32_e32 v27, 16, v29
	v_and_or_b32 v23, v23, s60, v27
	v_and_or_b32 v22, v22, s60, v26
	v_and_or_b32 v21, v21, s60, v25
	v_and_or_b32 v20, v20, s60, v24
	global_store_dwordx4 v[64:65], v[20:23], off offset:384 sc0 sc1
	s_waitcnt vmcnt(10)
; __device__ __forceinline__ float bf2f(unsigned h) { return __uint_as_float(h << 16); }
; __device__ __forceinline__ unsigned pk2(float lo, float hi) { return f2bf(lo) | (f2bf(hi) << 16); }
; __device__ __forceinline__ void mla_mid(const bf16_t* __restrict__ wino, const float* __restrict__ gq, const float* __restrict__ gkv, const float* __restrict__ cs_tab, const float* __restrict__ sn_tab, ...
;     ...
;             for (int part = 0; part < 2; ++part) {
;                 float f[8]; float s = 0.f;
; #pragma unroll
;                 for (int e = 0; e < 4; ++e) { f[2 * e] = bf2f(v[rr][part][e] & 0xffffu); f[2 * e + 1] = bf2f(v[rr][part][e] >> 16); s += f[2 * e] * f[2 * e] + f[2 * e + 1] * f[2 * e + 1]; }
;                 const float rstd = 1.0f / sqrtf(wave_sum(s) * (1.f / LORA) + RMS_EPS);
;                 const f32x4 g0 = part == 0 ? gq0 : gk0, g1 = part == 0 ? gq1 : gk1;
;                 v4u o; o.x = pk2(f[0] * rstd * g0[0], f[1] * rstd * g0[1]); o.y = pk2(f[2] * rstd * g0[2], f[3] * rstd * g0[3]);
;                 o.z = pk2(f[4] * rstd * g1[0], f[5] * rstd * g1[1]); o.w = pk2(f[6] * rstd * g1[2], f[7] * rstd * g1[3]);
;                 *(v4u*)((part == 0 ? cqn : ckvn) + ((size_t)(lane >> 3) * M_TOK + m) * 64 + (lane & 7) * 8) = o;
;             }
;             if (lane < 32) { const float x1 = bf2f(w[rr] & 0xffffu), x2 = bf2f(w[rr] >> 16);
;                 *(unsigned*)(kr + (size_t)m * 64 + 2 * lane) = pk2(x1 * cc[rr] - x2 * ss[rr], x1 * ss[rr] + x2 * cc[rr]); }
	v_lshlrev_b32_e32 v25, 16, v19
	v_lshlrev_b32_e32 v24, 16, v18
	v_lshlrev_b32_e32 v21, 16, v17
	v_lshlrev_b32_e32 v20, 16, v16
	v_pk_mul_f32 v[22:23], v[20:21], v[20:21]
	v_and_b32_e32 v17, 0xffff0000, v17
	v_and_b32_e32 v16, 0xffff0000, v16
	v_pk_fma_f32 v[22:23], v[16:17], v[16:17], v[22:23]
	v_pk_mul_f32 v[26:27], v[24:25], v[24:25]
	v_and_b32_e32 v19, 0xffff0000, v19
	v_and_b32_e32 v18, 0xffff0000, v18
	v_pk_fma_f32 v[26:27], v[18:19], v[18:19], v[26:27]
	v_add_f32_e32 v22, v22, v23
	v_add_f32_e32 v22, v26, v22
	v_add_f32_e32 v22, v27, v22
	s_nop 1
	v_add_f32_dpp v22, v22, v22 quad_perm:[1,0,3,2] row_mask:0xf bank_mask:0xf bound_ctrl:1
	s_nop 1
	v_add_f32_dpp v22, v22, v22 quad_perm:[2,3,0,1] row_mask:0xf bank_mask:0xf bound_ctrl:1
	s_nop 1
	v_add_f32_dpp v22, v22, v22 row_half_mirror row_mask:0xf bank_mask:0xf bound_ctrl:1
	s_nop 1
	v_add_f32_dpp v22, v22, v22 row_mirror row_mask:0xf bank_mask:0xf bound_ctrl:1
	v_mov_b32_e32 v23, v22
	s_nop 1
	v_permlane16_swap_b32_e32 v22, v23
	v_add_f32_e32 v22, v22, v23
	v_mov_b32_e32 v23, v22
	s_nop 1
	v_permlane32_swap_b32_e32 v22, v23
	v_add_f32_e32 v22, v22, v23
	v_fmamk_f32 v22, v22, 0x3b000000, v218
	v_cmp_gt_f32_e32 vcc, s30, v22
	v_mul_f32_e32 v23, 0x4f800000, v22
	s_nop 0
	v_cndmask_b32_e32 v22, v22, v23, vcc
	v_sqrt_f32_e32 v23, v22
	s_nop 0
	v_add_u32_e32 v26, -1, v23
	v_fma_f32 v27, -v26, v23, v22
	v_cmp_ge_f32_e64 s[42:43], 0, v27
	v_add_u32_e32 v27, 1, v23
	s_nop 0
	v_cndmask_b32_e64 v26, v23, v26, s[42:43]
	v_fma_f32 v23, -v27, v23, v22
	v_cmp_lt_f32_e64 s[42:43], 0, v23
	s_nop 1
	v_cndmask_b32_e64 v23, v26, v27, s[42:43]
	v_mul_f32_e32 v26, 0x37800000, v23
	v_cndmask_b32_e32 v23, v23, v26, vcc
	v_cmp_class_f32_e32 vcc, v22, v215
	s_nop 1
	v_cndmask_b32_e32 v22, v23, v22, vcc
	v_div_scale_f32 v23, s[0:1], v22, v22, 1.0
	v_rcp_f32_e32 v26, v23
	s_nop 0
	v_fma_f32 v27, -v23, v26, 1.0
	v_fmac_f32_e32 v26, v27, v26
	v_div_scale_f32 v27, vcc, 1.0, v22, 1.0
	v_mul_f32_e32 v28, v27, v26
	v_fma_f32 v29, -v23, v28, v27
	v_fmac_f32_e32 v28, v29, v26
	v_fma_f32 v23, -v23, v28, v27
	v_div_fmas_f32 v23, v23, v26, v28
	v_div_fixup_f32 v22, v23, v22, 1.0
	v_pk_mul_f32 v[18:19], v[22:23], v[18:19] op_sel_hi:[0,1]
	v_pk_mul_f32 v[20:21], v[22:23], v[20:21] op_sel_hi:[0,1]
	v_pk_mul_f32 v[16:17], v[22:23], v[16:17] op_sel_hi:[0,1]
	v_pk_mul_f32 v[18:19], v[8:9], v[18:19]
	v_pk_mul_f32 v[20:21], v[6:7], v[20:21]
	v_pk_mul_f32 v[16:17], v[12:13], v[16:17]
	v_pk_mul_f32 v[24:25], v[22:23], v[24:25] op_sel_hi:[0,1]
	v_bfe_u32 v22, v19, 16, 1
	v_pk_mul_f32 v[24:25], v[2:3], v[24:25]
	v_bfe_u32 v23, v18, 16, 1
	v_bfe_u32 v26, v17, 16, 1
	v_bfe_u32 v27, v16, 16, 1
	v_add3_u32 v19, v19, v22, s63
	v_bfe_u32 v22, v20, 16, 1
	v_add3_u32 v16, v16, v27, s63
	v_add3_u32 v17, v17, v26, s63
	v_add3_u32 v18, v18, v23, s63
	v_bfe_u32 v23, v21, 16, 1
	v_bfe_u32 v26, v24, 16, 1
	v_bfe_u32 v27, v25, 16, 1
	v_add3_u32 v20, v20, v22, s63
	v_add3_u32 v25, v25, v27, s63
	v_add3_u32 v24, v24, v26, s63
	v_add3_u32 v21, v21, v23, s63
	v_lshrrev_b32_e32 v20, 16, v20
	v_lshrrev_b32_e32 v21, 16, v21
	v_lshrrev_b32_e32 v22, 16, v24
	v_lshrrev_b32_e32 v23, 16, v25
	v_and_or_b32 v16, v16, s60, v20
	v_add_co_u32_e32 v20, vcc, 0x1e000000, v58
	v_and_or_b32 v19, v19, s60, v23
	v_and_or_b32 v18, v18, s60, v22
	v_and_or_b32 v17, v17, s60, v21
	v_addc_co_u32_e32 v21, vcc, 0, v59, vcc
	global_store_dwordx4 v[20:21], v[16:19], off offset:384 sc0 sc1
	s_and_saveexec_b64 s[6:7], s[40:41]
	s_cbranch_execz .LBB0_211
	s_waitcnt vmcnt(10)
	v_lshlrev_b32_e32 v17, 16, v55
	v_and_b32_e32 v16, 0xffff0000, v55
	s_waitcnt vmcnt(8)
	v_pk_mul_f32 v[18:19], v[56:57], v[16:17] op_sel:[0,1] op_sel_hi:[0,0]
	v_pk_fma_f32 v[20:21], v[54:55], v[16:17], v[18:19]
	v_pk_fma_f32 v[16:17], v[54:55], v[16:17], v[18:19] op_sel_hi:[0,1,1] neg_lo:[0,0,1] neg_hi:[0,0,1]
	v_and_b32_sdwa v16, v17, v217 dst_sel:DWORD dst_unused:UNUSED_PAD src0_sel:WORD_1 src1_sel:DWORD
	v_and_b32_sdwa v18, v20, v217 dst_sel:DWORD dst_unused:UNUSED_PAD src0_sel:WORD_1 src1_sel:DWORD
	v_add3_u32 v16, v17, v16, s63
	v_add3_u32 v18, v20, v18, s63
	v_lshrrev_b32_e32 v16, 16, v16
	v_and_or_b32 v16, v18, s60, v16
	global_store_dword v[40:41], v16, off offset:128
	s_branch .LBB0_211

; __device__ __forceinline__ float bf2f(unsigned h) { return __uint_as_float(h << 16); }
; template <int MODE> ...
;     for (int m = RPW * gw; m < M_TOK; m += RPW * NGW) {
;         f32x4 xv[RPW][8]; v2u yy[RPW][8];
; #pragma unroll
;         for (int rr = 0; rr < RPW; ++rr) {
;             const float* xr = ((MODE == 0 || xin != nullptr) ? xin : xres) + (size_t)(m + rr) * DM + lane * 4;
; #pragma unroll
;             for (int k = 0; k < 8; ++k) xv[rr][k] = *(const f32x4*)(xr + k * 256);
;             if (MODE >= 1) { const bf16_t* yr = y + (size_t)(m + rr) * 256 + lane * 4;
; #pragma unroll
;                 for (int k = 0; k < 8; ++k) yy[rr][k] = *(const v2u*)(yr + (size_t)k * ((size_t)M_TOK * 256)); }
;         }
;         if (MODE >= 1) {
;             float rstd[RPW];
; #pragma unroll
;             for (int rr = 0; rr < RPW; ++rr) { float s = 0.f;
; #pragma unroll
;                 for (int k = 0; k < 8; ++k)
; #pragma unroll
;                     for (int e = 0; e < 2; ++e) { const float a = bf2f(yy[rr][k][e] & 0xffffu), b = bf2f(yy[rr][k][e] >> 16); s += a * a + b * b; }
;                 rstd[rr] = 1.0f / sqrtf(wave_sum(s) * (1.f / DM) + RMS_EPS); }
.LBB0_225:
	v_lshl_add_u64 v[98:99], s[64:65], 0, v[146:147]
	v_add_co_u32_e32 v66, vcc, 0x1000, v98
	v_lshl_add_u64 v[100:101], v[150:151], 0, s[46:47]
	s_nop 0
	v_addc_co_u32_e32 v67, vcc, 0, v99, vcc
	v_add_co_u32_e32 v114, vcc, 0x8800000, v100
	global_load_dwordx4 v[94:97], v[98:99], off
	global_load_dwordx4 v[90:93], v[98:99], off offset:1024
	global_load_dwordx4 v[86:89], v[98:99], off offset:2048
	global_load_dwordx4 v[82:85], v[98:99], off offset:3072
	v_addc_co_u32_e32 v115, vcc, 0, v101, vcc
	global_load_dwordx4 v[78:81], v[66:67], off
	global_load_dwordx4 v[74:77], v[66:67], off offset:1024
	global_load_dwordx4 v[70:73], v[66:67], off offset:2048
	s_nop 0
	global_load_dwordx4 v[66:69], v[66:67], off offset:3072
	v_add_co_u32_e32 v118, vcc, 0x9000000, v100
	global_load_dwordx2 v[116:117], v[114:115], off
	s_nop 0
	v_addc_co_u32_e32 v119, vcc, 0, v101, vcc
	global_load_dwordx2 v[120:121], v[118:119], off
	v_add_co_u32_e32 v122, vcc, 0x9800000, v100
	s_add_i32 s42, s42, s18
	s_nop 0
	v_addc_co_u32_e32 v123, vcc, 0, v101, vcc
	global_load_dwordx2 v[124:125], v[122:123], off
	v_add_co_u32_e32 v126, vcc, 0xa000000, v100
	v_lshl_add_u64 v[150:151], v[150:151], 0, s[22:23]
	s_nop 0
	v_addc_co_u32_e32 v127, vcc, 0, v101, vcc
	global_load_dwordx2 v[128:129], v[126:127], off
	v_add_co_u32_e32 v152, vcc, 0xa800000, v100
	s_waitcnt vmcnt(3)
	v_lshlrev_b32_e32 v168, 16, v116
	v_addc_co_u32_e32 v153, vcc, 0, v101, vcc
	global_load_dwordx2 v[154:155], v[152:153], off
	v_add_co_u32_e32 v156, vcc, 0xb000000, v100
	v_and_b32_e32 v169, 0xffff0000, v116
	s_nop 0
	v_addc_co_u32_e32 v157, vcc, 0, v101, vcc
	global_load_dwordx2 v[158:159], v[156:157], off
	v_add_co_u32_e32 v160, vcc, 0xb800000, v100
	v_lshlrev_b32_e32 v116, 16, v117
	s_nop 0
	v_addc_co_u32_e32 v161, vcc, 0, v101, vcc
	global_load_dwordx2 v[162:163], v[160:161], off
	v_add_co_u32_e32 v164, vcc, 0xc000000, v100
	v_and_b32_e32 v117, 0xffff0000, v117
	s_nop 0
	v_addc_co_u32_e32 v165, vcc, 0, v101, vcc
	global_load_dwordx2 v[166:167], v[164:165], off
	v_add_co_u32_e32 v100, vcc, s31, v98
	v_mul_f32_e32 v1, v169, v169
	s_nop 0
	v_addc_co_u32_e32 v101, vcc, 0, v99, vcc
	v_add_co_u32_e32 v130, vcc, s33, v98
	v_mul_f32_e32 v170, v117, v117
	s_nop 0
	v_addc_co_u32_e32 v131, vcc, 0, v99, vcc
	global_load_dwordx4 v[110:113], v[130:131], off offset:-4096
	global_load_dwordx4 v[106:109], v[100:101], off offset:1024
	global_load_dwordx4 v[102:105], v[100:101], off offset:2048
	s_nop 0
	global_load_dwordx4 v[98:101], v[100:101], off offset:3072
	s_nop 0
	global_load_dwordx4 v[142:145], v[130:131], off
	global_load_dwordx4 v[138:141], v[130:131], off offset:1024
	global_load_dwordx4 v[134:137], v[130:131], off offset:2048
	s_nop 0
	global_load_dwordx4 v[130:133], v[130:131], off offset:3072
	s_nop 0
	global_load_dwordx2 v[114:115], v[114:115], off offset:512
	s_nop 0
	global_load_dwordx2 v[118:119], v[118:119], off offset:512
	s_nop 0
	global_load_dwordx2 v[122:123], v[122:123], off offset:512
	s_nop 0
	global_load_dwordx2 v[126:127], v[126:127], off offset:512
	s_nop 0
	global_load_dwordx2 v[152:153], v[152:153], off offset:512
	s_nop 0
	global_load_dwordx2 v[156:157], v[156:157], off offset:512
	s_nop 0
	global_load_dwordx2 v[160:161], v[160:161], off offset:512
	s_nop 0
	global_load_dwordx2 v[164:165], v[164:165], off offset:512
	v_fmac_f32_e32 v1, v168, v168
	v_fmac_f32_e32 v170, v116, v116
	s_waitcnt vmcnt(22)
	v_and_b32_e32 v171, 0xffff0000, v120
	v_add_f32_e32 v1, v1, v170
	v_lshlrev_b32_e32 v170, 16, v120
	v_mul_f32_e32 v120, v171, v171
	v_fmac_f32_e32 v120, v170, v170
	v_add_f32_e32 v1, v1, v120
	v_lshlrev_b32_e32 v120, 16, v121
	v_and_b32_e32 v121, 0xffff0000, v121
	v_mul_f32_e32 v172, v121, v121
	v_fmac_f32_e32 v172, v120, v120
	s_waitcnt vmcnt(21)
	v_and_b32_e32 v173, 0xffff0000, v124
	v_add_f32_e32 v1, v172, v1
	v_lshlrev_b32_e32 v172, 16, v124
	v_mul_f32_e32 v124, v173, v173
	v_fmac_f32_e32 v124, v172, v172
	v_and_b32_e32 v175, 0xffff0000, v125
	v_add_f32_e32 v1, v124, v1
	v_lshlrev_b32_e32 v174, 16, v125
	v_mul_f32_e32 v124, v175, v175
	v_fmac_f32_e32 v124, v174, v174
	s_waitcnt vmcnt(20)
	v_and_b32_e32 v177, 0xffff0000, v128
	v_add_f32_e32 v1, v124, v1
	v_lshlrev_b32_e32 v176, 16, v128
	v_mul_f32_e32 v124, v177, v177
	v_fmac_f32_e32 v124, v176, v176
	v_and_b32_e32 v179, 0xffff0000, v129
	v_add_f32_e32 v1, v124, v1
	v_lshlrev_b32_e32 v178, 16, v129
	v_mul_f32_e32 v124, v179, v179
	v_fmac_f32_e32 v124, v178, v178
	v_add_f32_e32 v1, v124, v1
	s_waitcnt vmcnt(19)
	v_and_b32_e32 v181, 0xffff0000, v154
	v_lshlrev_b32_e32 v180, 16, v154
	v_mul_f32_e32 v124, v181, v181
	v_fmac_f32_e32 v124, v180, v180
	v_lshlrev_b32_e32 v154, 16, v155
	v_and_b32_e32 v155, 0xffff0000, v155
	v_add_f32_e32 v1, v124, v1
	v_mul_f32_e32 v124, v155, v155
	v_fmac_f32_e32 v124, v154, v154
	s_waitcnt vmcnt(18)
	v_and_b32_e32 v183, 0xffff0000, v158
	v_add_f32_e32 v1, v124, v1
	v_lshlrev_b32_e32 v182, 16, v158
	v_mul_f32_e32 v124, v183, v183
	v_fmac_f32_e32 v124, v182, v182
	v_lshlrev_b32_e32 v158, 16, v159
	v_and_b32_e32 v159, 0xffff0000, v159
	v_add_f32_e32 v1, v124, v1
	v_mul_f32_e32 v124, v159, v159
	v_fmac_f32_e32 v124, v158, v158
	s_waitcnt vmcnt(17)
	v_and_b32_e32 v185, 0xffff0000, v162
	v_add_f32_e32 v1, v124, v1
	v_lshlrev_b32_e32 v184, 16, v162
	v_mul_f32_e32 v124, v185, v185
	v_fmac_f32_e32 v124, v184, v184
	v_lshlrev_b32_e32 v162, 16, v163
	v_and_b32_e32 v163, 0xffff0000, v163
	v_add_f32_e32 v1, v124, v1
	v_mul_f32_e32 v124, v163, v163
	v_fmac_f32_e32 v124, v162, v162
	s_waitcnt vmcnt(16)
; __device__ __forceinline__ float bf2f(unsigned h) { return __uint_as_float(h << 16); }
; template <int MODE> ...
;     ...
;             float rstd[RPW];
; #pragma unroll
;             for (int rr = 0; rr < RPW; ++rr) { float s = 0.f;
; #pragma unroll
;                 for (int k = 0; k < 8; ++k)
; #pragma unroll
;                     for (int e = 0; e < 2; ++e) { const float a = bf2f(yy[rr][k][e] & 0xffffu), b = bf2f(yy[rr][k][e] >> 16); s += a * a + b * b; }
;                 rstd[rr] = 1.0f / sqrtf(wave_sum(s) * (1.f / DM) + RMS_EPS); }
	v_and_b32_e32 v187, 0xffff0000, v166
	v_add_f32_e32 v1, v124, v1
	v_lshlrev_b32_e32 v186, 16, v166
	v_mul_f32_e32 v124, v187, v187
	v_fmac_f32_e32 v124, v186, v186
	v_lshlrev_b32_e32 v166, 16, v167
	v_and_b32_e32 v167, 0xffff0000, v167
	v_add_f32_e32 v1, v124, v1
	v_mul_f32_e32 v124, v167, v167
	v_fmac_f32_e32 v124, v166, v166
	v_add_f32_e32 v1, v124, v1
	s_waitcnt vmcnt(6)
	v_and_b32_e32 v191, 0xffff0000, v118
	v_lshlrev_b32_e32 v190, 16, v118
	v_add_f32_dpp v1, v1, v1 quad_perm:[1,0,3,2] row_mask:0xf bank_mask:0xf bound_ctrl:1
	v_mul_f32_e32 v118, v191, v191
	v_fmac_f32_e32 v118, v190, v190
	v_add_f32_dpp v1, v1, v1 quad_perm:[2,3,0,1] row_mask:0xf bank_mask:0xf bound_ctrl:1
	v_and_b32_e32 v193, 0xffff0000, v119
	v_lshlrev_b32_e32 v192, 16, v119
	v_add_f32_dpp v1, v1, v1 row_half_mirror row_mask:0xf bank_mask:0xf bound_ctrl:1
	s_waitcnt vmcnt(5)
	v_and_b32_e32 v195, 0xffff0000, v122
	v_lshlrev_b32_e32 v194, 16, v122
	v_add_f32_dpp v1, v1, v1 row_mirror row_mask:0xf bank_mask:0xf bound_ctrl:1
	v_mov_b32_e32 v124, v1
	s_nop 1
	v_permlane16_swap_b32_e32 v1, v124
	v_add_f32_e32 v1, v1, v124
	v_mov_b32_e32 v124, v1
	s_nop 1
	v_permlane32_swap_b32_e32 v1, v124
	v_add_f32_e32 v1, v1, v124
	v_fmamk_f32 v1, v1, 0x3a000000, v218
	v_cmp_gt_f32_e32 vcc, s30, v1
	v_mul_f32_e32 v124, 0x4f800000, v1
	v_and_b32_e32 v197, 0xffff0000, v123
	v_cndmask_b32_e32 v1, v1, v124, vcc
	v_sqrt_f32_e32 v124, v1
	v_lshlrev_b32_e32 v196, 16, v123
	s_waitcnt vmcnt(4)
	v_and_b32_e32 v199, 0xffff0000, v126
	v_lshlrev_b32_e32 v198, 16, v126
	v_add_u32_e32 v125, -1, v124
	v_fma_f32 v128, -v125, v124, v1
	v_cmp_ge_f32_e64 s[40:41], 0, v128
	v_add_u32_e32 v128, 1, v124
	v_and_b32_e32 v201, 0xffff0000, v127
	v_cndmask_b32_e64 v125, v124, v125, s[40:41]
	v_fma_f32 v124, -v128, v124, v1
	v_cmp_lt_f32_e64 s[40:41], 0, v124
	v_lshlrev_b32_e32 v200, 16, v127
	s_waitcnt vmcnt(3)
	v_and_b32_e32 v203, 0xffff0000, v152
	v_cndmask_b32_e64 v124, v125, v128, s[40:41]
	v_mul_f32_e32 v125, 0x37800000, v124
	v_cndmask_b32_e32 v124, v124, v125, vcc
	v_cmp_class_f32_e32 vcc, v1, v215
	v_lshlrev_b32_e32 v202, 16, v152
	v_lshlrev_b32_e32 v152, 16, v153
	v_cndmask_b32_e32 v1, v124, v1, vcc
	v_div_scale_f32 v124, s[0:1], v1, v1, 1.0
	v_rcp_f32_e32 v125, v124
	v_and_b32_e32 v153, 0xffff0000, v153
	s_waitcnt vmcnt(2)
	v_and_b32_e32 v205, 0xffff0000, v156
	v_lshlrev_b32_e32 v204, 16, v156
	v_fma_f32 v128, -v124, v125, 1.0
	v_fmac_f32_e32 v125, v128, v125
	v_div_scale_f32 v128, vcc, 1.0, v1, 1.0
	v_mul_f32_e32 v129, v128, v125
	v_fma_f32 v188, -v124, v129, v128
	v_fmac_f32_e32 v129, v188, v125
	v_fma_f32 v124, -v124, v129, v128
	v_div_fmas_f32 v124, v124, v125, v129
	v_div_fixup_f32 v188, v124, v1, 1.0
	v_lshlrev_b32_e32 v124, 16, v114
	v_and_b32_e32 v125, 0xffff0000, v114
	v_lshlrev_b32_e32 v114, 16, v115
	v_and_b32_e32 v115, 0xffff0000, v115
	v_mul_f32_e32 v1, v125, v125
	v_mul_f32_e32 v128, v115, v115
	v_fmac_f32_e32 v1, v124, v124
	v_fmac_f32_e32 v128, v114, v114
	v_add_f32_e32 v1, v1, v128
	v_add_f32_e32 v1, v1, v118
	v_mul_f32_e32 v118, v193, v193
	v_fmac_f32_e32 v118, v192, v192
	v_add_f32_e32 v1, v118, v1
	v_mul_f32_e32 v118, v195, v195
	v_fmac_f32_e32 v118, v194, v194
	v_add_f32_e32 v1, v118, v1
	v_mul_f32_e32 v118, v197, v197
	v_fmac_f32_e32 v118, v196, v196
	v_add_f32_e32 v1, v118, v1
	v_mul_f32_e32 v118, v199, v199
	v_fmac_f32_e32 v118, v198, v198
	v_add_f32_e32 v1, v118, v1
	v_mul_f32_e32 v118, v201, v201
	v_fmac_f32_e32 v118, v200, v200
	v_add_f32_e32 v1, v118, v1
	v_mul_f32_e32 v118, v203, v203
	v_fmac_f32_e32 v118, v202, v202
	v_add_f32_e32 v1, v118, v1
	v_mul_f32_e32 v118, v153, v153
	v_fmac_f32_e32 v118, v152, v152
	v_add_f32_e32 v1, v118, v1
	v_mul_f32_e32 v118, v205, v205
	v_fmac_f32_e32 v118, v204, v204
	v_lshlrev_b32_e32 v156, 16, v157
	v_and_b32_e32 v157, 0xffff0000, v157
	v_add_f32_e32 v1, v118, v1
	v_mul_f32_e32 v118, v157, v157
	v_fmac_f32_e32 v118, v156, v156
	s_waitcnt vmcnt(1)
	v_and_b32_e32 v207, 0xffff0000, v160
	v_add_f32_e32 v1, v118, v1
	v_lshlrev_b32_e32 v206, 16, v160
	v_mul_f32_e32 v118, v207, v207
	v_fmac_f32_e32 v118, v206, v206
	v_lshlrev_b32_e32 v160, 16, v161
	v_and_b32_e32 v161, 0xffff0000, v161
	v_add_f32_e32 v1, v118, v1
	v_mul_f32_e32 v118, v161, v161
	v_fmac_f32_e32 v118, v160, v160
	s_waitcnt vmcnt(0)
; __device__ __forceinline__ float bf2f(unsigned h) { return __uint_as_float(h << 16); }
; template <int MODE> ...
;     ...
;             float rstd[RPW];
; #pragma unroll
;             for (int rr = 0; rr < RPW; ++rr) { float s = 0.f;
; #pragma unroll
;                 for (int k = 0; k < 8; ++k)
; #pragma unroll
;                     for (int e = 0; e < 2; ++e) { const float a = bf2f(yy[rr][k][e] & 0xffffu), b = bf2f(yy[rr][k][e] >> 16); s += a * a + b * b; }
;                 rstd[rr] = 1.0f / sqrtf(wave_sum(s) * (1.f / DM) + RMS_EPS); }
; #pragma unroll
;             for (int k = 0; k < 8; ++k) { const f32x4 g = *(const f32x4*)(gpost + k * 256 + lane * 4);
; #pragma unroll
;                 for (int rr = 0; rr < RPW; ++rr) { f32x4 yv;
;                     yv[0] = bf2f(yy[rr][k][0] & 0xffffu); yv[1] = bf2f(yy[rr][k][0] >> 16); yv[2] = bf2f(yy[rr][k][1] & 0xffffu); yv[3] = bf2f(yy[rr][k][1] >> 16);
;                     xv[rr][k] += yv * rstd[rr] * g; } }
	v_and_b32_e32 v209, 0xffff0000, v164
	v_add_f32_e32 v1, v118, v1
	v_lshlrev_b32_e32 v208, 16, v164
	v_mul_f32_e32 v118, v209, v209
	v_fmac_f32_e32 v118, v208, v208
	v_lshlrev_b32_e32 v164, 16, v165
	v_and_b32_e32 v165, 0xffff0000, v165
	v_add_f32_e32 v1, v118, v1
	v_mul_f32_e32 v118, v165, v165
	v_fmac_f32_e32 v118, v164, v164
	v_add_f32_e32 v1, v118, v1
	v_pk_mul_f32 v[116:117], v[188:189], v[116:117] op_sel_hi:[0,1]
	v_pk_fma_f32 v[128:129], v[4:5], v[116:117], v[96:97]
	v_add_f32_dpp v1, v1, v1 quad_perm:[1,0,3,2] row_mask:0xf bank_mask:0xf bound_ctrl:1
	s_nop 1
	v_add_f32_dpp v1, v1, v1 quad_perm:[2,3,0,1] row_mask:0xf bank_mask:0xf bound_ctrl:1
	s_nop 1
	v_add_f32_dpp v1, v1, v1 row_half_mirror row_mask:0xf bank_mask:0xf bound_ctrl:1
	s_nop 1
	v_add_f32_dpp v1, v1, v1 row_mirror row_mask:0xf bank_mask:0xf bound_ctrl:1
	v_mov_b32_e32 v118, v1
	s_nop 1
	v_permlane16_swap_b32_e32 v1, v118
	v_add_f32_e32 v1, v1, v118
	v_mov_b32_e32 v118, v1
	s_nop 1
	v_permlane32_swap_b32_e32 v1, v118
	v_add_f32_e32 v1, v1, v118
	v_fmamk_f32 v1, v1, 0x3a000000, v218
	v_cmp_gt_f32_e32 vcc, s30, v1
	v_mul_f32_e32 v118, 0x4f800000, v1
	s_nop 0
	v_cndmask_b32_e32 v1, v1, v118, vcc
	v_sqrt_f32_e32 v118, v1
	s_nop 0
	v_add_u32_e32 v119, -1, v118
	v_fma_f32 v122, -v119, v118, v1
	v_cmp_ge_f32_e64 s[40:41], 0, v122
	v_add_u32_e32 v122, 1, v118
	s_nop 0
	v_cndmask_b32_e64 v119, v118, v119, s[40:41]
	v_fma_f32 v118, -v122, v118, v1
	v_cmp_lt_f32_e64 s[40:41], 0, v118
	s_nop 1
	v_cndmask_b32_e64 v118, v119, v122, s[40:41]
	v_mul_f32_e32 v119, 0x37800000, v118
	v_cndmask_b32_e32 v118, v118, v119, vcc
	v_cmp_class_f32_e32 vcc, v1, v215
	s_nop 1
	v_cndmask_b32_e32 v1, v118, v1, vcc
	v_div_scale_f32 v118, s[0:1], v1, v1, 1.0
	v_rcp_f32_e32 v119, v118
	s_nop 0
	v_fma_f32 v122, -v118, v119, 1.0
	v_fmac_f32_e32 v119, v122, v119
	v_div_scale_f32 v122, vcc, 1.0, v1, 1.0
	v_mul_f32_e32 v123, v122, v119
	v_fma_f32 v126, -v118, v123, v122
	v_fmac_f32_e32 v123, v126, v119
	v_fma_f32 v118, -v118, v123, v122
	v_div_fmas_f32 v118, v118, v119, v123
	v_div_fixup_f32 v210, v118, v1, 1.0
	v_pk_mul_f32 v[118:119], v[188:189], v[168:169] op_sel_hi:[0,1]
	v_pk_fma_f32 v[126:127], v[2:3], v[118:119], v[94:95]
	v_pk_mul_f32 v[94:95], v[210:211], v[124:125] op_sel_hi:[0,1]
	v_pk_mul_f32 v[96:97], v[210:211], v[114:115] op_sel_hi:[0,1]
	v_pk_fma_f32 v[122:123], v[2:3], v[94:95], v[110:111]
	v_pk_mul_f32 v[94:95], v[188:189], v[170:171] op_sel_hi:[0,1]
	v_pk_fma_f32 v[124:125], v[4:5], v[96:97], v[112:113]
	v_pk_mul_f32 v[96:97], v[188:189], v[120:121] op_sel_hi:[0,1]
	v_pk_fma_f32 v[118:119], v[6:7], v[94:95], v[90:91]
	v_pk_mul_f32 v[90:91], v[210:211], v[190:191] op_sel_hi:[0,1]
	v_pk_fma_f32 v[120:121], v[8:9], v[96:97], v[92:93]
	v_pk_mul_f32 v[92:93], v[210:211], v[192:193] op_sel_hi:[0,1]
	v_pk_fma_f32 v[114:115], v[6:7], v[90:91], v[106:107]
	v_pk_mul_f32 v[90:91], v[188:189], v[172:173] op_sel_hi:[0,1]
	v_pk_fma_f32 v[116:117], v[8:9], v[92:93], v[108:109]
	v_pk_mul_f32 v[92:93], v[188:189], v[174:175] op_sel_hi:[0,1]
	v_pk_fma_f32 v[110:111], v[10:11], v[90:91], v[86:87]
	v_pk_mul_f32 v[86:87], v[210:211], v[194:195] op_sel_hi:[0,1]
	v_pk_fma_f32 v[112:113], v[12:13], v[92:93], v[88:89]
	v_pk_mul_f32 v[88:89], v[210:211], v[196:197] op_sel_hi:[0,1]
	v_pk_fma_f32 v[106:107], v[10:11], v[86:87], v[102:103]
	v_pk_mul_f32 v[86:87], v[188:189], v[176:177] op_sel_hi:[0,1]
	v_pk_fma_f32 v[108:109], v[12:13], v[88:89], v[104:105]
	v_pk_mul_f32 v[88:89], v[188:189], v[178:179] op_sel_hi:[0,1]
	v_pk_fma_f32 v[102:103], v[14:15], v[86:87], v[82:83]
	v_pk_mul_f32 v[82:83], v[210:211], v[198:199] op_sel_hi:[0,1]
	v_pk_fma_f32 v[104:105], v[16:17], v[88:89], v[84:85]
	v_pk_mul_f32 v[84:85], v[210:211], v[200:201] op_sel_hi:[0,1]
	v_pk_fma_f32 v[98:99], v[14:15], v[82:83], v[98:99]
	v_pk_mul_f32 v[82:83], v[188:189], v[180:181] op_sel_hi:[0,1]
	v_pk_fma_f32 v[100:101], v[16:17], v[84:85], v[100:101]
	v_pk_mul_f32 v[84:85], v[188:189], v[154:155] op_sel_hi:[0,1]
	v_pk_fma_f32 v[94:95], v[18:19], v[82:83], v[78:79]
	v_pk_mul_f32 v[78:79], v[210:211], v[202:203] op_sel_hi:[0,1]
	v_pk_fma_f32 v[96:97], v[20:21], v[84:85], v[80:81]
	v_pk_mul_f32 v[80:81], v[210:211], v[152:153] op_sel_hi:[0,1]
	v_pk_fma_f32 v[90:91], v[18:19], v[78:79], v[142:143]
	v_pk_mul_f32 v[78:79], v[188:189], v[182:183] op_sel_hi:[0,1]
	v_pk_fma_f32 v[92:93], v[20:21], v[80:81], v[144:145]
	v_pk_mul_f32 v[80:81], v[188:189], v[158:159] op_sel_hi:[0,1]
	v_pk_fma_f32 v[86:87], v[22:23], v[78:79], v[74:75]
	v_pk_mul_f32 v[74:75], v[210:211], v[204:205] op_sel_hi:[0,1]
	v_pk_fma_f32 v[88:89], v[24:25], v[80:81], v[76:77]
	v_pk_mul_f32 v[76:77], v[210:211], v[156:157] op_sel_hi:[0,1]
	v_pk_fma_f32 v[82:83], v[22:23], v[74:75], v[138:139]
	v_pk_mul_f32 v[74:75], v[188:189], v[184:185] op_sel_hi:[0,1]
	v_pk_fma_f32 v[84:85], v[24:25], v[76:77], v[140:141]
	v_pk_mul_f32 v[76:77], v[188:189], v[162:163] op_sel_hi:[0,1]
	v_pk_fma_f32 v[78:79], v[26:27], v[74:75], v[70:71]
	v_pk_mul_f32 v[70:71], v[210:211], v[206:207] op_sel_hi:[0,1]
	v_pk_fma_f32 v[80:81], v[28:29], v[76:77], v[72:73]
	v_pk_mul_f32 v[72:73], v[210:211], v[160:161] op_sel_hi:[0,1]
	v_pk_fma_f32 v[74:75], v[26:27], v[70:71], v[134:135]
	v_pk_mul_f32 v[70:71], v[188:189], v[186:187] op_sel_hi:[0,1]
	v_pk_fma_f32 v[76:77], v[28:29], v[72:73], v[136:137]
	v_pk_mul_f32 v[72:73], v[188:189], v[166:167] op_sel_hi:[0,1]
	v_pk_fma_f32 v[70:71], v[30:31], v[70:71], v[66:67]
	v_pk_mul_f32 v[66:67], v[210:211], v[208:209] op_sel_hi:[0,1]
	v_pk_fma_f32 v[72:73], v[32:33], v[72:73], v[68:69]
	v_pk_mul_f32 v[68:69], v[210:211], v[164:165] op_sel_hi:[0,1]
; template <int MODE> ...
;     ...
;         if (MODE != 0)
; #pragma unroll
;         for (int rr = 0; rr < RPW; ++rr) { float* xo = xres + (size_t)(m + rr) * DM + lane * 4;
; #pragma unroll
;             for (int k = 0; k < 8; ++k) *(f32x4*)(xo + k * 256) = xv[rr][k]; }
;         if (MODE <= 1) {
;             float rstd[RPW];
; #pragma unroll
;             for (int rr = 0; rr < RPW; ++rr) { float s = 0.f;
; #pragma unroll
;                 for (int k = 0; k < 8; ++k) s += (xv[rr][k][0] * xv[rr][k][0] + xv[rr][k][1] * xv[rr][k][1]) + (xv[rr][k][2] * xv[rr][k][2] + xv[rr][k][3] * xv[rr][k][3]);
;                 rstd[rr] = 1.0f / sqrtf(wave_sum(s) * (1.f / DM) + RMS_EPS); }
	v_pk_fma_f32 v[66:67], v[30:31], v[66:67], v[130:131]
	v_lshl_add_u64 v[130:131], s[78:79], 0, v[146:147]
	v_pk_fma_f32 v[68:69], v[32:33], v[68:69], v[132:133]
	v_add_co_u32_e32 v132, vcc, s19, v130
	global_store_dwordx4 v[130:131], v[126:129], off sc0 sc1
	global_store_dwordx4 v[130:131], v[118:121], off offset:1024 sc0 sc1
	global_store_dwordx4 v[130:131], v[110:113], off offset:2048 sc0 sc1
	global_store_dwordx4 v[130:131], v[102:105], off offset:3072 sc0 sc1
	v_addc_co_u32_e32 v133, vcc, 0, v131, vcc
	v_add_co_u32_e32 v134, vcc, s31, v130
	v_mul_f32_e32 v1, v127, v127
	s_nop 0
	v_addc_co_u32_e32 v135, vcc, 0, v131, vcc
	v_add_co_u32_e32 v130, vcc, s33, v130
	global_store_dwordx4 v[134:135], v[94:97], off offset:-4096 sc0 sc1
	global_store_dwordx4 v[132:133], v[86:89], off offset:1024 sc0 sc1
	global_store_dwordx4 v[132:133], v[78:81], off offset:2048 sc0 sc1
	global_store_dwordx4 v[132:133], v[70:73], off offset:3072 sc0 sc1
	global_store_dwordx4 v[134:135], v[122:125], off sc0 sc1
	global_store_dwordx4 v[134:135], v[114:117], off offset:1024 sc0 sc1
	global_store_dwordx4 v[134:135], v[106:109], off offset:2048 sc0 sc1
	global_store_dwordx4 v[134:135], v[98:101], off offset:3072 sc0 sc1
	v_addc_co_u32_e32 v131, vcc, 0, v131, vcc
	global_store_dwordx4 v[130:131], v[90:93], off sc0 sc1
	global_store_dwordx4 v[130:131], v[82:85], off offset:1024 sc0 sc1
	global_store_dwordx4 v[130:131], v[74:77], off offset:2048 sc0 sc1
	global_store_dwordx4 v[130:131], v[66:69], off offset:3072 sc0 sc1
	v_mul_f32_e32 v130, v129, v129
	v_fmac_f32_e32 v1, v126, v126
	v_fmac_f32_e32 v130, v128, v128
	v_add_f32_e32 v1, v1, v130
	v_mul_f32_e32 v130, v119, v119
	v_mul_f32_e32 v131, v121, v121
	v_fmac_f32_e32 v130, v118, v118
	v_fmac_f32_e32 v131, v120, v120
	v_add_f32_e32 v130, v130, v131
	v_add_f32_e32 v1, v1, v130
	v_mul_f32_e32 v130, v111, v111
	v_mul_f32_e32 v131, v113, v113
	v_fmac_f32_e32 v130, v110, v110
	v_fmac_f32_e32 v131, v112, v112
	v_add_f32_e32 v130, v130, v131
	v_add_f32_e32 v1, v130, v1
	v_mul_f32_e32 v130, v103, v103
	v_mul_f32_e32 v131, v105, v105
	v_fmac_f32_e32 v130, v102, v102
	v_fmac_f32_e32 v131, v104, v104
	v_add_f32_e32 v130, v130, v131
	v_add_f32_e32 v1, v130, v1
	v_mul_f32_e32 v130, v95, v95
	v_mul_f32_e32 v131, v97, v97
	v_fmac_f32_e32 v130, v94, v94
	v_fmac_f32_e32 v131, v96, v96
	v_add_f32_e32 v130, v130, v131
	v_add_f32_e32 v1, v130, v1
	v_mul_f32_e32 v130, v87, v87
	v_mul_f32_e32 v131, v89, v89
	v_fmac_f32_e32 v130, v86, v86
	v_fmac_f32_e32 v131, v88, v88
	v_add_f32_e32 v130, v130, v131
	v_add_f32_e32 v1, v130, v1
	v_mul_f32_e32 v130, v79, v79
	v_mul_f32_e32 v131, v81, v81
	v_fmac_f32_e32 v130, v78, v78
	v_fmac_f32_e32 v131, v80, v80
	v_add_f32_e32 v130, v130, v131
	v_add_f32_e32 v1, v130, v1
	v_mul_f32_e32 v130, v71, v71
	v_mul_f32_e32 v131, v73, v73
	v_fmac_f32_e32 v130, v70, v70
	v_fmac_f32_e32 v131, v72, v72
	v_add_f32_e32 v130, v130, v131
	v_add_f32_e32 v1, v130, v1
	s_add_u32 s78, s78, s26
	s_addc_u32 s79, s79, s27
	v_add_f32_dpp v1, v1, v1 quad_perm:[1,0,3,2] row_mask:0xf bank_mask:0xf bound_ctrl:1
	s_add_u32 s64, s64, s26
	s_addc_u32 s65, s65, s27
	v_add_f32_dpp v1, v1, v1 quad_perm:[2,3,0,1] row_mask:0xf bank_mask:0xf bound_ctrl:1
	s_cmpk_gt_i32 s42, 0x3fff
	s_nop 0
	v_add_f32_dpp v1, v1, v1 row_half_mirror row_mask:0xf bank_mask:0xf bound_ctrl:1
	s_nop 1
	v_add_f32_dpp v1, v1, v1 row_mirror row_mask:0xf bank_mask:0xf bound_ctrl:1
	v_mov_b32_e32 v130, v1
	s_nop 1
	v_permlane16_swap_b32_e32 v1, v130
	v_add_f32_e32 v1, v1, v130
	v_mov_b32_e32 v130, v1
	s_nop 1
	v_permlane32_swap_b32_e32 v1, v130
	v_add_f32_e32 v1, v1, v130
	v_fmamk_f32 v1, v1, 0x3a000000, v218
	v_cmp_gt_f32_e32 vcc, s30, v1
	v_mul_f32_e32 v130, 0x4f800000, v1
	s_nop 0
	v_cndmask_b32_e32 v1, v1, v130, vcc
	v_sqrt_f32_e32 v130, v1
	s_nop 0
	v_add_u32_e32 v131, -1, v130
	v_fma_f32 v132, -v131, v130, v1
	v_cmp_ge_f32_e64 s[40:41], 0, v132
	v_add_u32_e32 v132, 1, v130
	s_nop 0
	v_cndmask_b32_e64 v131, v130, v131, s[40:41]
	v_fma_f32 v130, -v132, v130, v1
	v_cmp_lt_f32_e64 s[40:41], 0, v130
	s_nop 1
	v_cndmask_b32_e64 v130, v131, v132, s[40:41]
	v_mul_f32_e32 v131, 0x37800000, v130
	v_cndmask_b32_e32 v130, v130, v131, vcc
	v_cmp_class_f32_e32 vcc, v1, v215
	s_nop 1
	v_cndmask_b32_e32 v1, v130, v1, vcc
	v_div_scale_f32 v130, s[0:1], v1, v1, 1.0
	v_rcp_f32_e32 v131, v130
	s_nop 0
	v_fma_f32 v132, -v130, v131, 1.0
	v_fmac_f32_e32 v131, v132, v131
	v_div_scale_f32 v132, vcc, 1.0, v1, 1.0
	v_mul_f32_e32 v133, v132, v131
	v_fma_f32 v134, -v130, v133, v132
	v_fmac_f32_e32 v133, v134, v131
	v_fma_f32 v130, -v130, v133, v132
	v_div_fmas_f32 v130, v130, v131, v133
	v_div_fixup_f32 v130, v130, v1, 1.0
	v_mul_f32_e32 v1, v123, v123
	v_mul_f32_e32 v131, v125, v125
	v_fmac_f32_e32 v1, v122, v122
	v_fmac_f32_e32 v131, v124, v124
	v_add_f32_e32 v1, v1, v131
	v_mul_f32_e32 v131, v115, v115
	v_mul_f32_e32 v132, v117, v117
	v_fmac_f32_e32 v131, v114, v114
	v_fmac_f32_e32 v132, v116, v116
	v_add_f32_e32 v131, v131, v132
	v_add_f32_e32 v1, v1, v131
	v_mul_f32_e32 v131, v107, v107
	v_mul_f32_e32 v132, v109, v109
	v_fmac_f32_e32 v131, v106, v106
	v_fmac_f32_e32 v132, v108, v108
	v_add_f32_e32 v131, v131, v132
	v_add_f32_e32 v1, v131, v1
	v_mul_f32_e32 v131, v99, v99
	v_mul_f32_e32 v132, v101, v101
	v_fmac_f32_e32 v131, v98, v98
	v_fmac_f32_e32 v132, v100, v100
	v_add_f32_e32 v131, v131, v132
	v_add_f32_e32 v1, v131, v1
	v_mul_f32_e32 v131, v91, v91
	v_mul_f32_e32 v132, v93, v93
	v_fmac_f32_e32 v131, v90, v90
	v_fmac_f32_e32 v132, v92, v92
	v_add_f32_e32 v131, v131, v132
	v_add_f32_e32 v1, v131, v1
	v_mul_f32_e32 v131, v83, v83
	v_mul_f32_e32 v132, v85, v85
	v_fmac_f32_e32 v131, v82, v82
; __device__ __forceinline__ unsigned pk2(float lo, float hi) { return f2bf(lo) | (f2bf(hi) << 16); }
; template <int MODE> ...
;     ...
;             for (int rr = 0; rr < RPW; ++rr) { float s = 0.f;
; #pragma unroll
;                 for (int k = 0; k < 8; ++k) s += (xv[rr][k][0] * xv[rr][k][0] + xv[rr][k][1] * xv[rr][k][1]) + (xv[rr][k][2] * xv[rr][k][2] + xv[rr][k][3] * xv[rr][k][3]);
;                 rstd[rr] = 1.0f / sqrtf(wave_sum(s) * (1.f / DM) + RMS_EPS); }
; #pragma unroll
;             for (int k = 0; k < 8; ++k) { const f32x4 g = *(const f32x4*)(gpre + k * 256 + lane * 4);
; #pragma unroll
;                 for (int rr = 0; rr < RPW; ++rr) { const f32x4 a = xv[rr][k] * rstd[rr] * g;
;                     v2u o; o.x = pk2(a[0], a[1]); o.y = pk2(a[2], a[3]);
;                     *(v2u*)(h + ((size_t)(k * 4 + (lane >> 4)) * M_TOK + (m + rr)) * 64 + (lane & 15) * 4) = o; } }
	v_fmac_f32_e32 v132, v84, v84
	v_add_f32_e32 v131, v131, v132
	v_add_f32_e32 v1, v131, v1
	v_mul_f32_e32 v131, v75, v75
	v_mul_f32_e32 v132, v77, v77
	v_fmac_f32_e32 v131, v74, v74
	v_fmac_f32_e32 v132, v76, v76
	v_add_f32_e32 v131, v131, v132
	v_add_f32_e32 v1, v131, v1
	v_mul_f32_e32 v131, v67, v67
	v_mul_f32_e32 v132, v69, v69
	v_fmac_f32_e32 v131, v66, v66
	v_fmac_f32_e32 v132, v68, v68
	v_add_f32_e32 v131, v131, v132
	v_add_f32_e32 v1, v131, v1
	s_nop 1
	v_add_f32_dpp v1, v1, v1 quad_perm:[1,0,3,2] row_mask:0xf bank_mask:0xf bound_ctrl:1
	s_nop 1
	v_add_f32_dpp v1, v1, v1 quad_perm:[2,3,0,1] row_mask:0xf bank_mask:0xf bound_ctrl:1
	s_nop 1
	v_add_f32_dpp v1, v1, v1 row_half_mirror row_mask:0xf bank_mask:0xf bound_ctrl:1
	s_nop 1
	v_add_f32_dpp v1, v1, v1 row_mirror row_mask:0xf bank_mask:0xf bound_ctrl:1
	v_mov_b32_e32 v131, v1
	s_nop 1
	v_permlane16_swap_b32_e32 v1, v131
	v_add_f32_e32 v1, v1, v131
	v_mov_b32_e32 v131, v1
	s_nop 1
	v_permlane32_swap_b32_e32 v1, v131
	v_add_f32_e32 v1, v1, v131
	v_fmamk_f32 v1, v1, 0x3a000000, v218
	v_cmp_gt_f32_e32 vcc, s30, v1
	v_mul_f32_e32 v131, 0x4f800000, v1
	s_nop 0
	v_cndmask_b32_e32 v1, v1, v131, vcc
	v_sqrt_f32_e32 v131, v1
	s_nop 0
	v_add_u32_e32 v132, -1, v131
	v_fma_f32 v133, -v132, v131, v1
	v_cmp_ge_f32_e64 s[40:41], 0, v133
	v_add_u32_e32 v133, 1, v131
	s_nop 0
	v_cndmask_b32_e64 v132, v131, v132, s[40:41]
	v_fma_f32 v131, -v133, v131, v1
	v_cmp_lt_f32_e64 s[40:41], 0, v131
	s_nop 1
	v_cndmask_b32_e64 v131, v132, v133, s[40:41]
	v_mul_f32_e32 v132, 0x37800000, v131
	v_cndmask_b32_e32 v131, v131, v132, vcc
	v_cmp_class_f32_e32 vcc, v1, v215
	s_nop 1
	v_cndmask_b32_e32 v1, v131, v1, vcc
	v_div_scale_f32 v131, s[0:1], v1, v1, 1.0
	v_rcp_f32_e32 v132, v131
	s_mov_b32 s0, 0x4800000
	v_fma_f32 v133, -v131, v132, 1.0
	v_fmac_f32_e32 v132, v133, v132
	v_div_scale_f32 v133, vcc, 1.0, v1, 1.0
	v_mul_f32_e32 v134, v133, v132
	v_fma_f32 v135, -v131, v134, v133
	v_fmac_f32_e32 v134, v135, v132
	v_fma_f32 v131, -v131, v134, v133
	v_div_fmas_f32 v131, v131, v132, v134
	v_pk_mul_f32 v[126:127], v[126:127], v[130:131] op_sel_hi:[1,0]
	v_div_fixup_f32 v132, v131, v1, 1.0
	v_pk_mul_f32 v[126:127], v[46:47], v[126:127]
	v_pk_mul_f32 v[128:129], v[128:129], v[130:131] op_sel_hi:[1,0]
	v_bfe_u32 v1, v126, 16, 1
	v_add3_u32 v1, v126, v1, s63
	v_bfe_u32 v126, v127, 16, 1
	v_pk_mul_f32 v[128:129], v[48:49], v[128:129]
	v_lshrrev_b32_e32 v1, 16, v1
	v_add3_u32 v126, v127, v126, s63
	v_and_or_b32 v126, v126, s60, v1
	v_bfe_u32 v1, v128, 16, 1
	v_add3_u32 v1, v128, v1, s63
	v_bfe_u32 v127, v129, 16, 1
	v_pk_mul_f32 v[122:123], v[122:123], v[132:133] op_sel_hi:[1,0]
	v_lshrrev_b32_e32 v1, 16, v1
	v_add3_u32 v127, v129, v127, s63
	v_pk_mul_f32 v[122:123], v[46:47], v[122:123]
	v_and_or_b32 v127, v127, s60, v1
	v_bfe_u32 v1, v122, 16, 1
	v_pk_mul_f32 v[124:125], v[124:125], v[132:133] op_sel_hi:[1,0]
	v_add3_u32 v1, v122, v1, s63
	v_bfe_u32 v122, v123, 16, 1
	v_pk_mul_f32 v[124:125], v[48:49], v[124:125]
	v_lshrrev_b32_e32 v1, 16, v1
	v_add3_u32 v122, v123, v122, s63
	v_and_or_b32 v122, v122, s60, v1
	v_bfe_u32 v1, v124, 16, 1
	v_add3_u32 v1, v124, v1, s63
	v_bfe_u32 v123, v125, 16, 1
	v_pk_mul_f32 v[118:119], v[118:119], v[130:131] op_sel_hi:[1,0]
	v_lshrrev_b32_e32 v1, 16, v1
	v_add3_u32 v123, v125, v123, s63
	v_pk_mul_f32 v[118:119], v[34:35], v[118:119]
	v_and_or_b32 v123, v123, s60, v1
	v_bfe_u32 v1, v118, 16, 1
	v_pk_mul_f32 v[120:121], v[120:121], v[130:131] op_sel_hi:[1,0]
	v_add3_u32 v1, v118, v1, s63
	v_bfe_u32 v118, v119, 16, 1
	v_pk_mul_f32 v[120:121], v[36:37], v[120:121]
	v_lshrrev_b32_e32 v1, 16, v1
	v_add3_u32 v118, v119, v118, s63
	v_and_or_b32 v118, v118, s60, v1
	v_bfe_u32 v1, v120, 16, 1
	v_add3_u32 v1, v120, v1, s63
	v_bfe_u32 v119, v121, 16, 1
	v_pk_mul_f32 v[114:115], v[114:115], v[132:133] op_sel_hi:[1,0]
	v_lshrrev_b32_e32 v1, 16, v1
	v_add3_u32 v119, v121, v119, s63
	v_pk_mul_f32 v[114:115], v[34:35], v[114:115]
	v_and_or_b32 v119, v119, s60, v1
	v_bfe_u32 v1, v114, 16, 1
	v_pk_mul_f32 v[116:117], v[116:117], v[132:133] op_sel_hi:[1,0]
	v_add3_u32 v1, v114, v1, s63
	v_bfe_u32 v114, v115, 16, 1
	v_pk_mul_f32 v[116:117], v[36:37], v[116:117]
	v_lshrrev_b32_e32 v1, 16, v1
	v_add3_u32 v114, v115, v114, s63
	v_and_or_b32 v114, v114, s60, v1
	v_bfe_u32 v1, v116, 16, 1
	v_add3_u32 v1, v116, v1, s63
	v_bfe_u32 v115, v117, 16, 1
	v_pk_mul_f32 v[110:111], v[110:111], v[130:131] op_sel_hi:[1,0]
	v_lshrrev_b32_e32 v1, 16, v1
	v_add3_u32 v115, v117, v115, s63
	v_pk_mul_f32 v[110:111], v[38:39], v[110:111]
	v_and_or_b32 v115, v115, s60, v1
	v_bfe_u32 v1, v110, 16, 1
	v_pk_mul_f32 v[112:113], v[112:113], v[130:131] op_sel_hi:[1,0]
	v_add3_u32 v1, v110, v1, s63
	v_bfe_u32 v110, v111, 16, 1
	v_pk_mul_f32 v[112:113], v[40:41], v[112:113]
	v_lshrrev_b32_e32 v1, 16, v1
	v_add3_u32 v110, v111, v110, s63
	v_and_or_b32 v110, v110, s60, v1
	v_bfe_u32 v1, v112, 16, 1
	v_add3_u32 v1, v112, v1, s63
	v_bfe_u32 v111, v113, 16, 1
	v_pk_mul_f32 v[106:107], v[106:107], v[132:133] op_sel_hi:[1,0]
	v_lshrrev_b32_e32 v1, 16, v1
	v_add3_u32 v111, v113, v111, s63
	v_pk_mul_f32 v[106:107], v[38:39], v[106:107]
	v_and_or_b32 v111, v111, s60, v1
	v_bfe_u32 v1, v106, 16, 1
	v_pk_mul_f32 v[108:109], v[108:109], v[132:133] op_sel_hi:[1,0]
	v_add3_u32 v1, v106, v1, s63
	v_bfe_u32 v106, v107, 16, 1
	v_pk_mul_f32 v[108:109], v[40:41], v[108:109]
	v_lshrrev_b32_e32 v1, 16, v1
	v_add3_u32 v106, v107, v106, s63
	v_and_or_b32 v106, v106, s60, v1
	v_bfe_u32 v1, v108, 16, 1
	v_add3_u32 v1, v108, v1, s63
	v_bfe_u32 v107, v109, 16, 1
	v_pk_mul_f32 v[102:103], v[102:103], v[130:131] op_sel_hi:[1,0]
	v_lshrrev_b32_e32 v1, 16, v1
; __device__ __forceinline__ unsigned pk2(float lo, float hi) { return f2bf(lo) | (f2bf(hi) << 16); }
; template <int MODE> ...
;     ...
; #pragma unroll
;             for (int k = 0; k < 8; ++k) { const f32x4 g = *(const f32x4*)(gpre + k * 256 + lane * 4);
; #pragma unroll
;                 for (int rr = 0; rr < RPW; ++rr) { const f32x4 a = xv[rr][k] * rstd[rr] * g;
;                     v2u o; o.x = pk2(a[0], a[1]); o.y = pk2(a[2], a[3]);
;                     *(v2u*)(h + ((size_t)(k * 4 + (lane >> 4)) * M_TOK + (m + rr)) * 64 + (lane & 15) * 4) = o; } }
	v_add3_u32 v107, v109, v107, s63
	v_pk_mul_f32 v[102:103], v[42:43], v[102:103]
	v_and_or_b32 v107, v107, s60, v1
	v_bfe_u32 v1, v102, 16, 1
	v_pk_mul_f32 v[104:105], v[104:105], v[130:131] op_sel_hi:[1,0]
	v_add3_u32 v1, v102, v1, s63
	v_bfe_u32 v102, v103, 16, 1
	v_pk_mul_f32 v[104:105], v[44:45], v[104:105]
	v_lshrrev_b32_e32 v1, 16, v1
	v_add3_u32 v102, v103, v102, s63
	v_and_or_b32 v102, v102, s60, v1
	v_bfe_u32 v1, v104, 16, 1
	v_add3_u32 v1, v104, v1, s63
	v_bfe_u32 v103, v105, 16, 1
	v_pk_mul_f32 v[98:99], v[98:99], v[132:133] op_sel_hi:[1,0]
	v_lshrrev_b32_e32 v1, 16, v1
	v_add3_u32 v103, v105, v103, s63
	v_pk_mul_f32 v[98:99], v[42:43], v[98:99]
	v_and_or_b32 v103, v103, s60, v1
	v_bfe_u32 v1, v98, 16, 1
	v_pk_mul_f32 v[100:101], v[100:101], v[132:133] op_sel_hi:[1,0]
	v_add3_u32 v1, v98, v1, s63
	v_bfe_u32 v98, v99, 16, 1
	v_pk_mul_f32 v[100:101], v[44:45], v[100:101]
	v_lshrrev_b32_e32 v1, 16, v1
	v_add3_u32 v98, v99, v98, s63
	v_and_or_b32 v98, v98, s60, v1
	v_bfe_u32 v1, v100, 16, 1
	v_add3_u32 v1, v100, v1, s63
	v_bfe_u32 v99, v101, 16, 1
	v_pk_mul_f32 v[94:95], v[94:95], v[130:131] op_sel_hi:[1,0]
	v_lshrrev_b32_e32 v1, 16, v1
	v_add3_u32 v99, v101, v99, s63
	v_pk_mul_f32 v[94:95], v[50:51], v[94:95]
	v_and_or_b32 v99, v99, s60, v1
	v_bfe_u32 v1, v94, 16, 1
	v_pk_mul_f32 v[96:97], v[96:97], v[130:131] op_sel_hi:[1,0]
	v_add3_u32 v1, v94, v1, s63
	v_bfe_u32 v94, v95, 16, 1
	v_pk_mul_f32 v[96:97], v[52:53], v[96:97]
	v_lshrrev_b32_e32 v1, 16, v1
	v_add3_u32 v94, v95, v94, s63
	v_and_or_b32 v94, v94, s60, v1
	v_bfe_u32 v1, v96, 16, 1
	v_add3_u32 v1, v96, v1, s63
	v_bfe_u32 v95, v97, 16, 1
	v_pk_mul_f32 v[90:91], v[90:91], v[132:133] op_sel_hi:[1,0]
	v_lshrrev_b32_e32 v1, 16, v1
	v_add3_u32 v95, v97, v95, s63
	v_pk_mul_f32 v[90:91], v[50:51], v[90:91]
	v_and_or_b32 v95, v95, s60, v1
	v_bfe_u32 v1, v90, 16, 1
	v_pk_mul_f32 v[92:93], v[92:93], v[132:133] op_sel_hi:[1,0]
	v_add3_u32 v1, v90, v1, s63
	v_bfe_u32 v90, v91, 16, 1
	v_pk_mul_f32 v[92:93], v[52:53], v[92:93]
	v_lshrrev_b32_e32 v1, 16, v1
	v_add3_u32 v90, v91, v90, s63
	v_and_or_b32 v90, v90, s60, v1
	v_bfe_u32 v1, v92, 16, 1
	v_add3_u32 v1, v92, v1, s63
	v_bfe_u32 v91, v93, 16, 1
	v_pk_mul_f32 v[86:87], v[86:87], v[130:131] op_sel_hi:[1,0]
	v_lshrrev_b32_e32 v1, 16, v1
	v_add3_u32 v91, v93, v91, s63
	v_pk_mul_f32 v[86:87], v[54:55], v[86:87]
	v_and_or_b32 v91, v91, s60, v1
	v_bfe_u32 v1, v86, 16, 1
	v_pk_mul_f32 v[88:89], v[88:89], v[130:131] op_sel_hi:[1,0]
	v_add3_u32 v1, v86, v1, s63
	v_bfe_u32 v86, v87, 16, 1
	v_pk_mul_f32 v[88:89], v[56:57], v[88:89]
	v_lshrrev_b32_e32 v1, 16, v1
	v_add3_u32 v86, v87, v86, s63
	v_and_or_b32 v86, v86, s60, v1
	v_bfe_u32 v1, v88, 16, 1
	v_add3_u32 v1, v88, v1, s63
	v_bfe_u32 v87, v89, 16, 1
	v_pk_mul_f32 v[82:83], v[82:83], v[132:133] op_sel_hi:[1,0]
	v_lshrrev_b32_e32 v1, 16, v1
	v_add3_u32 v87, v89, v87, s63
	v_pk_mul_f32 v[82:83], v[54:55], v[82:83]
	v_and_or_b32 v87, v87, s60, v1
	v_bfe_u32 v1, v82, 16, 1
	v_pk_mul_f32 v[84:85], v[84:85], v[132:133] op_sel_hi:[1,0]
	v_add3_u32 v1, v82, v1, s63
	v_bfe_u32 v82, v83, 16, 1
	v_pk_mul_f32 v[84:85], v[56:57], v[84:85]
	v_lshrrev_b32_e32 v1, 16, v1
	v_add3_u32 v82, v83, v82, s63
	v_and_or_b32 v82, v82, s60, v1
	v_bfe_u32 v1, v84, 16, 1
	v_add3_u32 v1, v84, v1, s63
	v_bfe_u32 v83, v85, 16, 1
	v_pk_mul_f32 v[78:79], v[78:79], v[130:131] op_sel_hi:[1,0]
	v_lshrrev_b32_e32 v1, 16, v1
	v_add3_u32 v83, v85, v83, s63
	v_pk_mul_f32 v[78:79], v[58:59], v[78:79]
	v_and_or_b32 v83, v83, s60, v1
	v_bfe_u32 v1, v78, 16, 1
	v_pk_mul_f32 v[80:81], v[80:81], v[130:131] op_sel_hi:[1,0]
	v_add3_u32 v1, v78, v1, s63
	v_bfe_u32 v78, v79, 16, 1
	v_pk_mul_f32 v[80:81], v[60:61], v[80:81]
	v_lshrrev_b32_e32 v1, 16, v1
; __device__ __forceinline__ unsigned pk2(float lo, float hi) { return f2bf(lo) | (f2bf(hi) << 16); }
; template <int MODE> ...
;     ...
; #pragma unroll
;             for (int k = 0; k < 8; ++k) { const f32x4 g = *(const f32x4*)(gpre + k * 256 + lane * 4);
; #pragma unroll
;                 for (int rr = 0; rr < RPW; ++rr) { const f32x4 a = xv[rr][k] * rstd[rr] * g;
;                     v2u o; o.x = pk2(a[0], a[1]); o.y = pk2(a[2], a[3]);
;                     *(v2u*)(h + ((size_t)(k * 4 + (lane >> 4)) * M_TOK + (m + rr)) * 64 + (lane & 15) * 4) = o; } }
	v_add3_u32 v78, v79, v78, s63
	v_and_or_b32 v78, v78, s60, v1
	v_bfe_u32 v1, v80, 16, 1
	v_add3_u32 v1, v80, v1, s63
	v_bfe_u32 v79, v81, 16, 1
	v_pk_mul_f32 v[74:75], v[74:75], v[132:133] op_sel_hi:[1,0]
	v_lshrrev_b32_e32 v1, 16, v1
	v_add3_u32 v79, v81, v79, s63
	v_pk_mul_f32 v[74:75], v[58:59], v[74:75]
	v_and_or_b32 v79, v79, s60, v1
	v_bfe_u32 v1, v74, 16, 1
	v_pk_mul_f32 v[76:77], v[76:77], v[132:133] op_sel_hi:[1,0]
	v_add3_u32 v1, v74, v1, s63
	v_bfe_u32 v74, v75, 16, 1
	v_lshl_add_u64 v[128:129], v[148:149], 0, s[46:47]
	v_pk_mul_f32 v[76:77], v[60:61], v[76:77]
	v_lshrrev_b32_e32 v1, 16, v1
	v_add3_u32 v74, v75, v74, s63
	v_add_co_u32_e32 v134, vcc, s0, v128
	v_and_or_b32 v74, v74, s60, v1
	v_bfe_u32 v1, v76, 16, 1
	v_addc_co_u32_e32 v135, vcc, 0, v129, vcc
	s_mov_b32 s0, 0x5000000
	v_add3_u32 v1, v76, v1, s63
	v_bfe_u32 v75, v77, 16, 1
	v_pk_mul_f32 v[70:71], v[70:71], v[130:131] op_sel_hi:[1,0]
	v_add_co_u32_e32 v120, vcc, s0, v128
	v_lshrrev_b32_e32 v1, 16, v1
	v_add3_u32 v75, v77, v75, s63
	v_pk_mul_f32 v[70:71], v[62:63], v[70:71]
	v_addc_co_u32_e32 v121, vcc, 0, v129, vcc
	s_mov_b32 s0, 0x5800000
	v_and_or_b32 v75, v75, s60, v1
	v_bfe_u32 v1, v70, 16, 1
	v_add_co_u32_e32 v112, vcc, s0, v128
	v_pk_mul_f32 v[72:73], v[72:73], v[130:131] op_sel_hi:[1,0]
	v_add3_u32 v1, v70, v1, s63
	v_bfe_u32 v70, v71, 16, 1
	v_addc_co_u32_e32 v113, vcc, 0, v129, vcc
	s_mov_b32 s0, 0x6000000
	v_pk_mul_f32 v[72:73], v[64:65], v[72:73]
	v_lshrrev_b32_e32 v1, 16, v1
	v_add3_u32 v70, v71, v70, s63
	v_add_co_u32_e32 v104, vcc, s0, v128
	v_and_or_b32 v70, v70, s60, v1
	v_bfe_u32 v1, v72, 16, 1
	v_addc_co_u32_e32 v105, vcc, 0, v129, vcc
	s_mov_b32 s0, 0x6800000
	v_add3_u32 v1, v72, v1, s63
	v_bfe_u32 v71, v73, 16, 1
	v_pk_mul_f32 v[66:67], v[66:67], v[132:133] op_sel_hi:[1,0]
	v_add_co_u32_e32 v96, vcc, s0, v128
	v_lshrrev_b32_e32 v1, 16, v1
	v_add3_u32 v71, v73, v71, s63
	v_pk_mul_f32 v[66:67], v[62:63], v[66:67]
	v_addc_co_u32_e32 v97, vcc, 0, v129, vcc
	s_mov_b32 s0, 0x7000000
	v_and_or_b32 v71, v71, s60, v1
	v_bfe_u32 v1, v66, 16, 1
	v_add_co_u32_e32 v88, vcc, s0, v128
	v_pk_mul_f32 v[68:69], v[68:69], v[132:133] op_sel_hi:[1,0]
	v_add3_u32 v1, v66, v1, s63
	v_bfe_u32 v66, v67, 16, 1
	v_addc_co_u32_e32 v89, vcc, 0, v129, vcc
	s_mov_b32 s0, 0x7800000
	v_pk_mul_f32 v[68:69], v[64:65], v[68:69]
	v_lshrrev_b32_e32 v1, 16, v1
	v_add3_u32 v66, v67, v66, s63
	v_add_co_u32_e32 v80, vcc, s0, v128
	v_and_or_b32 v66, v66, s60, v1
	v_bfe_u32 v1, v68, 16, 1
	v_addc_co_u32_e32 v81, vcc, 0, v129, vcc
	s_brev_b32 s0, 16
	v_add3_u32 v1, v68, v1, s63
	v_bfe_u32 v67, v69, 16, 1
	v_add_co_u32_e32 v72, vcc, s0, v128
	v_lshrrev_b32_e32 v1, 16, v1
	v_add3_u32 v67, v69, v67, s63
	v_addc_co_u32_e32 v73, vcc, 0, v129, vcc
	v_and_or_b32 v67, v67, s60, v1
	v_lshl_add_u64 v[148:149], v[148:149], 0, s[20:21]
	global_store_dwordx2 v[134:135], v[126:127], off
	global_store_dwordx2 v[134:135], v[122:123], off offset:128
	global_store_dwordx2 v[120:121], v[118:119], off
	global_store_dwordx2 v[120:121], v[114:115], off offset:128
	global_store_dwordx2 v[112:113], v[110:111], off
	global_store_dwordx2 v[112:113], v[106:107], off offset:128
	global_store_dwordx2 v[104:105], v[102:103], off
	global_store_dwordx2 v[104:105], v[98:99], off offset:128
	global_store_dwordx2 v[96:97], v[94:95], off
	global_store_dwordx2 v[96:97], v[90:91], off offset:128
	global_store_dwordx2 v[88:89], v[86:87], off
	global_store_dwordx2 v[88:89], v[82:83], off offset:128
	global_store_dwordx2 v[80:81], v[78:79], off
	global_store_dwordx2 v[80:81], v[74:75], off offset:128
	global_store_dwordx2 v[72:73], v[70:71], off
	global_store_dwordx2 v[72:73], v[66:67], off offset:128
	s_cbranch_scc0 .LBB0_225

; __device__ __forceinline__ float bf2f(unsigned h) { return __uint_as_float(h << 16); }
; template <int MODE> ...
;     for (int m = RPW * gw; m < M_TOK; m += RPW * NGW) {
;         f32x4 xv[RPW][8]; v2u yy[RPW][8];
; #pragma unroll
;         for (int rr = 0; rr < RPW; ++rr) {
;             const float* xr = ((MODE == 0 || xin != nullptr) ? xin : xres) + (size_t)(m + rr) * DM + lane * 4;
; #pragma unroll
;             for (int k = 0; k < 8; ++k) xv[rr][k] = *(const f32x4*)(xr + k * 256);
;             if (MODE >= 1) { const bf16_t* yr = y + (size_t)(m + rr) * 256 + lane * 4;
; #pragma unroll
;                 for (int k = 0; k < 8; ++k) yy[rr][k] = *(const v2u*)(yr + (size_t)k * ((size_t)M_TOK * 256)); }
;         }
;         if (MODE >= 1) {
;             float rstd[RPW];
; #pragma unroll
;             for (int rr = 0; rr < RPW; ++rr) { float s = 0.f;
; #pragma unroll
;                 for (int k = 0; k < 8; ++k)
; #pragma unroll
;                     for (int e = 0; e < 2; ++e) { const float a = bf2f(yy[rr][k][e] & 0xffffu), b = bf2f(yy[rr][k][e] >> 16); s += a * a + b * b; }
;                 rstd[rr] = 1.0f / sqrtf(wave_sum(s) * (1.f / DM) + RMS_EPS); }
.LBB0_230:
	v_add_co_u32_e32 v104, vcc, 0xffffe000, v100
	s_add_i32 s30, s30, s6
	s_nop 0
	v_addc_co_u32_e32 v105, vcc, -1, v101, vcc
	v_add_co_u32_e32 v102, vcc, 0xfffff000, v100
	global_load_dwordx4 v[62:65], v[104:105], off
	s_nop 0
	v_addc_co_u32_e32 v103, vcc, -1, v101, vcc
	v_add_co_u32_e32 v116, vcc, 0xfc800000, v98
	global_load_dwordx4 v[58:61], v[102:103], off offset:-3072
	global_load_dwordx4 v[54:57], v[102:103], off offset:-2048
	global_load_dwordx4 v[50:53], v[102:103], off offset:-1024
	global_load_dwordx4 v[46:49], v[100:101], off offset:-4096
	global_load_dwordx4 v[42:45], v[100:101], off offset:-3072
	global_load_dwordx4 v[38:41], v[100:101], off offset:-2048
	global_load_dwordx4 v[34:37], v[100:101], off offset:-1024
	v_addc_co_u32_e32 v117, vcc, -1, v99, vcc
	v_add_co_u32_e32 v124, vcc, 0xfd000000, v98
	global_load_dwordx2 v[122:123], v[116:117], off offset:-512
	s_nop 0
	v_addc_co_u32_e32 v125, vcc, -1, v99, vcc
	global_load_dwordx2 v[120:121], v[124:125], off offset:-512
	v_add_co_u32_e32 v126, vcc, 0xfd800000, v98
	s_cmpk_gt_i32 s30, 0x3fff
	s_nop 0
	v_addc_co_u32_e32 v127, vcc, -1, v99, vcc
	global_load_dwordx2 v[118:119], v[126:127], off offset:-512
	v_add_co_u32_e32 v128, vcc, 0xfe000000, v98
	s_nop 1
	v_addc_co_u32_e32 v129, vcc, -1, v99, vcc
	global_load_dwordx2 v[112:113], v[128:129], off offset:-512
	v_add_co_u32_e32 v130, vcc, 0xfe800000, v98
	s_waitcnt vmcnt(3)
	v_and_b32_e32 v141, 0xffff0000, v123
	v_addc_co_u32_e32 v131, vcc, -1, v99, vcc
	global_load_dwordx2 v[108:109], v[130:131], off offset:-512
	v_add_co_u32_e32 v134, vcc, 0xff000000, v98
	v_lshlrev_b32_e32 v140, 16, v123
	s_nop 0
	v_addc_co_u32_e32 v135, vcc, -1, v99, vcc
	global_load_dwordx2 v[154:155], v[134:135], off offset:-512
	v_add_co_u32_e32 v136, vcc, 0xff800000, v98
	s_waitcnt vmcnt(4)
	v_and_b32_e32 v149, 0xffff0000, v121
	v_addc_co_u32_e32 v137, vcc, -1, v99, vcc
	global_load_dwordx2 v[114:115], v[136:137], off offset:-512
	global_load_dwordx2 v[110:111], v[98:99], off offset:-512
	global_load_dwordx4 v[94:97], v[100:101], off
	global_load_dwordx4 v[90:93], v[100:101], off offset:1024
	global_load_dwordx4 v[86:89], v[100:101], off offset:2048
	global_load_dwordx4 v[82:85], v[100:101], off offset:3072
	v_add_co_u32_e32 v106, vcc, s5, v100
	v_lshlrev_b32_e32 v148, 16, v121
	s_nop 0
	v_addc_co_u32_e32 v107, vcc, 0, v101, vcc
	global_load_dwordx4 v[78:81], v[106:107], off
	global_load_dwordx4 v[74:77], v[106:107], off offset:1024
	global_load_dwordx4 v[70:73], v[106:107], off offset:2048
	global_load_dwordx4 v[66:69], v[106:107], off offset:3072
	global_load_dwordx2 v[156:157], v[116:117], off
	global_load_dwordx2 v[152:153], v[124:125], off
	global_load_dwordx2 v[150:151], v[126:127], off
	global_load_dwordx2 v[142:143], v[128:129], off
	global_load_dwordx2 v[132:133], v[130:131], off
	s_nop 0
	global_load_dwordx2 v[124:125], v[134:135], off
	global_load_dwordx2 v[116:117], v[136:137], off
	global_load_dwordx2 v[146:147], v[98:99], off
	v_and_b32_e32 v131, 0xffff0000, v122
	v_lshlrev_b32_e32 v130, 16, v122
	v_mul_f32_e32 v1, v131, v131
	v_mul_f32_e32 v122, v141, v141
	v_and_b32_e32 v137, 0xffff0000, v120
	v_fmac_f32_e32 v1, v130, v130
	v_fmac_f32_e32 v122, v140, v140
	v_lshlrev_b32_e32 v136, 16, v120
	v_mul_f32_e32 v120, v137, v137
	v_add_f32_e32 v1, v1, v122
	v_fmac_f32_e32 v120, v136, v136
	v_add_f32_e32 v1, v1, v120
	v_mul_f32_e32 v120, v149, v149
	s_waitcnt vmcnt(21)
	v_and_b32_e32 v139, 0xffff0000, v118
	v_fmac_f32_e32 v120, v148, v148
	v_lshlrev_b32_e32 v138, 16, v118
	v_mul_f32_e32 v118, v139, v139
	v_add_f32_e32 v1, v120, v1
	v_fmac_f32_e32 v118, v138, v138
	v_and_b32_e32 v145, 0xffff0000, v119
	v_add_f32_e32 v1, v118, v1
	v_lshlrev_b32_e32 v144, 16, v119
	v_mul_f32_e32 v118, v145, v145
	s_waitcnt vmcnt(20)
	v_and_b32_e32 v129, 0xffff0000, v112
	v_fmac_f32_e32 v118, v144, v144
	v_lshlrev_b32_e32 v128, 16, v112
	v_mul_f32_e32 v112, v129, v129
	v_add_f32_e32 v1, v118, v1
	v_fmac_f32_e32 v112, v128, v128
	v_and_b32_e32 v135, 0xffff0000, v113
	v_add_f32_e32 v1, v112, v1
	v_lshlrev_b32_e32 v134, 16, v113
	v_mul_f32_e32 v112, v135, v135
	v_fmac_f32_e32 v112, v134, v134
	v_add_f32_e32 v1, v112, v1
	v_lshl_add_u64 v[98:99], v[98:99], 0, s[8:9]
	s_waitcnt vmcnt(19)
	v_and_b32_e32 v123, 0xffff0000, v108
	v_lshlrev_b32_e32 v122, 16, v108
	v_mul_f32_e32 v108, v123, v123
	v_fmac_f32_e32 v108, v122, v122
	v_and_b32_e32 v127, 0xffff0000, v109
	v_add_f32_e32 v1, v108, v1
	v_lshlrev_b32_e32 v126, 16, v109
	v_mul_f32_e32 v108, v127, v127
	v_fmac_f32_e32 v108, v126, v126
	s_waitcnt vmcnt(18)
	v_and_b32_e32 v119, 0xffff0000, v154
	v_add_f32_e32 v1, v108, v1
	v_lshlrev_b32_e32 v118, 16, v154
	v_mul_f32_e32 v108, v119, v119
	v_fmac_f32_e32 v108, v118, v118
	v_and_b32_e32 v121, 0xffff0000, v155
	v_add_f32_e32 v1, v108, v1
	v_lshlrev_b32_e32 v120, 16, v155
	v_mul_f32_e32 v108, v121, v121
	v_fmac_f32_e32 v108, v120, v120
	s_waitcnt vmcnt(17)
	v_and_b32_e32 v113, 0xffff0000, v114
	v_add_f32_e32 v1, v108, v1
	v_lshlrev_b32_e32 v112, 16, v114
	v_mul_f32_e32 v108, v113, v113
	v_fmac_f32_e32 v108, v112, v112
	v_lshlrev_b32_e32 v114, 16, v115
	v_and_b32_e32 v115, 0xffff0000, v115
	v_add_f32_e32 v1, v108, v1
	v_mul_f32_e32 v108, v115, v115
	v_fmac_f32_e32 v108, v114, v114
	s_waitcnt vmcnt(16)
	v_and_b32_e32 v109, 0xffff0000, v110
	v_add_f32_e32 v1, v108, v1
	v_lshlrev_b32_e32 v108, 16, v110
	v_mul_f32_e32 v110, v109, v109
	v_fmac_f32_e32 v110, v108, v108
	v_add_f32_e32 v1, v110, v1
	v_lshlrev_b32_e32 v110, 16, v111
	v_and_b32_e32 v111, 0xffff0000, v111
	v_mul_f32_e32 v154, v111, v111
	v_fmac_f32_e32 v154, v110, v110
	v_add_f32_e32 v1, v154, v1
	s_waitcnt vmcnt(6)
; __device__ __forceinline__ float bf2f(unsigned h) { return __uint_as_float(h << 16); }
; template <int MODE> ...
;     ...
;             float rstd[RPW];
; #pragma unroll
;             for (int rr = 0; rr < RPW; ++rr) { float s = 0.f;
; #pragma unroll
;                 for (int k = 0; k < 8; ++k)
; #pragma unroll
;                     for (int e = 0; e < 2; ++e) { const float a = bf2f(yy[rr][k][e] & 0xffffu), b = bf2f(yy[rr][k][e] >> 16); s += a * a + b * b; }
;                 rstd[rr] = 1.0f / sqrtf(wave_sum(s) * (1.f / DM) + RMS_EPS); }
	v_and_b32_e32 v161, 0xffff0000, v152
	s_waitcnt vmcnt(5)
	v_and_b32_e32 v163, 0xffff0000, v150
	v_add_f32_dpp v1, v1, v1 quad_perm:[1,0,3,2] row_mask:0xf bank_mask:0xf bound_ctrl:1
	v_lshlrev_b32_e32 v162, 16, v150
	v_mul_f32_e32 v150, v163, v163
	v_add_f32_dpp v1, v1, v1 quad_perm:[2,3,0,1] row_mask:0xf bank_mask:0xf bound_ctrl:1
	v_fmac_f32_e32 v150, v162, v162
	s_waitcnt vmcnt(4)
	v_and_b32_e32 v165, 0xffff0000, v142
	v_add_f32_dpp v1, v1, v1 row_half_mirror row_mask:0xf bank_mask:0xf bound_ctrl:1
	v_lshlrev_b32_e32 v164, 16, v142
	v_mul_f32_e32 v142, v165, v165
	v_add_f32_dpp v1, v1, v1 row_mirror row_mask:0xf bank_mask:0xf bound_ctrl:1
	v_mov_b32_e32 v154, v1
	s_nop 1
	v_permlane16_swap_b32_e32 v1, v154
	v_add_f32_e32 v1, v1, v154
	v_mov_b32_e32 v154, v1
	s_nop 1
	v_permlane32_swap_b32_e32 v1, v154
	v_add_f32_e32 v1, v1, v154
	v_fmamk_f32 v1, v1, 0x3a000000, v218
	v_cmp_gt_f32_e32 vcc, s14, v1
	v_mul_f32_e32 v154, 0x4f800000, v1
	v_fmac_f32_e32 v142, v164, v164
	v_cndmask_b32_e32 v1, v1, v154, vcc
	v_sqrt_f32_e32 v154, v1
	s_waitcnt vmcnt(3)
	v_and_b32_e32 v167, 0xffff0000, v132
	v_lshlrev_b32_e32 v166, 16, v132
	v_mul_f32_e32 v132, v167, v167
	v_add_u32_e32 v155, -1, v154
	v_fma_f32 v158, -v155, v154, v1
	v_cmp_ge_f32_e64 s[40:41], 0, v158
	v_add_u32_e32 v158, 1, v154
	v_fmac_f32_e32 v132, v166, v166
	v_cndmask_b32_e64 v155, v154, v155, s[40:41]
	v_fma_f32 v154, -v158, v154, v1
	v_cmp_lt_f32_e64 s[40:41], 0, v154
	s_waitcnt vmcnt(2)
	v_and_b32_e32 v169, 0xffff0000, v124
	v_lshlrev_b32_e32 v168, 16, v124
	v_cndmask_b32_e64 v154, v155, v158, s[40:41]
	v_mul_f32_e32 v155, 0x37800000, v154
	v_cndmask_b32_e32 v154, v154, v155, vcc
	v_cmp_class_f32_e32 vcc, v1, v215
	v_mul_f32_e32 v124, v169, v169
	v_fmac_f32_e32 v124, v168, v168
	v_cndmask_b32_e32 v1, v154, v1, vcc
	v_div_scale_f32 v154, s[0:1], v1, v1, 1.0
	v_rcp_f32_e32 v155, v154
	s_waitcnt vmcnt(1)
	v_and_b32_e32 v171, 0xffff0000, v116
	v_lshlrev_b32_e32 v170, 16, v116
	v_mul_f32_e32 v116, v171, v171
	v_fma_f32 v158, -v154, v155, 1.0
	v_fmac_f32_e32 v155, v158, v155
	v_div_scale_f32 v158, vcc, 1.0, v1, 1.0
	v_mul_f32_e32 v159, v158, v155
	v_fma_f32 v160, -v154, v159, v158
	v_fmac_f32_e32 v159, v160, v155
	v_fma_f32 v154, -v154, v159, v158
	v_div_fmas_f32 v154, v154, v155, v159
	v_lshlrev_b32_e32 v158, 16, v156
	v_and_b32_e32 v159, 0xffff0000, v156
	v_lshlrev_b32_e32 v156, 16, v157
	v_and_b32_e32 v157, 0xffff0000, v157
	v_div_fixup_f32 v154, v154, v1, 1.0
	v_mul_f32_e32 v1, v159, v159
	v_mul_f32_e32 v155, v157, v157
	v_fmac_f32_e32 v1, v158, v158
	v_fmac_f32_e32 v155, v156, v156
	v_lshlrev_b32_e32 v160, 16, v152
	v_mul_f32_e32 v152, v161, v161
	v_add_f32_e32 v1, v1, v155
	v_fmac_f32_e32 v152, v160, v160
	v_add_f32_e32 v1, v1, v152
	v_lshlrev_b32_e32 v152, 16, v153
	v_and_b32_e32 v153, 0xffff0000, v153
	v_mul_f32_e32 v155, v153, v153
	v_fmac_f32_e32 v155, v152, v152
	v_add_f32_e32 v1, v155, v1
	v_add_f32_e32 v1, v150, v1
	v_lshlrev_b32_e32 v150, 16, v151
	v_and_b32_e32 v151, 0xffff0000, v151
	v_mul_f32_e32 v155, v151, v151
	v_fmac_f32_e32 v155, v150, v150
	v_add_f32_e32 v1, v155, v1
	v_add_f32_e32 v1, v142, v1
	v_lshlrev_b32_e32 v142, 16, v143
	v_and_b32_e32 v143, 0xffff0000, v143
	v_mul_f32_e32 v155, v143, v143
	v_fmac_f32_e32 v155, v142, v142
	v_add_f32_e32 v1, v155, v1
	v_add_f32_e32 v1, v132, v1
	v_lshlrev_b32_e32 v132, 16, v133
	v_and_b32_e32 v133, 0xffff0000, v133
	v_mul_f32_e32 v155, v133, v133
	v_fmac_f32_e32 v155, v132, v132
	v_add_f32_e32 v1, v155, v1
	v_add_f32_e32 v1, v124, v1
	v_lshlrev_b32_e32 v124, 16, v125
	v_and_b32_e32 v125, 0xffff0000, v125
	v_mul_f32_e32 v155, v125, v125
	v_fmac_f32_e32 v155, v124, v124
	v_add_f32_e32 v1, v155, v1
	v_fmac_f32_e32 v116, v170, v170
	v_and_b32_e32 v173, 0xffff0000, v117
	v_add_f32_e32 v1, v116, v1
	v_lshlrev_b32_e32 v172, 16, v117
	v_mul_f32_e32 v116, v173, v173
	v_fmac_f32_e32 v116, v172, v172
	s_waitcnt vmcnt(0)
; __device__ __forceinline__ float bf2f(unsigned h) { return __uint_as_float(h << 16); }
; template <int MODE> ...
;     ...
;             float rstd[RPW];
; #pragma unroll
;             for (int rr = 0; rr < RPW; ++rr) { float s = 0.f;
; #pragma unroll
;                 for (int k = 0; k < 8; ++k)
; #pragma unroll
;                     for (int e = 0; e < 2; ++e) { const float a = bf2f(yy[rr][k][e] & 0xffffu), b = bf2f(yy[rr][k][e] >> 16); s += a * a + b * b; }
;                 rstd[rr] = 1.0f / sqrtf(wave_sum(s) * (1.f / DM) + RMS_EPS); }
; #pragma unroll
;             for (int k = 0; k < 8; ++k) { const f32x4 g = *(const f32x4*)(gpost + k * 256 + lane * 4);
; #pragma unroll
;                 for (int rr = 0; rr < RPW; ++rr) { f32x4 yv;
;                     yv[0] = bf2f(yy[rr][k][0] & 0xffffu); yv[1] = bf2f(yy[rr][k][0] >> 16); yv[2] = bf2f(yy[rr][k][1] & 0xffffu); yv[3] = bf2f(yy[rr][k][1] >> 16);
;                     xv[rr][k] += yv * rstd[rr] * g; } }
;         }
;         if (MODE != 0)
; #pragma unroll
;         for (int rr = 0; rr < RPW; ++rr) { float* xo = xres + (size_t)(m + rr) * DM + lane * 4;
; #pragma unroll
;             for (int k = 0; k < 8; ++k) *(f32x4*)(xo + k * 256) = xv[rr][k]; }
	v_and_b32_e32 v117, 0xffff0000, v146
	v_add_f32_e32 v1, v116, v1
	v_lshlrev_b32_e32 v116, 16, v146
	v_mul_f32_e32 v146, v117, v117
	v_fmac_f32_e32 v146, v116, v116
	v_add_f32_e32 v1, v146, v1
	v_lshlrev_b32_e32 v146, 16, v147
	v_and_b32_e32 v147, 0xffff0000, v147
	v_mul_f32_e32 v155, v147, v147
	v_fmac_f32_e32 v155, v146, v146
	v_add_f32_e32 v1, v155, v1
	s_nop 1
	v_add_f32_dpp v1, v1, v1 quad_perm:[1,0,3,2] row_mask:0xf bank_mask:0xf bound_ctrl:1
	s_nop 1
	v_add_f32_dpp v1, v1, v1 quad_perm:[2,3,0,1] row_mask:0xf bank_mask:0xf bound_ctrl:1
	s_nop 1
	v_add_f32_dpp v1, v1, v1 row_half_mirror row_mask:0xf bank_mask:0xf bound_ctrl:1
	s_nop 1
	v_add_f32_dpp v1, v1, v1 row_mirror row_mask:0xf bank_mask:0xf bound_ctrl:1
	v_mov_b32_e32 v155, v1
	s_nop 1
	v_permlane16_swap_b32_e32 v1, v155
	v_add_f32_e32 v1, v1, v155
	v_mov_b32_e32 v155, v1
	s_nop 1
	v_permlane32_swap_b32_e32 v1, v155
	v_add_f32_e32 v1, v1, v155
	v_fmamk_f32 v1, v1, 0x3a000000, v218
	v_cmp_gt_f32_e32 vcc, s14, v1
	v_mul_f32_e32 v155, 0x4f800000, v1
	s_nop 0
	v_cndmask_b32_e32 v1, v1, v155, vcc
	v_sqrt_f32_e32 v155, v1
	s_nop 0
	v_add_u32_e32 v174, -1, v155
	v_fma_f32 v175, -v174, v155, v1
	v_cmp_ge_f32_e64 s[40:41], 0, v175
	v_add_u32_e32 v175, 1, v155
	s_nop 0
	v_cndmask_b32_e64 v174, v155, v174, s[40:41]
	v_fma_f32 v155, -v175, v155, v1
	v_cmp_lt_f32_e64 s[40:41], 0, v155
	s_nop 1
	v_cndmask_b32_e64 v155, v174, v175, s[40:41]
	v_mul_f32_e32 v174, 0x37800000, v155
	v_cndmask_b32_e32 v155, v155, v174, vcc
	v_cmp_class_f32_e32 vcc, v1, v215
	s_nop 1
	v_cndmask_b32_e32 v1, v155, v1, vcc
	v_div_scale_f32 v155, s[0:1], v1, v1, 1.0
	v_rcp_f32_e32 v174, v155
	s_nop 0
	v_fma_f32 v175, -v155, v174, 1.0
	v_fmac_f32_e32 v174, v175, v174
	v_div_scale_f32 v175, vcc, 1.0, v1, 1.0
	v_mul_f32_e32 v176, v175, v174
	v_fma_f32 v177, -v155, v176, v175
	v_fmac_f32_e32 v176, v177, v174
	v_fma_f32 v155, -v155, v176, v175
	v_div_fmas_f32 v155, v155, v174, v176
	v_div_fixup_f32 v174, v155, v1, 1.0
	v_pk_mul_f32 v[130:131], v[154:155], v[130:131] op_sel_hi:[0,1]
	v_pk_fma_f32 v[62:63], v[2:3], v[130:131], v[62:63]
	v_pk_mul_f32 v[130:131], v[174:175], v[158:159] op_sel_hi:[0,1]
	v_pk_fma_f32 v[94:95], v[2:3], v[130:131], v[94:95]
	v_pk_mul_f32 v[130:131], v[154:155], v[136:137] op_sel_hi:[0,1]
	v_pk_fma_f32 v[58:59], v[6:7], v[130:131], v[58:59]
	v_pk_mul_f32 v[130:131], v[174:175], v[160:161] op_sel_hi:[0,1]
	v_pk_mul_f32 v[136:137], v[154:155], v[148:149] op_sel_hi:[0,1]
	v_pk_fma_f32 v[90:91], v[6:7], v[130:131], v[90:91]
	v_pk_mul_f32 v[130:131], v[154:155], v[138:139] op_sel_hi:[0,1]
	v_pk_fma_f32 v[60:61], v[8:9], v[136:137], v[60:61]
	v_pk_mul_f32 v[136:137], v[174:175], v[152:153] op_sel_hi:[0,1]
	v_pk_fma_f32 v[54:55], v[10:11], v[130:131], v[54:55]
	v_pk_mul_f32 v[130:131], v[174:175], v[162:163] op_sel_hi:[0,1]
	v_pk_mul_f32 v[140:141], v[154:155], v[140:141] op_sel_hi:[0,1]
	v_pk_fma_f32 v[92:93], v[8:9], v[136:137], v[92:93]
	v_pk_mul_f32 v[136:137], v[154:155], v[144:145] op_sel_hi:[0,1]
	v_pk_fma_f32 v[86:87], v[10:11], v[130:131], v[86:87]
	v_pk_mul_f32 v[128:129], v[154:155], v[128:129] op_sel_hi:[0,1]
	v_pk_mul_f32 v[130:131], v[154:155], v[134:135] op_sel_hi:[0,1]
	v_pk_mul_f32 v[122:123], v[154:155], v[122:123] op_sel_hi:[0,1]
	v_pk_mul_f32 v[126:127], v[154:155], v[126:127] op_sel_hi:[0,1]
	v_pk_mul_f32 v[118:119], v[154:155], v[118:119] op_sel_hi:[0,1]
	v_pk_mul_f32 v[120:121], v[154:155], v[120:121] op_sel_hi:[0,1]
	v_pk_mul_f32 v[112:113], v[154:155], v[112:113] op_sel_hi:[0,1]
	v_pk_mul_f32 v[114:115], v[154:155], v[114:115] op_sel_hi:[0,1]
	v_pk_mul_f32 v[108:109], v[154:155], v[108:109] op_sel_hi:[0,1]
	v_pk_mul_f32 v[110:111], v[154:155], v[110:111] op_sel_hi:[0,1]
	v_pk_fma_f32 v[64:65], v[4:5], v[140:141], v[64:65]
	v_pk_mul_f32 v[140:141], v[174:175], v[156:157] op_sel_hi:[0,1]
	v_pk_fma_f32 v[56:57], v[12:13], v[136:137], v[56:57]
	v_pk_mul_f32 v[136:137], v[174:175], v[150:151] op_sel_hi:[0,1]
	v_pk_fma_f32 v[52:53], v[16:17], v[130:131], v[52:53]
	v_pk_fma_f32 v[50:51], v[14:15], v[128:129], v[50:51]
	v_pk_mul_f32 v[128:129], v[174:175], v[164:165] op_sel_hi:[0,1]
	v_pk_mul_f32 v[130:131], v[174:175], v[142:143] op_sel_hi:[0,1]
	v_pk_fma_f32 v[48:49], v[20:21], v[126:127], v[48:49]
	v_pk_fma_f32 v[46:47], v[18:19], v[122:123], v[46:47]
	v_pk_mul_f32 v[122:123], v[174:175], v[166:167] op_sel_hi:[0,1]
	v_pk_mul_f32 v[126:127], v[174:175], v[132:133] op_sel_hi:[0,1]
	v_pk_fma_f32 v[44:45], v[24:25], v[120:121], v[44:45]
	v_pk_fma_f32 v[42:43], v[22:23], v[118:119], v[42:43]
	v_pk_mul_f32 v[118:119], v[174:175], v[168:169] op_sel_hi:[0,1]
	v_pk_mul_f32 v[120:121], v[174:175], v[124:125] op_sel_hi:[0,1]
	v_pk_fma_f32 v[40:41], v[28:29], v[114:115], v[40:41]
	v_pk_fma_f32 v[38:39], v[26:27], v[112:113], v[38:39]
	v_pk_mul_f32 v[112:113], v[174:175], v[170:171] op_sel_hi:[0,1]
	v_pk_mul_f32 v[114:115], v[174:175], v[172:173] op_sel_hi:[0,1]
	v_pk_fma_f32 v[36:37], v[32:33], v[110:111], v[36:37]
	v_pk_fma_f32 v[34:35], v[30:31], v[108:109], v[34:35]
	v_pk_mul_f32 v[108:109], v[174:175], v[116:117] op_sel_hi:[0,1]
	v_pk_mul_f32 v[110:111], v[174:175], v[146:147] op_sel_hi:[0,1]
	v_pk_fma_f32 v[96:97], v[4:5], v[140:141], v[96:97]
	v_pk_fma_f32 v[88:89], v[12:13], v[136:137], v[88:89]
	v_pk_fma_f32 v[84:85], v[16:17], v[130:131], v[84:85]
	v_pk_fma_f32 v[82:83], v[14:15], v[128:129], v[82:83]
	v_pk_fma_f32 v[80:81], v[20:21], v[126:127], v[80:81]
	v_pk_fma_f32 v[78:79], v[18:19], v[122:123], v[78:79]
	v_pk_fma_f32 v[76:77], v[24:25], v[120:121], v[76:77]
	v_pk_fma_f32 v[74:75], v[22:23], v[118:119], v[74:75]
	v_pk_fma_f32 v[72:73], v[28:29], v[114:115], v[72:73]
	v_pk_fma_f32 v[70:71], v[26:27], v[112:113], v[70:71]
	v_pk_fma_f32 v[68:69], v[32:33], v[110:111], v[68:69]
	v_pk_fma_f32 v[66:67], v[30:31], v[108:109], v[66:67]
	global_store_dwordx4 v[104:105], v[62:65], off sc0 sc1
	global_store_dwordx4 v[102:103], v[58:61], off offset:-3072 sc0 sc1
	global_store_dwordx4 v[102:103], v[54:57], off offset:-2048 sc0 sc1
	global_store_dwordx4 v[102:103], v[50:53], off offset:-1024 sc0 sc1
	global_store_dwordx4 v[100:101], v[46:49], off offset:-4096 sc0 sc1
	global_store_dwordx4 v[100:101], v[42:45], off offset:-3072 sc0 sc1
	global_store_dwordx4 v[100:101], v[38:41], off offset:-2048 sc0 sc1
	global_store_dwordx4 v[100:101], v[34:37], off offset:-1024 sc0 sc1
	global_store_dwordx4 v[100:101], v[94:97], off sc0 sc1
	global_store_dwordx4 v[100:101], v[90:93], off offset:1024 sc0 sc1
	global_store_dwordx4 v[100:101], v[86:89], off offset:2048 sc0 sc1
	global_store_dwordx4 v[100:101], v[82:85], off offset:3072 sc0 sc1
	global_store_dwordx4 v[106:107], v[78:81], off sc0 sc1
	global_store_dwordx4 v[106:107], v[74:77], off offset:1024 sc0 sc1
	global_store_dwordx4 v[106:107], v[70:73], off offset:2048 sc0 sc1
	global_store_dwordx4 v[106:107], v[66:69], off offset:3072 sc0 sc1
	v_lshl_add_u64 v[100:101], v[100:101], 0, s[12:13]
	s_cbranch_scc0 .LBB0_230

; __device__ __forceinline__ unsigned cvt_pk_bf16(float lo, float hi) { unsigned r; asm volatile("v_cvt_pk_bf16_f32 %0, %1, %2" : "=v"(r) : "v"(lo), "v"(hi)); return r; }
;     __device__ __forceinline__ void operator()(const f32x4 (&acc)[2][2][4][2], const Unit& u, int wr, int wc, int fr, int fq) const {
;     ...
;         for (int ai = 0; ai < 2; ++ai)
; #pragma unroll
;             for (int m = 0; m < 4; ++m) { bf16_t* rowp = base + (size_t)(row0 + ai * HALF + m * 16) * ldc + col0;
; #pragma unroll
;                 for (int bj = 0; bj < 2; ++bj) { f32x4 v0 = acc[ai][bj][m][0] + bv[bj][0], v1 = acc[ai][bj][m][1] + bv[bj][1];
;                     if (ACT == 1) { f32x2 a = gelu_pk((f32x2){v0[0], v0[1]}), b = gelu_pk((f32x2){v0[2], v0[3]}), c = gelu_pk((f32x2){v1[0], v1[1]}), d = gelu_pk((f32x2){v1[2], v1[3]});
;                         v0 = (f32x4){a.x, a.y, b.x, b.y}; v1 = (f32x4){c.x, c.y, d.x, d.y}; }
;                     v0 = v0 * sc; v1 = v1 * sc; u32x4 w; w.x = cvt_pk_bf16(v0[0], v0[1]); w.y = cvt_pk_bf16(v0[2], v0[3]); w.z = cvt_pk_bf16(v1[0], v1[1]); w.w = cvt_pk_bf16(v1[2], v1[3]);
;                     *(u32x4*)(rowp + bj * HALF) = w; } }
.LBB0_377:
	s_ashr_i32 s69, s68, 31
	s_lshl_b32 s12, s68, 8
	s_lshl_b64 s[6:7], s[68:69], 23
	s_and_b64 s[8:9], s[98:99], exec
	s_cselect_b32 s6, 0, s6
	s_cselect_b32 s7, 0, s7
	s_add_u32 s6, s30, s6
	s_addc_u32 s7, s31, s7
	s_and_b64 s[8:9], s[98:99], exec
	s_cselect_b32 s8, s12, 0
	v_lshl_add_u32 v147, s44, 8, v1
	v_or_b32_e32 v142, s8, v145
	v_ashrrev_i32_e32 v143, 31, v142
	v_ashrrev_i32_e32 v148, 31, v147
	v_lshl_add_u64 v[142:143], v[142:143], 1, s[6:7]
	v_mul_lo_u32 v152, s57, v148
	v_mad_u64_u32 v[148:149], s[6:7], s57, v147, 0
	v_add_u32_e32 v149, v149, v152
	v_lshl_add_u64 v[148:149], v[148:149], 1, v[142:143]
	v_pk_add_f32 v[128:129], v[128:129], 0 op_sel_hi:[1,0]
	v_pk_add_f32 v[126:127], v[126:127], 0 op_sel_hi:[1,0]
	v_pk_add_f32 v[150:151], v[124:125], 0 op_sel_hi:[1,0]
	v_pk_add_f32 v[124:125], v[122:123], 0 op_sel_hi:[1,0]
	v_cvt_pk_bf16_f32 v122, v126, v127
	v_cvt_pk_bf16_f32 v123, v128, v129
	v_pk_add_f32 v[118:119], v[118:119], 0 op_sel_hi:[1,0]
	v_cvt_pk_bf16_f32 v124, v124, v125
	v_cvt_pk_bf16_f32 v125, v150, v151
	global_store_dwordx4 v[148:149], v[122:125], off sc0 sc1
	v_pk_add_f32 v[120:121], v[120:121], 0 op_sel_hi:[1,0]
	v_pk_add_f32 v[114:115], v[114:115], 0 op_sel_hi:[1,0]
	v_pk_add_f32 v[122:123], v[112:113], 0 op_sel_hi:[1,0]
	v_pk_add_f32 v[112:113], v[110:111], 0 op_sel_hi:[1,0]
	v_cvt_pk_bf16_f32 v110, v118, v119
	v_cvt_pk_bf16_f32 v111, v120, v121
	v_pk_add_f32 v[102:103], v[102:103], 0 op_sel_hi:[1,0]
	v_cvt_pk_bf16_f32 v112, v112, v113
	v_cvt_pk_bf16_f32 v113, v122, v123
	global_store_dwordx4 v[148:149], v[110:113], off offset:256 sc0 sc1
	v_pk_add_f32 v[104:105], v[104:105], 0 op_sel_hi:[1,0]
	v_pk_add_f32 v[98:99], v[98:99], 0 op_sel_hi:[1,0]
	v_or_b32_e32 v110, 16, v147
	v_mad_u64_u32 v[110:111], s[6:7], s57, v110, 0
	v_add_u32_e32 v111, v111, v152
	v_lshl_add_u64 v[110:111], v[110:111], 1, v[142:143]
	v_pk_add_f32 v[112:113], v[116:117], 0 op_sel_hi:[1,0]
	v_pk_add_f32 v[116:117], v[108:109], 0 op_sel_hi:[1,0]
	v_pk_add_f32 v[108:109], v[106:107], 0 op_sel_hi:[1,0]
	v_cvt_pk_bf16_f32 v106, v114, v115
	v_cvt_pk_bf16_f32 v107, v112, v113
	v_pk_add_f32 v[86:87], v[86:87], 0 op_sel_hi:[1,0]
	v_cvt_pk_bf16_f32 v108, v108, v109
	v_cvt_pk_bf16_f32 v109, v116, v117
	global_store_dwordx4 v[110:111], v[106:109], off sc0 sc1
	v_pk_add_f32 v[88:89], v[88:89], 0 op_sel_hi:[1,0]
	v_pk_add_f32 v[82:83], v[82:83], 0 op_sel_hi:[1,0]
	v_pk_add_f32 v[106:107], v[96:97], 0 op_sel_hi:[1,0]
	v_pk_add_f32 v[96:97], v[94:95], 0 op_sel_hi:[1,0]
	v_cvt_pk_bf16_f32 v94, v102, v103
	v_cvt_pk_bf16_f32 v95, v104, v105
	v_pk_add_f32 v[70:71], v[70:71], 0 op_sel_hi:[1,0]
	v_cvt_pk_bf16_f32 v96, v96, v97
	v_cvt_pk_bf16_f32 v97, v106, v107
	global_store_dwordx4 v[110:111], v[94:97], off offset:256 sc0 sc1
	v_pk_add_f32 v[72:73], v[72:73], 0 op_sel_hi:[1,0]
	v_pk_add_f32 v[64:65], v[64:65], 0 op_sel_hi:[1,0]
	v_or_b32_e32 v94, 32, v147
	v_mad_u64_u32 v[94:95], s[6:7], s57, v94, 0
	v_add_u32_e32 v95, v95, v152
	v_lshl_add_u64 v[94:95], v[94:95], 1, v[142:143]
	v_pk_add_f32 v[96:97], v[100:101], 0 op_sel_hi:[1,0]
	v_pk_add_f32 v[100:101], v[92:93], 0 op_sel_hi:[1,0]
	v_pk_add_f32 v[92:93], v[90:91], 0 op_sel_hi:[1,0]
	v_cvt_pk_bf16_f32 v90, v98, v99
	v_cvt_pk_bf16_f32 v91, v96, v97
	v_pk_add_f32 v[62:63], v[62:63], 0 op_sel_hi:[1,0]
	v_cvt_pk_bf16_f32 v92, v92, v93
	v_cvt_pk_bf16_f32 v93, v100, v101
	global_store_dwordx4 v[94:95], v[90:93], off sc0 sc1
	v_pk_add_f32 v[54:55], v[54:55], 0 op_sel_hi:[1,0]
	v_pk_add_f32 v[56:57], v[56:57], 0 op_sel_hi:[1,0]
	v_pk_add_f32 v[90:91], v[80:81], 0 op_sel_hi:[1,0]
	v_pk_add_f32 v[80:81], v[78:79], 0 op_sel_hi:[1,0]
	v_cvt_pk_bf16_f32 v78, v86, v87
	v_cvt_pk_bf16_f32 v79, v88, v89
	v_pk_add_f32 v[48:49], v[48:49], 0 op_sel_hi:[1,0]
	v_cvt_pk_bf16_f32 v80, v80, v81
	v_cvt_pk_bf16_f32 v81, v90, v91
	global_store_dwordx4 v[94:95], v[78:81], off offset:256 sc0 sc1
	v_pk_add_f32 v[46:47], v[46:47], 0 op_sel_hi:[1,0]
	v_pk_add_f32 v[38:39], v[38:39], 0 op_sel_hi:[1,0]
	v_or_b32_e32 v78, 48, v147
	v_mad_u64_u32 v[78:79], s[6:7], s57, v78, 0
	v_add_u32_e32 v79, v79, v152
	v_lshl_add_u64 v[78:79], v[78:79], 1, v[142:143]
	v_pk_add_f32 v[80:81], v[84:85], 0 op_sel_hi:[1,0]
	v_pk_add_f32 v[84:85], v[76:77], 0 op_sel_hi:[1,0]
	v_pk_add_f32 v[76:77], v[74:75], 0 op_sel_hi:[1,0]
	v_cvt_pk_bf16_f32 v74, v82, v83
	v_cvt_pk_bf16_f32 v75, v80, v81
	v_pk_add_f32 v[40:41], v[40:41], 0 op_sel_hi:[1,0]
	v_cvt_pk_bf16_f32 v76, v76, v77
; __device__ __forceinline__ unsigned cvt_pk_bf16(float lo, float hi) { unsigned r; asm volatile("v_cvt_pk_bf16_f32 %0, %1, %2" : "=v"(r) : "v"(lo), "v"(hi)); return r; }
; #define PG8_BAR __builtin_amdgcn_s_barrier()
;     __device__ __forceinline__ void operator()(const f32x4 (&acc)[2][2][4][2], const Unit& u, int wr, int wc, int fr, int fq) const {
;     ...
;         for (int ai = 0; ai < 2; ++ai)
; #pragma unroll
;             for (int m = 0; m < 4; ++m) { bf16_t* rowp = base + (size_t)(row0 + ai * HALF + m * 16) * ldc + col0;
; #pragma unroll
;                 for (int bj = 0; bj < 2; ++bj) { f32x4 v0 = acc[ai][bj][m][0] + bv[bj][0], v1 = acc[ai][bj][m][1] + bv[bj][1];
;                     if (ACT == 1) { f32x2 a = gelu_pk((f32x2){v0[0], v0[1]}), b = gelu_pk((f32x2){v0[2], v0[3]}), c = gelu_pk((f32x2){v1[0], v1[1]}), d = gelu_pk((f32x2){v1[2], v1[3]});
;                         v0 = (f32x4){a.x, a.y, b.x, b.y}; v1 = (f32x4){c.x, c.y, d.x, d.y}; }
;                     v0 = v0 * sc; v1 = v1 * sc; u32x4 w; w.x = cvt_pk_bf16(v0[0], v0[1]); w.y = cvt_pk_bf16(v0[2], v0[3]); w.z = cvt_pk_bf16(v1[0], v1[1]); w.w = cvt_pk_bf16(v1[2], v1[3]);
;                     *(u32x4*)(rowp + bj * HALF) = w; } }
; template <class Epi, class Sched, bool ALIGN_EPI = false, bool SP2 = false>
; __device__ __forceinline__ void gemm_phase(PG8_LAS unsigned char* lds, const Gemm g, const Sched& S, const Epi& E) {
;     ...
;         if constexpr (ALIGN_EPI) { if (wr == 0) PG8_BAR; }
;         if constexpr (!Epi::AFTER_DRAIN) { E(acc, cur, wr, wc, fr, fq); S.done(cur); }
;         if (!has_next) break;
; #pragma unroll
;         for (int a = 0; a < 2; ++a)
; #pragma unroll
;             for (int b = 0; b < 2; ++b)
; #pragma unroll
;                 for (int m = 0; m < 4; ++m)
; #pragma unroll
;                     for (int n = 0; n < 2; ++n) acc[a][b][m][n] = (f32x4){0.f, 0.f, 0.f, 0.f};
;         cur = nxt; cA = nA; cB = nB; ++ui;
;         if constexpr (ALIGN_EPI) { if (wr == 1) PG8_BAR; }
	v_cvt_pk_bf16_f32 v77, v84, v85
	global_store_dwordx4 v[78:79], v[74:77], off sc0 sc1
	v_pk_add_f32 v[32:33], v[32:33], 0 op_sel_hi:[1,0]
	v_pk_add_f32 v[30:31], v[30:31], 0 op_sel_hi:[1,0]
	v_pk_add_f32 v[74:75], v[68:69], 0 op_sel_hi:[1,0]
	v_pk_add_f32 v[68:69], v[66:67], 0 op_sel_hi:[1,0]
	v_cvt_pk_bf16_f32 v66, v70, v71
	v_cvt_pk_bf16_f32 v67, v72, v73
	v_pk_add_f32 v[22:23], v[22:23], 0 op_sel_hi:[1,0]
	v_cvt_pk_bf16_f32 v68, v68, v69
	v_cvt_pk_bf16_f32 v69, v74, v75
	global_store_dwordx4 v[78:79], v[66:69], off offset:256 sc0 sc1
	v_pk_add_f32 v[24:25], v[24:25], 0 op_sel_hi:[1,0]
	v_pk_add_f32 v[16:17], v[16:17], 0 op_sel_hi:[1,0]
	v_add_u32_e32 v66, 0x80, v147
	v_ashrrev_i32_e32 v69, 31, v66
	v_mad_u64_u32 v[66:67], s[6:7], s57, v66, 0
	v_mov_b32_e32 v68, v67
	v_mad_u64_u32 v[68:69], s[6:7], s57, v69, v[68:69]
	v_mov_b32_e32 v67, v68
	v_lshl_add_u64 v[66:67], v[66:67], 1, v[142:143]
	v_pk_add_f32 v[68:69], v[60:61], 0 op_sel_hi:[1,0]
	v_pk_add_f32 v[60:61], v[58:59], 0 op_sel_hi:[1,0]
	v_cvt_pk_bf16_f32 v58, v62, v63
	v_cvt_pk_bf16_f32 v59, v64, v65
	v_pk_add_f32 v[14:15], v[14:15], 0 op_sel_hi:[1,0]
	v_cvt_pk_bf16_f32 v60, v60, v61
	v_cvt_pk_bf16_f32 v61, v68, v69
	global_store_dwordx4 v[66:67], v[58:61], off sc0 sc1
	s_andn2_b64 vcc, exec, s[40:41]
	v_pk_add_f32 v[8:9], v[8:9], 0 op_sel_hi:[1,0]
	v_pk_add_f32 v[58:59], v[52:53], 0 op_sel_hi:[1,0]
	v_pk_add_f32 v[52:53], v[50:51], 0 op_sel_hi:[1,0]
	v_cvt_pk_bf16_f32 v50, v54, v55
	v_cvt_pk_bf16_f32 v51, v56, v57
	v_pk_add_f32 v[6:7], v[6:7], 0 op_sel_hi:[1,0]
	v_cvt_pk_bf16_f32 v52, v52, v53
	v_cvt_pk_bf16_f32 v53, v58, v59
	global_store_dwordx4 v[66:67], v[50:53], off offset:256 sc0 sc1
	s_nop 1
	v_add_u32_e32 v50, 0x90, v147
	v_ashrrev_i32_e32 v53, 31, v50
	v_mad_u64_u32 v[50:51], s[6:7], s57, v50, 0
	v_mov_b32_e32 v52, v51
	v_mad_u64_u32 v[52:53], s[6:7], s57, v53, v[52:53]
	v_mov_b32_e32 v51, v52
	v_lshl_add_u64 v[50:51], v[50:51], 1, v[142:143]
	v_pk_add_f32 v[52:53], v[44:45], 0 op_sel_hi:[1,0]
	v_pk_add_f32 v[44:45], v[42:43], 0 op_sel_hi:[1,0]
	v_cvt_pk_bf16_f32 v42, v46, v47
	v_cvt_pk_bf16_f32 v43, v48, v49
	s_nop 0
	v_cvt_pk_bf16_f32 v44, v44, v45
	v_cvt_pk_bf16_f32 v45, v52, v53
	global_store_dwordx4 v[50:51], v[42:45], off sc0 sc1
	s_nop 1
	v_pk_add_f32 v[42:43], v[36:37], 0 op_sel_hi:[1,0]
	v_pk_add_f32 v[36:37], v[34:35], 0 op_sel_hi:[1,0]
	v_cvt_pk_bf16_f32 v34, v38, v39
	v_cvt_pk_bf16_f32 v35, v40, v41
	s_nop 0
	v_cvt_pk_bf16_f32 v36, v36, v37
	v_cvt_pk_bf16_f32 v37, v42, v43
	global_store_dwordx4 v[50:51], v[34:37], off offset:256 sc0 sc1
	s_nop 1
	v_add_u32_e32 v34, 0xa0, v147
	v_ashrrev_i32_e32 v37, 31, v34
	v_mad_u64_u32 v[34:35], s[6:7], s57, v34, 0
	v_mov_b32_e32 v36, v35
	v_mad_u64_u32 v[36:37], s[6:7], s57, v37, v[36:37]
	v_mov_b32_e32 v35, v36
	v_lshl_add_u64 v[34:35], v[34:35], 1, v[142:143]
	v_pk_add_f32 v[36:37], v[28:29], 0 op_sel_hi:[1,0]
	v_pk_add_f32 v[28:29], v[26:27], 0 op_sel_hi:[1,0]
	v_cvt_pk_bf16_f32 v26, v30, v31
	v_cvt_pk_bf16_f32 v27, v32, v33
	s_nop 0
	v_cvt_pk_bf16_f32 v28, v28, v29
	v_cvt_pk_bf16_f32 v29, v36, v37
	global_store_dwordx4 v[34:35], v[26:29], off sc0 sc1
	s_nop 1
	v_pk_add_f32 v[26:27], v[20:21], 0 op_sel_hi:[1,0]
	v_pk_add_f32 v[20:21], v[18:19], 0 op_sel_hi:[1,0]
	v_cvt_pk_bf16_f32 v18, v22, v23
	v_cvt_pk_bf16_f32 v19, v24, v25
	s_nop 0
	v_cvt_pk_bf16_f32 v20, v20, v21
	v_cvt_pk_bf16_f32 v21, v26, v27
	global_store_dwordx4 v[34:35], v[18:21], off offset:256 sc0 sc1
	s_nop 1
	v_add_u32_e32 v18, 0xb0, v147
	v_ashrrev_i32_e32 v21, 31, v18
	v_mad_u64_u32 v[18:19], s[6:7], s57, v18, 0
	v_mov_b32_e32 v20, v19
	v_mad_u64_u32 v[20:21], s[6:7], s57, v21, v[20:21]
	v_mov_b32_e32 v19, v20
	v_lshl_add_u64 v[18:19], v[18:19], 1, v[142:143]
	v_pk_add_f32 v[20:21], v[12:13], 0 op_sel_hi:[1,0]
	v_pk_add_f32 v[12:13], v[10:11], 0 op_sel_hi:[1,0]
	v_cvt_pk_bf16_f32 v10, v14, v15
	v_cvt_pk_bf16_f32 v11, v16, v17
	s_mov_b64 s[6:7], -1
	v_cvt_pk_bf16_f32 v12, v12, v13
	v_cvt_pk_bf16_f32 v13, v20, v21
	global_store_dwordx4 v[18:19], v[10:13], off sc0 sc1
	s_nop 1
	v_pk_add_f32 v[10:11], v[4:5], 0 op_sel_hi:[1,0]
	v_pk_add_f32 v[4:5], v[2:3], 0 op_sel_hi:[1,0]
	v_cvt_pk_bf16_f32 v2, v6, v7
	v_cvt_pk_bf16_f32 v3, v8, v9
	s_nop 0
	v_cvt_pk_bf16_f32 v4, v4, v5
	v_cvt_pk_bf16_f32 v5, v10, v11
	global_store_dwordx4 v[18:19], v[2:5], off offset:256 sc0 sc1
	s_cbranch_vccnz .LBB0_368
	s_andn2_b64 vcc, exec, s[84:85]
	s_cbranch_vccnz .LBB0_367
	s_barrier
	s_branch .LBB0_367

; #define LAS __attribute__((address_space(3)))
; __device__ __forceinline__ unsigned pk2(float lo, float hi) { return f2bf(lo) | (f2bf(hi) << 16); }
; #define LDS_WAIT() asm volatile("s_waitcnt lgkmcnt(0)" ::: "memory")
; __device__ __forceinline__ void wt_item(const float* __restrict__ W, int ldw, int K, int src_c0, bf16_t* __restrict__ WT, int dst_r0, int k0, LAS float* scr, int lane, int Ndst) {
; #pragma unroll 32
;     for (int i = 0; i < 32; ++i) { const int kk = 2 * i + (lane >> 5); scr[kk * 33 + (lane & 31)] = (src_c0 >= 0) ? W[(size_t)(k0 + kk) * ldw + src_c0 + (lane & 31)] : 0.f; }
;     LDS_WAIT(); asm volatile("" ::: "memory");
;     const int c = lane & 7;
; #pragma unroll
;     for (int j = 0; j < 4; ++j) { const int n = (lane >> 3) + 8 * j; const LAS float* s = scr + (8 * c) * 33 + n;
;         v4u o; o.x = pk2(s[0 * 33], s[1 * 33]); o.y = pk2(s[2 * 33], s[3 * 33]); o.z = pk2(s[4 * 33], s[5 * 33]); o.w = pk2(s[6 * 33], s[7 * 33]);
;         *(v4u*)(WT + ((size_t)(k0 >> 6) * Ndst + dst_r0 + n) * 64 + 8 * c) = o; }
;     LDS_WAIT(); asm volatile("" ::: "memory");
; }
; __device__ __forceinline__ void conv_generic(const float* W, int ldw, int K, int Ndst, bool win_map, bf16_t* WT, LAS float* scr, int gw, int NGW, int lane) {
;     const int nblk = Ndst / 32, items = (K / 64) * nblk;
;     for (int it = gw; it < items; it += NGW) { const int kb = it / nblk, nb = it % nblk; int src = nb * 32;
;         if (win_map) src = nb < 32 ? nb * 32 : nb < 96 ? 1088 + (nb - 32) * 32 : nb < 98 ? 1024 + (nb - 96) * 32 : -1;
;         wt_item(W, ldw, K, src, WT, nb * 32, kb * 64, scr, lane, Ndst); }
; }
.LBB0_409:
	v_add_u32_e32 v13, 0x1400, v50
	s_waitcnt vmcnt(2)
	ds_write2_b32 v13, v11, v51 offset0:40 offset1:106
	s_waitcnt vmcnt(0)
	ds_write2_b32 v13, v52, v53 offset0:172 offset1:238
	s_waitcnt lgkmcnt(0)
	ds_read2_b32 v[18:19], v47 offset1:8
	ds_read2_b32 v[56:57], v47 offset0:33 offset1:41
	ds_read2_b32 v[58:59], v47 offset0:66 offset1:74
	ds_read2_b32 v[60:61], v47 offset0:99 offset1:107
	ds_read2_b32 v[62:63], v47 offset0:132 offset1:140
	s_waitcnt lgkmcnt(4)
	v_bfe_u32 v11, v18, 16, 1
	v_add3_u32 v11, v18, v11, s63
	s_waitcnt lgkmcnt(3)
	v_bfe_u32 v13, v56, 16, 1
	v_lshrrev_b32_e32 v11, 16, v11
	v_add3_u32 v13, v56, v13, s63
	ds_read2_b32 v[64:65], v47 offset0:165 offset1:173
	v_and_or_b32 v52, v13, s60, v11
	s_waitcnt lgkmcnt(3)
	v_bfe_u32 v11, v58, 16, 1
	v_add3_u32 v11, v58, v11, s63
	s_waitcnt lgkmcnt(2)
	v_bfe_u32 v13, v60, 16, 1
	ds_read2_b32 v[66:67], v47 offset0:198 offset1:206
	v_lshrrev_b32_e32 v11, 16, v11
	v_add3_u32 v13, v60, v13, s63
	ds_read2_b32 v[68:69], v47 offset0:231 offset1:239
	v_and_or_b32 v53, v13, s60, v11
	s_waitcnt lgkmcnt(3)
	v_bfe_u32 v11, v62, 16, 1
	s_ashr_i32 s0, s22, 31
	v_add3_u32 v11, v62, v11, s63
	s_waitcnt lgkmcnt(2)
	v_bfe_u32 v13, v64, 16, 1
	s_mul_hi_u32 s1, s22, s14
	s_mul_i32 s0, s0, s14
	v_lshrrev_b32_e32 v11, 16, v11
	v_add3_u32 v13, v64, v13, s63
	s_add_i32 s1, s1, s0
	s_mul_i32 s22, s22, s14
	s_ashr_i32 s0, s21, 31
	v_and_or_b32 v54, v13, s60, v11
	s_waitcnt lgkmcnt(1)
	v_bfe_u32 v11, v66, 16, 1
	s_add_u32 s5, s22, s21
	v_add3_u32 v11, v66, v11, s63
	s_waitcnt lgkmcnt(0)
	v_bfe_u32 v13, v68, 16, 1
	s_addc_u32 s0, s1, s0
	v_lshrrev_b32_e32 v11, 16, v11
	v_add3_u32 v13, v68, v13, s63
	v_and_or_b32 v55, v13, s60, v11
	v_mov_b32_e32 v71, s0
	v_or_b32_e32 v70, s5, v2
	v_bfe_u32 v11, v19, 16, 1
	v_lshlrev_b64 v[70:71], 7, v[70:71]
	v_add3_u32 v11, v19, v11, s63
	v_bfe_u32 v13, v57, 16, 1
	v_lshl_add_u64 v[70:71], v[16:17], 0, v[70:71]
	v_lshrrev_b32_e32 v11, 16, v11
	v_add3_u32 v13, v57, v13, s63
	global_store_dwordx4 v[70:71], v[52:55], off sc0 sc1
	v_mov_b32_e32 v19, s0
	v_or_b32_e32 v18, s5, v4
	v_and_or_b32 v52, v13, s60, v11
	v_bfe_u32 v11, v59, 16, 1
	v_add3_u32 v11, v59, v11, s63
	v_bfe_u32 v13, v61, 16, 1
	v_lshrrev_b32_e32 v11, 16, v11
	v_add3_u32 v13, v61, v13, s63
	v_and_or_b32 v53, v13, s60, v11
	v_bfe_u32 v11, v63, 16, 1
	v_add3_u32 v11, v63, v11, s63
	v_bfe_u32 v13, v65, 16, 1
	v_lshrrev_b32_e32 v11, 16, v11
	v_add3_u32 v13, v65, v13, s63
	v_and_or_b32 v54, v13, s60, v11
	v_bfe_u32 v11, v67, 16, 1
	v_add3_u32 v11, v67, v11, s63
	v_bfe_u32 v13, v69, 16, 1
	v_lshrrev_b32_e32 v11, 16, v11
	v_add3_u32 v13, v69, v13, s63
	v_lshlrev_b64 v[18:19], 7, v[18:19]
	v_and_or_b32 v55, v13, s60, v11
	ds_read2_b32 v[56:57], v47 offset0:16 offset1:24
	v_lshl_add_u64 v[18:19], v[16:17], 0, v[18:19]
	global_store_dwordx4 v[18:19], v[52:55], off sc0 sc1
	ds_read2_b32 v[18:19], v47 offset0:49 offset1:57
	ds_read2_b32 v[58:59], v47 offset0:82 offset1:90
	ds_read2_b32 v[60:61], v47 offset0:115 offset1:123
	s_waitcnt lgkmcnt(3)
	v_bfe_u32 v11, v56, 16, 1
	v_add3_u32 v11, v56, v11, s63
	s_waitcnt lgkmcnt(2)
	v_bfe_u32 v13, v18, 16, 1
	ds_read2_b32 v[62:63], v47 offset0:148 offset1:156
	v_lshrrev_b32_e32 v11, 16, v11
	v_add3_u32 v13, v18, v13, s63
	ds_read2_b32 v[64:65], v47 offset0:181 offset1:189
	v_and_or_b32 v52, v13, s60, v11
	s_waitcnt lgkmcnt(3)
	v_bfe_u32 v11, v58, 16, 1
	v_add3_u32 v11, v58, v11, s63
	s_waitcnt lgkmcnt(2)
	v_bfe_u32 v13, v60, 16, 1
	ds_read2_b32 v[66:67], v47 offset0:214 offset1:222
	v_lshrrev_b32_e32 v11, 16, v11
	v_add3_u32 v13, v60, v13, s63
	ds_read2_b32 v[68:69], v47 offset0:247 offset1:255
	v_and_or_b32 v53, v13, s60, v11
	s_waitcnt lgkmcnt(3)
	v_bfe_u32 v11, v62, 16, 1
	v_add3_u32 v11, v62, v11, s63
	s_waitcnt lgkmcnt(2)
	v_bfe_u32 v13, v64, 16, 1
	v_lshrrev_b32_e32 v11, 16, v11
	v_add3_u32 v13, v64, v13, s63
	v_and_or_b32 v54, v13, s60, v11
	s_waitcnt lgkmcnt(1)
	v_bfe_u32 v11, v66, 16, 1
	v_add3_u32 v11, v66, v11, s63
	s_waitcnt lgkmcnt(0)
	v_bfe_u32 v13, v68, 16, 1
	v_lshrrev_b32_e32 v11, 16, v11
	v_add3_u32 v13, v68, v13, s63
	v_and_or_b32 v55, v13, s60, v11
	v_mov_b32_e32 v71, s0
	v_or_b32_e32 v70, s5, v6
	v_bfe_u32 v11, v57, 16, 1
	v_lshlrev_b64 v[70:71], 7, v[70:71]
	v_add3_u32 v11, v57, v11, s63
	v_bfe_u32 v13, v19, 16, 1
	v_lshl_add_u64 v[70:71], v[16:17], 0, v[70:71]
	v_lshrrev_b32_e32 v11, 16, v11
	v_add3_u32 v13, v19, v13, s63
	global_store_dwordx4 v[70:71], v[52:55], off sc0 sc1
	v_mov_b32_e32 v19, s0
	v_or_b32_e32 v18, s5, v8
	v_and_or_b32 v52, v13, s60, v11
	v_bfe_u32 v11, v59, 16, 1
	v_add3_u32 v11, v59, v11, s63
	v_bfe_u32 v13, v61, 16, 1
	v_lshrrev_b32_e32 v11, 16, v11
	v_add3_u32 v13, v61, v13, s63
	v_and_or_b32 v53, v13, s60, v11
	v_bfe_u32 v11, v63, 16, 1
	v_add3_u32 v11, v63, v11, s63
	v_bfe_u32 v13, v65, 16, 1
	v_lshrrev_b32_e32 v11, 16, v11
	v_add3_u32 v13, v65, v13, s63
	v_and_or_b32 v54, v13, s60, v11
	v_bfe_u32 v11, v67, 16, 1
	v_add3_u32 v11, v67, v11, s63
	v_bfe_u32 v13, v69, 16, 1
	v_lshrrev_b32_e32 v11, 16, v11
	v_add3_u32 v13, v69, v13, s63
	v_lshlrev_b64 v[18:19], 7, v[18:19]
	v_and_or_b32 v55, v13, s60, v11
	v_lshl_add_u64 v[18:19], v[16:17], 0, v[18:19]
	global_store_dwordx4 v[18:19], v[52:55], off sc0 sc1
	s_waitcnt lgkmcnt(0)
	s_add_i32 s20, s20, s33
	s_add_i32 s18, s18, s19
	s_cmp_lt_i32 s20, s16
	s_cbranch_scc0 .LBB0_389
